# ladder variant: eight rungs only on the clusters fed by twelve fragment reads, two rungs on the others
# speedup vs baseline: 1.0022x; 1.0022x over previous
.LBB0_403:
	s_add_u32 s14, s4, 0x100
	s_addc_u32 s15, s5, 0
	s_add_i32 s38, 0, 0x10000
	v_add_u32_e32 v12, s38, v193
	ds_read_b128 v[0:3], v12
	ds_read_b128 v[8:11], v12 offset:2048
	ds_read_b128 v[4:7], v12 offset:1024
	ds_read_b128 v[12:15], v12 offset:3072
	s_cmp_eq_u32 s37, 12
	s_cselect_b32 s19, s9, s15
	s_cselect_b32 s18, s8, s14
	s_cselect_b32 s17, s11, s36
	s_cselect_b32 s16, s10, s7
	v_lshl_add_u64 v[190:191], s[4:5], 0, v[186:187]
	s_add_i32 m0, s23, 0xc000
	ds_read_b128 v[16:19], v206
	ds_read_b128 v[24:27], v206 offset:2048
	ds_read_b128 v[162:165], v206 offset:4096
	ds_read_b128 v[170:173], v206 offset:6144
	ds_read_b128 v[20:23], v206 offset:1024
	ds_read_b128 v[28:31], v206 offset:3072
	ds_read_b128 v[166:169], v206 offset:5120
	ds_read_b128 v[174:177], v206 offset:7168
	global_load_lds_dwordx4 v[190:191], off
	v_lshl_add_u64 v[190:191], s[4:5], 0, v[188:189]
	s_add_i32 m0, s23, 0xe000
	s_nop 0
	global_load_lds_dwordx4 v[190:191], off
	s_waitcnt lgkmcnt(8)
	s_barrier
	s_waitcnt lgkmcnt(7)
	s_setprio 1
	v_mfma_f32_16x16x32_f16 v[158:161], v[0:3], v[16:19], v[158:161]
	v_mfma_f32_16x16x32_f16 v[142:145], v[8:11], v[16:19], v[142:145]
	s_waitcnt lgkmcnt(6)
	v_mfma_f32_16x16x32_f16 v[150:153], v[0:3], v[24:27], v[150:153]
	v_mfma_f32_16x16x32_f16 v[134:137], v[8:11], v[24:27], v[134:137]
	s_waitcnt lgkmcnt(5)
	v_mfma_f32_16x16x32_f16 v[154:157], v[0:3], v[162:165], v[154:157]
	v_mfma_f32_16x16x32_f16 v[138:141], v[8:11], v[162:165], v[138:141]
	s_waitcnt lgkmcnt(4)
	v_mfma_f32_16x16x32_f16 v[146:149], v[0:3], v[170:173], v[146:149]
	v_mfma_f32_16x16x32_f16 v[130:133], v[8:11], v[170:173], v[130:133]
	s_waitcnt lgkmcnt(3)
	v_mfma_f32_16x16x32_f16 v[158:161], v[4:7], v[20:23], v[158:161]
	v_mfma_f32_16x16x32_f16 v[142:145], v[12:15], v[20:23], v[142:145]
	s_waitcnt lgkmcnt(2)
	v_mfma_f32_16x16x32_f16 v[150:153], v[4:7], v[28:31], v[150:153]
	v_mfma_f32_16x16x32_f16 v[134:137], v[12:15], v[28:31], v[134:137]
	s_waitcnt lgkmcnt(1)
	v_mfma_f32_16x16x32_f16 v[154:157], v[4:7], v[166:169], v[154:157]
	v_mfma_f32_16x16x32_f16 v[138:141], v[12:15], v[166:169], v[138:141]
	s_waitcnt lgkmcnt(0)
	v_mfma_f32_16x16x32_f16 v[146:149], v[4:7], v[174:177], v[146:149]
	v_mfma_f32_16x16x32_f16 v[130:133], v[12:15], v[174:177], v[130:133]
	s_setprio 0
	s_barrier
	s_add_i32 s39, 0, 0x14000
	s_add_i32 s4, s38, s22
	v_add_u32_e32 v32, s39, v193
	v_lshl_add_u64 v[190:191], s[16:17], 0, v[178:179]
	s_mov_b32 m0, s4
	ds_read_b128 v[208:211], v32
	ds_read_b128 v[216:219], v32 offset:2048
	ds_read_b128 v[212:215], v32 offset:1024
	ds_read_b128 v[230:233], v32 offset:3072
	global_load_lds_dwordx4 v[190:191], off
	v_lshl_add_u64 v[238:239], s[16:17], 0, v[180:181]
	s_add_i32 m0, s4, 0x2000
	s_nop 0
	global_load_lds_dwordx4 v[238:239], off
	s_barrier
	s_waitcnt lgkmcnt(0)
	s_setprio 1
	s_waitcnt lgkmcnt(0)
	v_mfma_f32_16x16x32_f16 v[94:97], v[208:211], v[16:19], v[94:97]
	v_mfma_f32_16x16x32_f16 v[16:19], v[216:219], v[16:19], v[78:81]
	v_mfma_f32_16x16x32_f16 v[94:97], v[212:215], v[20:23], v[94:97]
	v_mfma_f32_16x16x32_f16 v[16:19], v[230:233], v[20:23], v[16:19]
	v_mfma_f32_16x16x32_f16 v[20:23], v[208:211], v[24:27], v[86:89]
	v_mfma_f32_16x16x32_f16 v[24:27], v[216:219], v[24:27], v[70:73]
	v_mfma_f32_16x16x32_f16 v[70:73], v[216:219], v[162:165], v[74:77]
	v_mfma_f32_16x16x32_f16 v[74:77], v[230:233], v[166:169], v[70:73]
	v_mfma_f32_16x16x32_f16 v[70:73], v[208:211], v[170:173], v[82:85]
	v_mfma_f32_16x16x32_f16 v[66:69], v[216:219], v[170:173], v[66:69]
	v_mfma_f32_16x16x32_f16 v[20:23], v[212:215], v[28:31], v[20:23]
	v_mfma_f32_16x16x32_f16 v[24:27], v[230:233], v[28:31], v[24:27]
	v_mfma_f32_16x16x32_f16 v[28:31], v[208:211], v[162:165], v[90:93]
	v_mfma_f32_16x16x32_f16 v[82:85], v[212:215], v[174:177], v[70:73]
	v_mfma_f32_16x16x32_f16 v[66:69], v[230:233], v[174:177], v[66:69]
	v_mfma_f32_16x16x32_f16 v[28:31], v[212:215], v[166:169], v[28:31]
	s_setprio 0
	s_mov_b32 m0, s23
	v_lshl_add_u64 v[240:241], s[18:19], 0, v[178:179]
	s_barrier
	ds_read_b128 v[70:73], v206 offset:16384
	ds_read_b128 v[86:89], v206 offset:18432
	ds_read_b128 v[162:165], v206 offset:20480
	ds_read_b128 v[170:173], v206 offset:22528
	ds_read_b128 v[78:81], v206 offset:17408
	ds_read_b128 v[90:93], v206 offset:19456
	ds_read_b128 v[166:169], v206 offset:21504
	ds_read_b128 v[174:177], v206 offset:23552
	global_load_lds_dwordx4 v[240:241], off
	v_lshl_add_u64 v[242:243], s[18:19], 0, v[180:181]
	s_mov_b32 m0, s24
	s_nop 0
	global_load_lds_dwordx4 v[242:243], off
	s_barrier
	s_waitcnt lgkmcnt(3)
	s_setprio 1
	v_mfma_f32_16x16x32_f16 v[126:129], v[0:3], v[70:73], v[126:129]
	v_mfma_f32_16x16x32_f16 v[110:113], v[8:11], v[70:73], v[110:113]
	v_mfma_f32_16x16x32_f16 v[118:121], v[0:3], v[86:89], v[118:121]
	v_mfma_f32_16x16x32_f16 v[102:105], v[8:11], v[86:89], v[102:105]
	v_mfma_f32_16x16x32_f16 v[122:125], v[0:3], v[162:165], v[122:125]
	v_mfma_f32_16x16x32_f16 v[106:109], v[8:11], v[162:165], v[106:109]
	v_mfma_f32_16x16x32_f16 v[0:3], v[0:3], v[170:173], v[114:117]
	v_mfma_f32_16x16x32_f16 v[126:129], v[4:7], v[78:81], v[126:129]
	s_waitcnt lgkmcnt(0)
	v_mfma_f32_16x16x32_f16 v[110:113], v[12:15], v[78:81], v[110:113]
	v_mfma_f32_16x16x32_f16 v[118:121], v[4:7], v[90:93], v[118:121]
	v_mfma_f32_16x16x32_f16 v[102:105], v[12:15], v[90:93], v[102:105]
	v_mfma_f32_16x16x32_f16 v[122:125], v[4:7], v[166:169], v[122:125]
	v_mfma_f32_16x16x32_f16 v[106:109], v[12:15], v[166:169], v[106:109]
	v_mfma_f32_16x16x32_f16 v[0:3], v[4:7], v[174:177], v[0:3]
	v_mfma_f32_16x16x32_f16 v[4:7], v[8:11], v[170:173], v[98:101]
	v_mfma_f32_16x16x32_f16 v[4:7], v[12:15], v[174:177], v[4:7]
	s_setprio 0
	s_barrier
	s_add_u32 s4, s16, 0x40000
	s_addc_u32 s5, s17, 0
	s_add_i32 s38, s39, s22
	v_lshl_add_u64 v[8:9], s[4:5], 0, v[178:179]
	s_mov_b32 m0, s38
	s_nop 0
	global_load_lds_dwordx4 v[8:9], off
	v_lshl_add_u64 v[8:9], s[4:5], 0, v[180:181]
	s_add_i32 m0, s38, 0x2000
	s_nop 0
	global_load_lds_dwordx4 v[8:9], off
	s_waitcnt vmcnt(6)
	s_barrier
	s_setprio 1
	v_mfma_f32_16x16x32_f16 v[12:15], v[216:219], v[70:73], v[46:49]
	v_mfma_f32_16x16x32_f16 v[46:49], v[208:211], v[86:89], v[54:57]
	v_mfma_f32_16x16x32_f16 v[54:57], v[212:215], v[90:93], v[46:49]
	v_mfma_f32_16x16x32_f16 v[46:49], v[208:211], v[162:165], v[58:61]
	v_mfma_f32_16x16x32_f16 v[38:41], v[216:219], v[86:89], v[38:41]
	v_mfma_f32_16x16x32_f16 v[58:61], v[212:215], v[166:169], v[46:49]
	v_mfma_f32_16x16x32_f16 v[42:45], v[216:219], v[162:165], v[42:45]
	v_mfma_f32_16x16x32_f16 v[46:49], v[208:211], v[170:173], v[50:53]
	v_mfma_f32_16x16x32_f16 v[34:37], v[216:219], v[170:173], v[34:37]
	v_mfma_f32_16x16x32_f16 v[8:11], v[208:211], v[70:73], v[62:65]
	v_mfma_f32_16x16x32_f16 v[38:41], v[230:233], v[90:93], v[38:41]
	v_mfma_f32_16x16x32_f16 v[42:45], v[230:233], v[166:169], v[42:45]
	v_mfma_f32_16x16x32_f16 v[50:53], v[212:215], v[174:177], v[46:49]
	v_mfma_f32_16x16x32_f16 v[34:37], v[230:233], v[174:177], v[34:37]
	v_mfma_f32_16x16x32_f16 v[8:11], v[212:215], v[78:81], v[8:11]
	v_mfma_f32_16x16x32_f16 v[12:15], v[230:233], v[78:81], v[12:15]
	s_setprio 0
	s_add_i32 s38, 0, 0x18000
	v_add_u32_e32 v32, s38, v193
	s_barrier
	ds_read_b128 v[46:49], v32
	ds_read_b128 v[62:65], v32 offset:1024
	ds_read_b128 v[98:101], v32 offset:2048
	ds_read_b128 v[162:165], v32 offset:3072
	s_add_u32 s4, s18, 0x40000
	s_addc_u32 s5, s19, 0
	s_mov_b32 m0, s25
	v_lshl_add_u64 v[86:87], s[4:5], 0, v[178:179]
	ds_read_b128 v[70:73], v206 offset:32768
	ds_read_b128 v[78:81], v206 offset:33792
	ds_read_b128 v[90:93], v206 offset:34816
	ds_read_b128 v[114:117], v206 offset:35840
	ds_read_b128 v[166:169], v206 offset:36864
	ds_read_b128 v[170:173], v206 offset:37888
	ds_read_b128 v[174:177], v206 offset:38912
	ds_read_b128 v[208:211], v206 offset:39936
	global_load_lds_dwordx4 v[86:87], off
	v_lshl_add_u64 v[86:87], s[4:5], 0, v[180:181]
	s_mov_b32 m0, s26
	s_nop 0
	global_load_lds_dwordx4 v[86:87], off
	s_waitcnt lgkmcnt(8)
	s_barrier
	s_waitcnt lgkmcnt(6)
	s_setprio 1
	v_mfma_f32_16x16x32_f16 v[86:89], v[46:49], v[70:73], v[158:161]
	v_mfma_f32_16x16x32_f16 v[158:161], v[62:65], v[78:81], v[86:89]
	v_mfma_f32_16x16x32_f16 v[86:89], v[98:101], v[70:73], v[142:145]
	v_mfma_f32_16x16x32_f16 v[142:145], v[162:165], v[78:81], v[86:89]
	s_waitcnt lgkmcnt(4)
	v_mfma_f32_16x16x32_f16 v[86:89], v[46:49], v[90:93], v[150:153]
	v_mfma_f32_16x16x32_f16 v[150:153], v[62:65], v[114:117], v[86:89]
	v_mfma_f32_16x16x32_f16 v[86:89], v[98:101], v[90:93], v[134:137]
	v_mfma_f32_16x16x32_f16 v[134:137], v[162:165], v[114:117], v[86:89]
	s_waitcnt lgkmcnt(2)
	v_mfma_f32_16x16x32_f16 v[86:89], v[46:49], v[166:169], v[154:157]
	v_mfma_f32_16x16x32_f16 v[154:157], v[62:65], v[170:173], v[86:89]
	v_mfma_f32_16x16x32_f16 v[86:89], v[98:101], v[166:169], v[138:141]
	v_mfma_f32_16x16x32_f16 v[138:141], v[162:165], v[170:173], v[86:89]
	s_waitcnt lgkmcnt(0)
	v_mfma_f32_16x16x32_f16 v[86:89], v[46:49], v[174:177], v[146:149]
	v_mfma_f32_16x16x32_f16 v[146:149], v[62:65], v[208:211], v[86:89]
	v_mfma_f32_16x16x32_f16 v[86:89], v[98:101], v[174:177], v[130:133]
	v_mfma_f32_16x16x32_f16 v[130:133], v[162:165], v[208:211], v[86:89]
	s_setprio 0
	s_barrier
	s_add_i32 s18, 0, 0x1c000
	s_add_i32 s4, s38, s22
	v_add_u32_e32 v32, s18, v193
	s_nop 1
	v_lshl_add_u64 v[86:87], v[190:191], 0, s[84:85]
	s_mov_b32 m0, s4
	ds_read_b128 v[212:215], v32
	ds_read_b128 v[230:233], v32 offset:2048
	ds_read_b128 v[216:219], v32 offset:1024
	ds_read_b128 v[234:237], v32 offset:3072
	global_load_lds_dwordx4 v[86:87], off
	v_lshl_add_u64 v[86:87], v[238:239], 0, s[84:85]
	s_add_i32 m0, s4, 0x2000
	s_nop 0
	global_load_lds_dwordx4 v[86:87], off
	s_barrier
	s_waitcnt lgkmcnt(0)
	s_setprio 1
	s_waitcnt lgkmcnt(0)
	v_mfma_f32_16x16x32_f16 v[86:89], v[212:215], v[70:73], v[94:97]
	v_mfma_f32_16x16x32_f16 v[16:19], v[230:233], v[70:73], v[16:19]
	v_mfma_f32_16x16x32_f16 v[94:97], v[216:219], v[78:81], v[86:89]
	v_mfma_f32_16x16x32_f16 v[78:81], v[234:237], v[78:81], v[16:19]
	v_mfma_f32_16x16x32_f16 v[16:19], v[212:215], v[90:93], v[20:23]
	v_mfma_f32_16x16x32_f16 v[86:89], v[216:219], v[114:117], v[16:19]
	v_mfma_f32_16x16x32_f16 v[16:19], v[230:233], v[90:93], v[24:27]
	v_mfma_f32_16x16x32_f16 v[70:73], v[234:237], v[114:117], v[16:19]
	v_mfma_f32_16x16x32_f16 v[16:19], v[212:215], v[166:169], v[28:31]
	v_mfma_f32_16x16x32_f16 v[90:93], v[216:219], v[170:173], v[16:19]
	v_mfma_f32_16x16x32_f16 v[16:19], v[230:233], v[166:169], v[74:77]
	v_mfma_f32_16x16x32_f16 v[74:77], v[234:237], v[170:173], v[16:19]
	v_mfma_f32_16x16x32_f16 v[16:19], v[212:215], v[174:177], v[82:85]
	v_mfma_f32_16x16x32_f16 v[82:85], v[216:219], v[208:211], v[16:19]
	v_mfma_f32_16x16x32_f16 v[16:19], v[230:233], v[174:177], v[66:69]
	v_mfma_f32_16x16x32_f16 v[66:69], v[234:237], v[208:211], v[16:19]
	s_setprio 0
	s_mov_b32 m0, s28
	v_lshl_add_u64 v[114:115], v[240:241], 0, s[84:85]
	s_barrier
	s_nop 2
	ds_read_b128 v[16:19], v206 offset:49152
	ds_read_b128 v[20:23], v206 offset:50176
	ds_read_b128 v[24:27], v206 offset:51200
	ds_read_b128 v[28:31], v206 offset:52224
	ds_read_b128 v[166:169], v206 offset:53248
	ds_read_b128 v[174:177], v206 offset:55296
	ds_read_b128 v[170:173], v206 offset:54272
	ds_read_b128 v[208:211], v206 offset:56320
	global_load_lds_dwordx4 v[114:115], off
	v_lshl_add_u64 v[114:115], v[242:243], 0, s[84:85]
	s_mov_b32 m0, s29
	s_nop 0
	global_load_lds_dwordx4 v[114:115], off
	s_barrier
	s_waitcnt lgkmcnt(2)
	s_setprio 1
	v_mfma_f32_16x16x32_f16 v[114:117], v[46:49], v[16:19], v[126:129]
	v_mfma_f32_16x16x32_f16 v[126:129], v[62:65], v[20:23], v[114:117]
	v_mfma_f32_16x16x32_f16 v[114:117], v[46:49], v[24:27], v[118:121]
	v_mfma_f32_16x16x32_f16 v[118:121], v[62:65], v[28:31], v[114:117]
	v_mfma_f32_16x16x32_f16 v[114:117], v[46:49], v[166:169], v[122:125]
	v_mfma_f32_16x16x32_f16 v[0:3], v[46:49], v[174:177], v[0:3]
	v_mfma_f32_16x16x32_f16 v[110:113], v[98:101], v[16:19], v[110:113]
	v_mfma_f32_16x16x32_f16 v[102:105], v[98:101], v[24:27], v[102:105]
	s_waitcnt lgkmcnt(0)
	v_mfma_f32_16x16x32_f16 v[122:125], v[62:65], v[170:173], v[114:117]
	v_mfma_f32_16x16x32_f16 v[106:109], v[98:101], v[166:169], v[106:109]
	v_mfma_f32_16x16x32_f16 v[114:117], v[62:65], v[208:211], v[0:3]
	v_mfma_f32_16x16x32_f16 v[0:3], v[98:101], v[174:177], v[4:7]
	v_mfma_f32_16x16x32_f16 v[110:113], v[162:165], v[20:23], v[110:113]
	v_mfma_f32_16x16x32_f16 v[102:105], v[162:165], v[28:31], v[102:105]
	v_mfma_f32_16x16x32_f16 v[106:109], v[162:165], v[170:173], v[106:109]
	v_mfma_f32_16x16x32_f16 v[98:101], v[162:165], v[208:211], v[0:3]
	s_setprio 0
	s_barrier
	s_add_u32 s4, s16, 0x40080
	s_addc_u32 s5, s17, 0
	s_add_i32 s16, s18, s22
	v_lshl_add_u64 v[0:1], s[4:5], 0, v[178:179]
	s_mov_b32 m0, s16
	s_nop 0
	global_load_lds_dwordx4 v[0:1], off
	v_lshl_add_u64 v[0:1], s[4:5], 0, v[180:181]
	s_add_i32 m0, s16, 0x2000
	s_nop 0
	global_load_lds_dwordx4 v[0:1], off
	s_waitcnt vmcnt(6)
	s_barrier
	s_setprio 1
	v_mfma_f32_16x16x32_f16 v[0:3], v[212:215], v[16:19], v[8:11]
	v_mfma_f32_16x16x32_f16 v[62:65], v[216:219], v[20:23], v[0:3]
	v_mfma_f32_16x16x32_f16 v[0:3], v[230:233], v[16:19], v[12:15]
	v_mfma_f32_16x16x32_f16 v[46:49], v[234:237], v[20:23], v[0:3]
	v_mfma_f32_16x16x32_f16 v[0:3], v[212:215], v[24:27], v[54:57]
	v_mfma_f32_16x16x32_f16 v[54:57], v[216:219], v[28:31], v[0:3]
	v_mfma_f32_16x16x32_f16 v[0:3], v[230:233], v[24:27], v[38:41]
	v_mfma_f32_16x16x32_f16 v[38:41], v[234:237], v[28:31], v[0:3]
	v_mfma_f32_16x16x32_f16 v[0:3], v[212:215], v[166:169], v[58:61]
	v_mfma_f32_16x16x32_f16 v[58:61], v[216:219], v[170:173], v[0:3]
	v_mfma_f32_16x16x32_f16 v[0:3], v[230:233], v[166:169], v[42:45]
	v_mfma_f32_16x16x32_f16 v[42:45], v[234:237], v[170:173], v[0:3]
	v_mfma_f32_16x16x32_f16 v[0:3], v[212:215], v[174:177], v[50:53]
	v_mfma_f32_16x16x32_f16 v[50:53], v[216:219], v[208:211], v[0:3]
	v_mfma_f32_16x16x32_f16 v[0:3], v[230:233], v[174:177], v[34:37]
	v_mfma_f32_16x16x32_f16 v[34:37], v[234:237], v[208:211], v[0:3]
	s_setprio 0
	s_add_i32 s37, s37, 2
	s_add_u32 s7, s7, 0x100
	s_addc_u32 s36, s36, 0
	s_cmp_gt_u32 s37, 13
	s_mov_b64 s[4:5], s[14:15]
	s_barrier
	s_cbranch_scc0 .LBB0_403
	s_lshl_b32 s7, s34, 8
	s_cmp_lt_i32 s35, 28
	s_mov_b64 s[4:5], -1
	s_cbranch_scc0 .LBB0_431
	s_add_i32 s16, s7, s27
	v_or_b32_e32 v207, s16, v192
	s_cmp_gt_i32 s35, 3
	s_cbranch_scc0 .LBB0_411
	s_add_i32 s4, s35, -12
	s_cmp_gt_u32 s4, 7
	s_mov_b64 s[4:5], -1
	s_cbranch_scc0 .LBB0_408
	s_lshl_b32 s4, s35, 8
	s_add_i32 s5, s4, 0xfffffc00
	s_cmp_lt_u32 s35, 12
	s_cselect_b32 s4, s4, s5
	v_and_b32_e32 v10, 7, v220
	v_and_b32_e32 v11, 8, v220
	v_cmp_ne_u32_e32 vcc, 0, v11
	v_and_b32_e32 v12, 0x60, v194
	v_lshlrev_b32_e32 v12, 1, v12
	v_lshl_or_b32 v12, v11, 2, v12
	v_and_b32_e32 v13, 0x18, v194
	v_or_b32_e32 v12, v12, v13
	v_or_b32_e32 v32, s4, v12
	v_or_b32_e32 v14, s16, v10
	v_mov_b64_e32 v[4:5], s[70:71]
	v_mad_i64_i32 v[0:1], s[4:5], v14, s33, v[4:5]
	v_lshlrev_b64 v[6:7], 1, v[32:33]
	v_lshl_add_u64 v[16:17], v[0:1], 0, v[6:7]
	v_mov_b32_e32 v32, 0x30000
	v_lshl_add_u64 v[18:19], v[16:17], 0, v[32:33]
	v_lshl_add_u64 v[20:21], v[18:19], 0, v[32:33]
	v_lshl_add_u64 v[22:23], v[20:21], 0, v[32:33]
	v_mov_b32_e32 v8, 0x180000
	v_mov_b32_e32 v9, 0
	v_lshl_add_u64 v[24:25], v[16:17], 0, v[8:9]
	v_lshl_add_u64 v[26:27], v[24:25], 0, v[32:33]
	v_lshl_add_u64 v[28:29], v[26:27], 0, v[32:33]
	v_lshl_add_u64 v[30:31], v[28:29], 0, v[32:33]
	v_mov_b32_e32 v8, 0x18000
	v_cvt_pk_f16_f32 v158, v158, v159
	v_cvt_pk_f16_f32 v159, v160, v161
	v_cvt_pk_f16_f32 v160, v142, v143
	v_cvt_pk_f16_f32 v161, v144, v145
	v_cvt_pk_f16_f32 v94, v94, v95
	v_cvt_pk_f16_f32 v95, v96, v97
	v_cvt_pk_f16_f32 v96, v78, v79
	v_cvt_pk_f16_f32 v97, v80, v81
	v_mov_b32_dpp v0, v158 row_ror:8 row_mask:0xf bank_mask:0xf
	v_mov_b32_dpp v1, v159 row_ror:8 row_mask:0xf bank_mask:0xf
	v_mov_b32_dpp v2, v160 row_ror:8 row_mask:0xf bank_mask:0xf
	v_mov_b32_dpp v3, v161 row_ror:8 row_mask:0xf bank_mask:0xf
	v_mov_b32_dpp v4, v94 row_ror:8 row_mask:0xf bank_mask:0xf
	v_mov_b32_dpp v5, v95 row_ror:8 row_mask:0xf bank_mask:0xf
	v_mov_b32_dpp v6, v96 row_ror:8 row_mask:0xf bank_mask:0xf
	v_mov_b32_dpp v7, v97 row_ror:8 row_mask:0xf bank_mask:0xf
	v_cndmask_b32_e32 v158, v158, v4, vcc
	v_cndmask_b32_e32 v159, v159, v5, vcc
	v_cndmask_b32_e32 v160, v160, v6, vcc
	v_cndmask_b32_e32 v161, v161, v7, vcc
	v_cndmask_b32_e32 v94, v0, v94, vcc
	v_cndmask_b32_e32 v95, v1, v95, vcc
	v_cndmask_b32_e32 v96, v2, v96, vcc
	v_cndmask_b32_e32 v97, v3, v97, vcc
	v_lshl_add_u64 v[10:11], v[16:17], 0, v[8:9]
	global_store_dwordx4 v[16:17], v[158:161], off
	global_store_dwordx4 v[10:11], v[94:97], off
	v_cvt_pk_f16_f32 v150, v150, v151
	v_cvt_pk_f16_f32 v151, v152, v153
	v_cvt_pk_f16_f32 v152, v134, v135
	v_cvt_pk_f16_f32 v153, v136, v137
	v_cvt_pk_f16_f32 v86, v86, v87
	v_cvt_pk_f16_f32 v87, v88, v89
	v_cvt_pk_f16_f32 v88, v70, v71
	v_cvt_pk_f16_f32 v89, v72, v73
	v_mov_b32_dpp v0, v150 row_ror:8 row_mask:0xf bank_mask:0xf
	v_mov_b32_dpp v1, v151 row_ror:8 row_mask:0xf bank_mask:0xf
	v_mov_b32_dpp v2, v152 row_ror:8 row_mask:0xf bank_mask:0xf
	v_mov_b32_dpp v3, v153 row_ror:8 row_mask:0xf bank_mask:0xf
	v_mov_b32_dpp v4, v86 row_ror:8 row_mask:0xf bank_mask:0xf
	v_mov_b32_dpp v5, v87 row_ror:8 row_mask:0xf bank_mask:0xf
	v_mov_b32_dpp v6, v88 row_ror:8 row_mask:0xf bank_mask:0xf
	v_mov_b32_dpp v7, v89 row_ror:8 row_mask:0xf bank_mask:0xf
	v_cndmask_b32_e32 v150, v150, v4, vcc
	v_cndmask_b32_e32 v151, v151, v5, vcc
	v_cndmask_b32_e32 v152, v152, v6, vcc
	v_cndmask_b32_e32 v153, v153, v7, vcc
	v_cndmask_b32_e32 v86, v0, v86, vcc
	v_cndmask_b32_e32 v87, v1, v87, vcc
	v_cndmask_b32_e32 v88, v2, v88, vcc
	v_cndmask_b32_e32 v89, v3, v89, vcc
	v_lshl_add_u64 v[10:11], v[18:19], 0, v[8:9]
	global_store_dwordx4 v[18:19], v[150:153], off
	global_store_dwordx4 v[10:11], v[86:89], off
	v_cvt_pk_f16_f32 v154, v154, v155
	v_cvt_pk_f16_f32 v155, v156, v157
	v_cvt_pk_f16_f32 v156, v138, v139
	v_cvt_pk_f16_f32 v157, v140, v141
	v_cvt_pk_f16_f32 v90, v90, v91
	v_cvt_pk_f16_f32 v91, v92, v93
	v_cvt_pk_f16_f32 v92, v74, v75
	v_cvt_pk_f16_f32 v93, v76, v77
	v_mov_b32_dpp v0, v154 row_ror:8 row_mask:0xf bank_mask:0xf
	v_mov_b32_dpp v1, v155 row_ror:8 row_mask:0xf bank_mask:0xf
	v_mov_b32_dpp v2, v156 row_ror:8 row_mask:0xf bank_mask:0xf
	v_mov_b32_dpp v3, v157 row_ror:8 row_mask:0xf bank_mask:0xf
	v_mov_b32_dpp v4, v90 row_ror:8 row_mask:0xf bank_mask:0xf
	v_mov_b32_dpp v5, v91 row_ror:8 row_mask:0xf bank_mask:0xf
	v_mov_b32_dpp v6, v92 row_ror:8 row_mask:0xf bank_mask:0xf
	v_mov_b32_dpp v7, v93 row_ror:8 row_mask:0xf bank_mask:0xf
	v_cndmask_b32_e32 v154, v154, v4, vcc
	v_cndmask_b32_e32 v155, v155, v5, vcc
	v_cndmask_b32_e32 v156, v156, v6, vcc
	v_cndmask_b32_e32 v157, v157, v7, vcc
	v_cndmask_b32_e32 v90, v0, v90, vcc
	v_cndmask_b32_e32 v91, v1, v91, vcc
	v_cndmask_b32_e32 v92, v2, v92, vcc
	v_cndmask_b32_e32 v93, v3, v93, vcc
	v_lshl_add_u64 v[10:11], v[20:21], 0, v[8:9]
	global_store_dwordx4 v[20:21], v[154:157], off
	global_store_dwordx4 v[10:11], v[90:93], off
	v_cvt_pk_f16_f32 v146, v146, v147
	v_cvt_pk_f16_f32 v147, v148, v149
	v_cvt_pk_f16_f32 v148, v130, v131
	v_cvt_pk_f16_f32 v149, v132, v133
	v_cvt_pk_f16_f32 v82, v82, v83
	v_cvt_pk_f16_f32 v83, v84, v85
	v_cvt_pk_f16_f32 v84, v66, v67
	v_cvt_pk_f16_f32 v85, v68, v69
	v_mov_b32_dpp v0, v146 row_ror:8 row_mask:0xf bank_mask:0xf
	v_mov_b32_dpp v1, v147 row_ror:8 row_mask:0xf bank_mask:0xf
	v_mov_b32_dpp v2, v148 row_ror:8 row_mask:0xf bank_mask:0xf
	v_mov_b32_dpp v3, v149 row_ror:8 row_mask:0xf bank_mask:0xf
	v_mov_b32_dpp v4, v82 row_ror:8 row_mask:0xf bank_mask:0xf
	v_mov_b32_dpp v5, v83 row_ror:8 row_mask:0xf bank_mask:0xf
	v_mov_b32_dpp v6, v84 row_ror:8 row_mask:0xf bank_mask:0xf
	v_mov_b32_dpp v7, v85 row_ror:8 row_mask:0xf bank_mask:0xf
	v_cndmask_b32_e32 v146, v146, v4, vcc
	v_cndmask_b32_e32 v147, v147, v5, vcc
	v_cndmask_b32_e32 v148, v148, v6, vcc
	v_cndmask_b32_e32 v149, v149, v7, vcc
	v_cndmask_b32_e32 v82, v0, v82, vcc
	v_cndmask_b32_e32 v83, v1, v83, vcc
	v_cndmask_b32_e32 v84, v2, v84, vcc
	v_cndmask_b32_e32 v85, v3, v85, vcc
	v_lshl_add_u64 v[10:11], v[22:23], 0, v[8:9]
	global_store_dwordx4 v[22:23], v[146:149], off
	global_store_dwordx4 v[10:11], v[82:85], off
	v_cvt_pk_f16_f32 v126, v126, v127
	v_cvt_pk_f16_f32 v127, v128, v129
	v_cvt_pk_f16_f32 v128, v110, v111
	v_cvt_pk_f16_f32 v129, v112, v113
	v_cvt_pk_f16_f32 v62, v62, v63
	v_cvt_pk_f16_f32 v63, v64, v65
	v_cvt_pk_f16_f32 v64, v46, v47
	v_cvt_pk_f16_f32 v65, v48, v49
	v_mov_b32_dpp v0, v126 row_ror:8 row_mask:0xf bank_mask:0xf
	v_mov_b32_dpp v1, v127 row_ror:8 row_mask:0xf bank_mask:0xf
	v_mov_b32_dpp v2, v128 row_ror:8 row_mask:0xf bank_mask:0xf
	v_mov_b32_dpp v3, v129 row_ror:8 row_mask:0xf bank_mask:0xf
	v_mov_b32_dpp v4, v62 row_ror:8 row_mask:0xf bank_mask:0xf
	v_mov_b32_dpp v5, v63 row_ror:8 row_mask:0xf bank_mask:0xf
	v_mov_b32_dpp v6, v64 row_ror:8 row_mask:0xf bank_mask:0xf
	v_mov_b32_dpp v7, v65 row_ror:8 row_mask:0xf bank_mask:0xf
	v_cndmask_b32_e32 v126, v126, v4, vcc
	v_cndmask_b32_e32 v127, v127, v5, vcc
	v_cndmask_b32_e32 v128, v128, v6, vcc
	v_cndmask_b32_e32 v129, v129, v7, vcc
	v_cndmask_b32_e32 v62, v0, v62, vcc
	v_cndmask_b32_e32 v63, v1, v63, vcc
	v_cndmask_b32_e32 v64, v2, v64, vcc
	v_cndmask_b32_e32 v65, v3, v65, vcc
	v_lshl_add_u64 v[10:11], v[24:25], 0, v[8:9]
	global_store_dwordx4 v[24:25], v[126:129], off
	global_store_dwordx4 v[10:11], v[62:65], off
	v_cvt_pk_f16_f32 v118, v118, v119
	v_cvt_pk_f16_f32 v119, v120, v121
	v_cvt_pk_f16_f32 v120, v102, v103
	v_cvt_pk_f16_f32 v121, v104, v105
	v_cvt_pk_f16_f32 v54, v54, v55
	v_cvt_pk_f16_f32 v55, v56, v57
	v_cvt_pk_f16_f32 v56, v38, v39
	v_cvt_pk_f16_f32 v57, v40, v41
	v_mov_b32_dpp v0, v118 row_ror:8 row_mask:0xf bank_mask:0xf
	v_mov_b32_dpp v1, v119 row_ror:8 row_mask:0xf bank_mask:0xf
	v_mov_b32_dpp v2, v120 row_ror:8 row_mask:0xf bank_mask:0xf
	v_mov_b32_dpp v3, v121 row_ror:8 row_mask:0xf bank_mask:0xf
	v_mov_b32_dpp v4, v54 row_ror:8 row_mask:0xf bank_mask:0xf
	v_mov_b32_dpp v5, v55 row_ror:8 row_mask:0xf bank_mask:0xf
	v_mov_b32_dpp v6, v56 row_ror:8 row_mask:0xf bank_mask:0xf
	v_mov_b32_dpp v7, v57 row_ror:8 row_mask:0xf bank_mask:0xf
	v_cndmask_b32_e32 v118, v118, v4, vcc
	v_cndmask_b32_e32 v119, v119, v5, vcc
	v_cndmask_b32_e32 v120, v120, v6, vcc
	v_cndmask_b32_e32 v121, v121, v7, vcc
	v_cndmask_b32_e32 v54, v0, v54, vcc
	v_cndmask_b32_e32 v55, v1, v55, vcc
	v_cndmask_b32_e32 v56, v2, v56, vcc
	v_cndmask_b32_e32 v57, v3, v57, vcc
	v_lshl_add_u64 v[10:11], v[26:27], 0, v[8:9]
	global_store_dwordx4 v[26:27], v[118:121], off
	global_store_dwordx4 v[10:11], v[54:57], off
	v_cvt_pk_f16_f32 v122, v122, v123
	v_cvt_pk_f16_f32 v123, v124, v125
	v_cvt_pk_f16_f32 v124, v106, v107
	v_cvt_pk_f16_f32 v125, v108, v109
	v_cvt_pk_f16_f32 v58, v58, v59
	v_cvt_pk_f16_f32 v59, v60, v61
	v_cvt_pk_f16_f32 v60, v42, v43
	v_cvt_pk_f16_f32 v61, v44, v45
	v_mov_b32_dpp v0, v122 row_ror:8 row_mask:0xf bank_mask:0xf
	v_mov_b32_dpp v1, v123 row_ror:8 row_mask:0xf bank_mask:0xf
	v_mov_b32_dpp v2, v124 row_ror:8 row_mask:0xf bank_mask:0xf
	v_mov_b32_dpp v3, v125 row_ror:8 row_mask:0xf bank_mask:0xf
	v_mov_b32_dpp v4, v58 row_ror:8 row_mask:0xf bank_mask:0xf
	v_mov_b32_dpp v5, v59 row_ror:8 row_mask:0xf bank_mask:0xf
	v_mov_b32_dpp v6, v60 row_ror:8 row_mask:0xf bank_mask:0xf
	v_mov_b32_dpp v7, v61 row_ror:8 row_mask:0xf bank_mask:0xf
	v_cndmask_b32_e32 v122, v122, v4, vcc
	v_cndmask_b32_e32 v123, v123, v5, vcc
	v_cndmask_b32_e32 v124, v124, v6, vcc
	v_cndmask_b32_e32 v125, v125, v7, vcc
	v_cndmask_b32_e32 v58, v0, v58, vcc
	v_cndmask_b32_e32 v59, v1, v59, vcc
	v_cndmask_b32_e32 v60, v2, v60, vcc
	v_cndmask_b32_e32 v61, v3, v61, vcc
	v_lshl_add_u64 v[10:11], v[28:29], 0, v[8:9]
	global_store_dwordx4 v[28:29], v[122:125], off
	global_store_dwordx4 v[10:11], v[58:61], off
	v_cvt_pk_f16_f32 v114, v114, v115
	v_cvt_pk_f16_f32 v115, v116, v117
	v_cvt_pk_f16_f32 v116, v98, v99
	v_cvt_pk_f16_f32 v117, v100, v101
	v_cvt_pk_f16_f32 v50, v50, v51
	v_cvt_pk_f16_f32 v51, v52, v53
	v_cvt_pk_f16_f32 v52, v34, v35
	v_cvt_pk_f16_f32 v53, v36, v37
	v_mov_b32_dpp v0, v114 row_ror:8 row_mask:0xf bank_mask:0xf
	v_mov_b32_dpp v1, v115 row_ror:8 row_mask:0xf bank_mask:0xf
	v_mov_b32_dpp v2, v116 row_ror:8 row_mask:0xf bank_mask:0xf
	v_mov_b32_dpp v3, v117 row_ror:8 row_mask:0xf bank_mask:0xf
	v_mov_b32_dpp v4, v50 row_ror:8 row_mask:0xf bank_mask:0xf
	v_mov_b32_dpp v5, v51 row_ror:8 row_mask:0xf bank_mask:0xf
	v_mov_b32_dpp v6, v52 row_ror:8 row_mask:0xf bank_mask:0xf
	v_mov_b32_dpp v7, v53 row_ror:8 row_mask:0xf bank_mask:0xf
	v_cndmask_b32_e32 v114, v114, v4, vcc
	v_cndmask_b32_e32 v115, v115, v5, vcc
	v_cndmask_b32_e32 v116, v116, v6, vcc
	v_cndmask_b32_e32 v117, v117, v7, vcc
	v_cndmask_b32_e32 v50, v0, v50, vcc
	v_cndmask_b32_e32 v51, v1, v51, vcc
	v_cndmask_b32_e32 v52, v2, v52, vcc
	v_cndmask_b32_e32 v53, v3, v53, vcc
	v_lshl_add_u64 v[10:11], v[30:31], 0, v[8:9]
	global_store_dwordx4 v[30:31], v[114:117], off
	global_store_dwordx4 v[10:11], v[50:53], off
	s_mov_b64 s[4:5], 0

.LBB0_940:
	s_add_u32 s20, s14, 0x100
	s_addc_u32 s21, s15, 0
	s_add_i32 s40, 0, 0x10000
	v_add_u32_e32 v32, s40, v209
	ds_read_b128 v[132:135], v32
	ds_read_b128 v[140:143], v32 offset:2048
	ds_read_b128 v[136:139], v32 offset:1024
	ds_read_b128 v[144:147], v32 offset:3072
	s_cmp_eq_u32 s11, 12
	s_cselect_b32 s25, s17, s21
	s_cselect_b32 s24, s16, s20
	s_cselect_b32 s23, s19, s3
	s_cselect_b32 s22, s18, s1
	v_lshl_add_u64 v[34:35], s[14:15], 0, v[200:201]
	s_add_i32 m0, s30, 0xc000
	ds_read_b128 v[148:151], v211
	ds_read_b128 v[156:159], v211 offset:2048
	ds_read_b128 v[164:167], v211 offset:4096
	ds_read_b128 v[172:175], v211 offset:6144
	ds_read_b128 v[152:155], v211 offset:1024
	ds_read_b128 v[160:163], v211 offset:3072
	ds_read_b128 v[168:171], v211 offset:5120
	ds_read_b128 v[176:179], v211 offset:7168
	global_load_lds_dwordx4 v[34:35], off
	v_lshl_add_u64 v[34:35], s[14:15], 0, v[202:203]
	s_add_i32 m0, s30, 0xe000
	s_nop 0
	global_load_lds_dwordx4 v[34:35], off
	s_waitcnt lgkmcnt(8)
	s_barrier
	s_waitcnt lgkmcnt(7)
	s_setprio 1
	v_mfma_f32_16x16x32_f16 v[128:131], v[132:135], v[148:151], v[128:131]
	v_mfma_f32_16x16x32_f16 v[124:127], v[140:143], v[148:151], v[124:127]
	s_waitcnt lgkmcnt(6)
	v_mfma_f32_16x16x32_f16 v[120:123], v[132:135], v[156:159], v[120:123]
	v_mfma_f32_16x16x32_f16 v[116:119], v[140:143], v[156:159], v[116:119]
	s_waitcnt lgkmcnt(5)
	v_mfma_f32_16x16x32_f16 v[112:115], v[132:135], v[164:167], v[112:115]
	v_mfma_f32_16x16x32_f16 v[108:111], v[140:143], v[164:167], v[108:111]
	s_waitcnt lgkmcnt(4)
	v_mfma_f32_16x16x32_f16 v[104:107], v[132:135], v[172:175], v[104:107]
	v_mfma_f32_16x16x32_f16 v[100:103], v[140:143], v[172:175], v[100:103]
	s_waitcnt lgkmcnt(3)
	v_mfma_f32_16x16x32_f16 v[128:131], v[136:139], v[152:155], v[128:131]
	v_mfma_f32_16x16x32_f16 v[124:127], v[144:147], v[152:155], v[124:127]
	s_waitcnt lgkmcnt(2)
	v_mfma_f32_16x16x32_f16 v[120:123], v[136:139], v[160:163], v[120:123]
	v_mfma_f32_16x16x32_f16 v[116:119], v[144:147], v[160:163], v[116:119]
	s_waitcnt lgkmcnt(1)
	v_mfma_f32_16x16x32_f16 v[112:115], v[136:139], v[168:171], v[112:115]
	v_mfma_f32_16x16x32_f16 v[108:111], v[144:147], v[168:171], v[108:111]
	s_waitcnt lgkmcnt(0)
	v_mfma_f32_16x16x32_f16 v[104:107], v[136:139], v[176:179], v[104:107]
	v_mfma_f32_16x16x32_f16 v[100:103], v[144:147], v[176:179], v[100:103]
	s_setprio 0
	s_barrier
	s_add_i32 s41, 0, 0x14000
	s_add_i32 s14, s40, s29
	v_add_u32_e32 v32, s41, v209
	v_lshl_add_u64 v[204:205], s[22:23], 0, v[196:197]
	s_mov_b32 m0, s14
	ds_read_b128 v[180:183], v32
	ds_read_b128 v[188:191], v32 offset:2048
	ds_read_b128 v[184:187], v32 offset:1024
	ds_read_b128 v[192:195], v32 offset:3072
	global_load_lds_dwordx4 v[204:205], off
	v_lshl_add_u64 v[206:207], s[22:23], 0, v[198:199]
	s_add_i32 m0, s14, 0x2000
	s_nop 0
	global_load_lds_dwordx4 v[206:207], off
	s_barrier
	s_waitcnt lgkmcnt(2)
	s_setprio 1
	v_mfma_f32_16x16x32_f16 v[96:99], v[180:183], v[148:151], v[96:99]
	v_mfma_f32_16x16x32_f16 v[92:95], v[188:191], v[148:151], v[92:95]
	v_mfma_f32_16x16x32_f16 v[88:91], v[180:183], v[156:159], v[88:91]
	v_mfma_f32_16x16x32_f16 v[84:87], v[188:191], v[156:159], v[84:87]
	v_mfma_f32_16x16x32_f16 v[80:83], v[180:183], v[164:167], v[80:83]
	v_mfma_f32_16x16x32_f16 v[76:79], v[188:191], v[164:167], v[76:79]
	v_mfma_f32_16x16x32_f16 v[72:75], v[180:183], v[172:175], v[72:75]
	v_mfma_f32_16x16x32_f16 v[68:71], v[188:191], v[172:175], v[68:71]
	s_waitcnt lgkmcnt(0)
	v_mfma_f32_16x16x32_f16 v[96:99], v[184:187], v[152:155], v[96:99]
	v_mfma_f32_16x16x32_f16 v[92:95], v[192:195], v[152:155], v[92:95]
	v_mfma_f32_16x16x32_f16 v[88:91], v[184:187], v[160:163], v[88:91]
	v_mfma_f32_16x16x32_f16 v[84:87], v[192:195], v[160:163], v[84:87]
	v_mfma_f32_16x16x32_f16 v[80:83], v[184:187], v[168:171], v[80:83]
	v_mfma_f32_16x16x32_f16 v[76:79], v[192:195], v[168:171], v[76:79]
	v_mfma_f32_16x16x32_f16 v[72:75], v[184:187], v[176:179], v[72:75]
	v_mfma_f32_16x16x32_f16 v[68:71], v[192:195], v[176:179], v[68:71]
	s_setprio 0
	s_mov_b32 m0, s30
	v_lshl_add_u64 v[212:213], s[24:25], 0, v[196:197]
	s_barrier
	ds_read_b128 v[148:151], v211 offset:16384
	ds_read_b128 v[156:159], v211 offset:18432
	ds_read_b128 v[164:167], v211 offset:20480
	ds_read_b128 v[172:175], v211 offset:22528
	ds_read_b128 v[152:155], v211 offset:17408
	ds_read_b128 v[160:163], v211 offset:19456
	ds_read_b128 v[168:171], v211 offset:21504
	ds_read_b128 v[176:179], v211 offset:23552
	global_load_lds_dwordx4 v[212:213], off
	v_lshl_add_u64 v[214:215], s[24:25], 0, v[198:199]
	s_mov_b32 m0, s31
	s_nop 0
	global_load_lds_dwordx4 v[214:215], off
	s_barrier
	s_waitcnt lgkmcnt(4)
	s_setprio 1
	v_mfma_f32_16x16x32_f16 v[64:67], v[132:135], v[148:151], v[64:67]
	v_mfma_f32_16x16x32_f16 v[60:63], v[140:143], v[148:151], v[60:63]
	v_mfma_f32_16x16x32_f16 v[56:59], v[132:135], v[156:159], v[56:59]
	v_mfma_f32_16x16x32_f16 v[52:55], v[140:143], v[156:159], v[52:55]
	v_mfma_f32_16x16x32_f16 v[48:51], v[132:135], v[164:167], v[48:51]
	v_mfma_f32_16x16x32_f16 v[44:47], v[140:143], v[164:167], v[44:47]
	v_mfma_f32_16x16x32_f16 v[40:43], v[132:135], v[172:175], v[40:43]
	v_mfma_f32_16x16x32_f16 v[34:37], v[140:143], v[172:175], v[36:39]
	s_waitcnt lgkmcnt(0)
	v_mfma_f32_16x16x32_f16 v[64:67], v[136:139], v[152:155], v[64:67]
	v_mfma_f32_16x16x32_f16 v[60:63], v[144:147], v[152:155], v[60:63]
	v_mfma_f32_16x16x32_f16 v[56:59], v[136:139], v[160:163], v[56:59]
	v_mfma_f32_16x16x32_f16 v[52:55], v[144:147], v[160:163], v[52:55]
	v_mfma_f32_16x16x32_f16 v[48:51], v[136:139], v[168:171], v[48:51]
	v_mfma_f32_16x16x32_f16 v[44:47], v[144:147], v[168:171], v[44:47]
	v_mfma_f32_16x16x32_f16 v[40:43], v[136:139], v[176:179], v[40:43]
	v_mfma_f32_16x16x32_f16 v[34:37], v[144:147], v[176:179], v[34:37]
	s_setprio 0
	s_barrier
	s_add_u32 s14, s22, 0x40000
	s_addc_u32 s15, s23, 0
	s_add_i32 s40, s41, s29
	v_lshl_add_u64 v[38:39], s[14:15], 0, v[196:197]
	s_mov_b32 m0, s40
	s_nop 0
	global_load_lds_dwordx4 v[38:39], off
	v_lshl_add_u64 v[38:39], s[14:15], 0, v[198:199]
	s_add_i32 m0, s40, 0x2000
	s_nop 0
	global_load_lds_dwordx4 v[38:39], off
	s_waitcnt vmcnt(6)
	s_barrier
	s_setprio 1
	v_mfma_f32_16x16x32_f16 v[28:31], v[180:183], v[148:151], v[28:31]
	v_mfma_f32_16x16x32_f16 v[24:27], v[188:191], v[148:151], v[24:27]
	v_mfma_f32_16x16x32_f16 v[20:23], v[180:183], v[156:159], v[20:23]
	v_mfma_f32_16x16x32_f16 v[16:19], v[188:191], v[156:159], v[16:19]
	v_mfma_f32_16x16x32_f16 v[12:15], v[180:183], v[164:167], v[12:15]
	v_mfma_f32_16x16x32_f16 v[8:11], v[188:191], v[164:167], v[8:11]
	v_mfma_f32_16x16x32_f16 v[4:7], v[180:183], v[172:175], v[4:7]
	v_mfma_f32_16x16x32_f16 v[0:3], v[188:191], v[172:175], v[0:3]
	v_mfma_f32_16x16x32_f16 v[28:31], v[184:187], v[152:155], v[28:31]
	v_mfma_f32_16x16x32_f16 v[24:27], v[192:195], v[152:155], v[24:27]
	v_mfma_f32_16x16x32_f16 v[20:23], v[184:187], v[160:163], v[20:23]
	v_mfma_f32_16x16x32_f16 v[16:19], v[192:195], v[160:163], v[16:19]
	v_mfma_f32_16x16x32_f16 v[12:15], v[184:187], v[168:171], v[12:15]
	v_mfma_f32_16x16x32_f16 v[8:11], v[192:195], v[168:171], v[8:11]
	v_mfma_f32_16x16x32_f16 v[4:7], v[184:187], v[176:179], v[4:7]
	v_mfma_f32_16x16x32_f16 v[0:3], v[192:195], v[176:179], v[0:3]
	s_setprio 0
	s_add_i32 s40, 0, 0x18000
	v_add_u32_e32 v32, s40, v209
	s_barrier
	ds_read_b128 v[132:135], v32
	ds_read_b128 v[140:143], v32 offset:2048
	ds_read_b128 v[136:139], v32 offset:1024
	ds_read_b128 v[144:147], v32 offset:3072
	s_add_u32 s14, s24, 0x40000
	s_addc_u32 s15, s25, 0
	s_mov_b32 m0, s34
	v_lshl_add_u64 v[38:39], s[14:15], 0, v[196:197]
	ds_read_b128 v[148:151], v211 offset:32768
	ds_read_b128 v[156:159], v211 offset:34816
	ds_read_b128 v[164:167], v211 offset:36864
	ds_read_b128 v[172:175], v211 offset:38912
	ds_read_b128 v[152:155], v211 offset:33792
	ds_read_b128 v[160:163], v211 offset:35840
	ds_read_b128 v[168:171], v211 offset:37888
	ds_read_b128 v[176:179], v211 offset:39936
	global_load_lds_dwordx4 v[38:39], off
	v_lshl_add_u64 v[38:39], s[14:15], 0, v[198:199]
	s_mov_b32 m0, s35
	s_nop 0
	global_load_lds_dwordx4 v[38:39], off
	s_waitcnt lgkmcnt(8)
	s_barrier
	s_waitcnt lgkmcnt(7)
	s_setprio 1
	v_mfma_f32_16x16x32_f16 v[128:131], v[132:135], v[148:151], v[128:131]
	v_mfma_f32_16x16x32_f16 v[124:127], v[140:143], v[148:151], v[124:127]
	s_waitcnt lgkmcnt(6)
	v_mfma_f32_16x16x32_f16 v[120:123], v[132:135], v[156:159], v[120:123]
	v_mfma_f32_16x16x32_f16 v[116:119], v[140:143], v[156:159], v[116:119]
	s_waitcnt lgkmcnt(5)
	v_mfma_f32_16x16x32_f16 v[112:115], v[132:135], v[164:167], v[112:115]
	v_mfma_f32_16x16x32_f16 v[108:111], v[140:143], v[164:167], v[108:111]
	s_waitcnt lgkmcnt(4)
	v_mfma_f32_16x16x32_f16 v[104:107], v[132:135], v[172:175], v[104:107]
	v_mfma_f32_16x16x32_f16 v[100:103], v[140:143], v[172:175], v[100:103]
	s_waitcnt lgkmcnt(3)
	v_mfma_f32_16x16x32_f16 v[128:131], v[136:139], v[152:155], v[128:131]
	v_mfma_f32_16x16x32_f16 v[124:127], v[144:147], v[152:155], v[124:127]
	s_waitcnt lgkmcnt(2)
	v_mfma_f32_16x16x32_f16 v[120:123], v[136:139], v[160:163], v[120:123]
	v_mfma_f32_16x16x32_f16 v[116:119], v[144:147], v[160:163], v[116:119]
	s_waitcnt lgkmcnt(1)
	v_mfma_f32_16x16x32_f16 v[112:115], v[136:139], v[168:171], v[112:115]
	v_mfma_f32_16x16x32_f16 v[108:111], v[144:147], v[168:171], v[108:111]
	s_waitcnt lgkmcnt(0)
	v_mfma_f32_16x16x32_f16 v[104:107], v[136:139], v[176:179], v[104:107]
	v_mfma_f32_16x16x32_f16 v[100:103], v[144:147], v[176:179], v[100:103]
	s_setprio 0
	s_barrier
	s_add_i32 s24, 0, 0x1c000
	s_add_i32 s14, s40, s29
	v_add_u32_e32 v32, s24, v209
	v_lshl_add_u64 v[38:39], v[204:205], 0, s[84:85]
	s_mov_b32 m0, s14
	ds_read_b128 v[180:183], v32
	ds_read_b128 v[188:191], v32 offset:2048
	ds_read_b128 v[184:187], v32 offset:1024
	ds_read_b128 v[192:195], v32 offset:3072
	global_load_lds_dwordx4 v[38:39], off
	v_lshl_add_u64 v[38:39], v[206:207], 0, s[84:85]
	s_add_i32 m0, s14, 0x2000
	s_nop 0
	global_load_lds_dwordx4 v[38:39], off
	s_barrier
	s_waitcnt lgkmcnt(2)
	s_setprio 1
	v_mfma_f32_16x16x32_f16 v[96:99], v[180:183], v[148:151], v[96:99]
	v_mfma_f32_16x16x32_f16 v[92:95], v[188:191], v[148:151], v[92:95]
	v_mfma_f32_16x16x32_f16 v[88:91], v[180:183], v[156:159], v[88:91]
	v_mfma_f32_16x16x32_f16 v[84:87], v[188:191], v[156:159], v[84:87]
	v_mfma_f32_16x16x32_f16 v[80:83], v[180:183], v[164:167], v[80:83]
	v_mfma_f32_16x16x32_f16 v[76:79], v[188:191], v[164:167], v[76:79]
	v_mfma_f32_16x16x32_f16 v[72:75], v[180:183], v[172:175], v[72:75]
	v_mfma_f32_16x16x32_f16 v[68:71], v[188:191], v[172:175], v[68:71]
	s_waitcnt lgkmcnt(0)
	v_mfma_f32_16x16x32_f16 v[96:99], v[184:187], v[152:155], v[96:99]
	v_mfma_f32_16x16x32_f16 v[92:95], v[192:195], v[152:155], v[92:95]
	v_mfma_f32_16x16x32_f16 v[88:91], v[184:187], v[160:163], v[88:91]
	v_mfma_f32_16x16x32_f16 v[84:87], v[192:195], v[160:163], v[84:87]
	v_mfma_f32_16x16x32_f16 v[80:83], v[184:187], v[168:171], v[80:83]
	v_mfma_f32_16x16x32_f16 v[76:79], v[192:195], v[168:171], v[76:79]
	v_mfma_f32_16x16x32_f16 v[72:75], v[184:187], v[176:179], v[72:75]
	v_mfma_f32_16x16x32_f16 v[68:71], v[192:195], v[176:179], v[68:71]
	s_setprio 0
	s_mov_b32 m0, s36
	v_lshl_add_u64 v[38:39], v[212:213], 0, s[84:85]
	s_barrier
	ds_read_b128 v[148:151], v211 offset:49152
	ds_read_b128 v[156:159], v211 offset:51200
	ds_read_b128 v[164:167], v211 offset:53248
	ds_read_b128 v[172:175], v211 offset:55296
	ds_read_b128 v[152:155], v211 offset:50176
	ds_read_b128 v[160:163], v211 offset:52224
	ds_read_b128 v[168:171], v211 offset:54272
	ds_read_b128 v[176:179], v211 offset:56320
	global_load_lds_dwordx4 v[38:39], off
	v_lshl_add_u64 v[38:39], v[214:215], 0, s[84:85]
	s_mov_b32 m0, s37
	s_nop 0
	global_load_lds_dwordx4 v[38:39], off
	s_barrier
	s_waitcnt lgkmcnt(4)
	s_setprio 1
	v_mfma_f32_16x16x32_f16 v[64:67], v[132:135], v[148:151], v[64:67]
	v_mfma_f32_16x16x32_f16 v[60:63], v[140:143], v[148:151], v[60:63]
	v_mfma_f32_16x16x32_f16 v[56:59], v[132:135], v[156:159], v[56:59]
	v_mfma_f32_16x16x32_f16 v[52:55], v[140:143], v[156:159], v[52:55]
	v_mfma_f32_16x16x32_f16 v[48:51], v[132:135], v[164:167], v[48:51]
	v_mfma_f32_16x16x32_f16 v[44:47], v[140:143], v[164:167], v[44:47]
	v_mfma_f32_16x16x32_f16 v[38:41], v[132:135], v[172:175], v[40:43]
	v_mfma_f32_16x16x32_f16 v[34:37], v[140:143], v[172:175], v[34:37]
	s_waitcnt lgkmcnt(0)
	v_mfma_f32_16x16x32_f16 v[64:67], v[136:139], v[152:155], v[64:67]
	v_mfma_f32_16x16x32_f16 v[60:63], v[144:147], v[152:155], v[60:63]
	v_mfma_f32_16x16x32_f16 v[56:59], v[136:139], v[160:163], v[56:59]
	v_mfma_f32_16x16x32_f16 v[52:55], v[144:147], v[160:163], v[52:55]
	v_mfma_f32_16x16x32_f16 v[48:51], v[136:139], v[168:171], v[48:51]
	v_mfma_f32_16x16x32_f16 v[44:47], v[144:147], v[168:171], v[44:47]
	v_mfma_f32_16x16x32_f16 v[40:43], v[136:139], v[176:179], v[38:41]
	v_mfma_f32_16x16x32_f16 v[36:39], v[144:147], v[176:179], v[34:37]
	s_setprio 0
	s_barrier
	s_add_u32 s14, s22, 0x40080
	s_addc_u32 s15, s23, 0
	s_add_i32 s22, s24, s29
	v_lshl_add_u64 v[34:35], s[14:15], 0, v[196:197]
	s_mov_b32 m0, s22
	s_nop 0
	global_load_lds_dwordx4 v[34:35], off
	v_lshl_add_u64 v[34:35], s[14:15], 0, v[198:199]
	s_add_i32 m0, s22, 0x2000
	s_nop 0
	global_load_lds_dwordx4 v[34:35], off
	s_waitcnt vmcnt(6)
	s_barrier
	s_setprio 1
	v_mfma_f32_16x16x32_f16 v[28:31], v[180:183], v[148:151], v[28:31]
	v_mfma_f32_16x16x32_f16 v[24:27], v[188:191], v[148:151], v[24:27]
	v_mfma_f32_16x16x32_f16 v[20:23], v[180:183], v[156:159], v[20:23]
	v_mfma_f32_16x16x32_f16 v[16:19], v[188:191], v[156:159], v[16:19]
	v_mfma_f32_16x16x32_f16 v[12:15], v[180:183], v[164:167], v[12:15]
	v_mfma_f32_16x16x32_f16 v[8:11], v[188:191], v[164:167], v[8:11]
	v_mfma_f32_16x16x32_f16 v[4:7], v[180:183], v[172:175], v[4:7]
	v_mfma_f32_16x16x32_f16 v[0:3], v[188:191], v[172:175], v[0:3]
	v_mfma_f32_16x16x32_f16 v[28:31], v[184:187], v[152:155], v[28:31]
	v_mfma_f32_16x16x32_f16 v[24:27], v[192:195], v[152:155], v[24:27]
	v_mfma_f32_16x16x32_f16 v[20:23], v[184:187], v[160:163], v[20:23]
	v_mfma_f32_16x16x32_f16 v[16:19], v[192:195], v[160:163], v[16:19]
	v_mfma_f32_16x16x32_f16 v[12:15], v[184:187], v[168:171], v[12:15]
	v_mfma_f32_16x16x32_f16 v[8:11], v[192:195], v[168:171], v[8:11]
	v_mfma_f32_16x16x32_f16 v[4:7], v[184:187], v[176:179], v[4:7]
	v_mfma_f32_16x16x32_f16 v[0:3], v[192:195], v[176:179], v[0:3]
	s_setprio 0
	s_add_i32 s11, s11, 2
	s_add_u32 s1, s1, 0x100
	s_addc_u32 s3, s3, 0
	s_cmp_gt_u32 s11, 13
	s_mov_b64 s[14:15], s[20:21]
	s_barrier
	s_cbranch_scc0 .LBB0_940
	v_lshl_add_u32 v34, s12, 8, v208
	v_lshl_or_b32 v156, s10, 8, v210
	s_cmp_lg_u32 s13, 0
	s_cselect_b64 s[10:11], -1, 0
	s_cmp_eq_u32 s13, 0
	v_ashrrev_i32_e32 v157, 31, v156
	v_ashrrev_i32_e32 v35, 31, v34
	v_mad_i64_i32 v[158:159], s[12:13], v34, s33, 0
	v_or_b32_e32 v160, 16, v34
	v_or_b32_e32 v162, 32, v34
	v_or_b32_e32 v164, 48, v34
	s_cbranch_scc1 .LBB0_946
	v_lshl_add_u64 v[132:133], s[70:71], 0, v[158:159]
	v_lshlrev_b64 v[166:167], 1, v[156:157]
	v_lshl_add_u64 v[132:133], v[132:133], 0, v[166:167]
	s_mov_b64 s[16:17], 0x2800
	v_mov_b64_e32 v[168:169], s[70:71]
	s_movk_i32 s1, 0x2000
	v_lshl_add_u64 v[134:135], v[132:133], 0, s[16:17]
	v_mad_i64_i32 v[136:137], s[12:13], v160, s33, v[168:169]
	v_add_co_u32_e32 v132, vcc, s1, v132
	v_lshl_add_u64 v[136:137], v[136:137], 0, v[166:167]
	s_nop 0
	v_addc_co_u32_e32 v133, vcc, 0, v133, vcc
	v_lshl_add_u64 v[138:139], v[136:137], 0, s[16:17]
	v_mad_i64_i32 v[140:141], s[12:13], v162, s33, v[168:169]
	v_add_co_u32_e32 v136, vcc, s1, v136
	v_lshl_add_u64 v[140:141], v[140:141], 0, v[166:167]
	s_nop 0
	v_addc_co_u32_e32 v137, vcc, 0, v137, vcc
	v_mad_i64_i32 v[144:145], s[12:13], v164, s33, v[168:169]
	global_load_dwordx4 v[170:173], v[132:133], off offset:2048
	global_load_dwordx4 v[152:155], v[136:137], off offset:2048
	global_load_dwordx4 v[174:177], v[134:135], off offset:256
	global_load_dwordx4 v[148:151], v[138:139], off offset:256
	v_add_co_u32_e32 v132, vcc, s1, v140
	v_lshl_add_u64 v[144:145], v[144:145], 0, v[166:167]
	s_nop 0
	v_addc_co_u32_e32 v133, vcc, 0, v141, vcc
	v_add_co_u32_e32 v134, vcc, s1, v144
	v_lshl_add_u64 v[142:143], v[140:141], 0, s[16:17]
	s_nop 0
	v_addc_co_u32_e32 v135, vcc, 0, v145, vcc
	v_lshl_add_u64 v[178:179], v[144:145], 0, s[16:17]
	global_load_dwordx4 v[144:147], v[132:133], off offset:2048
	global_load_dwordx4 v[136:139], v[134:135], off offset:2048
	s_nop 0
	global_load_dwordx4 v[140:143], v[142:143], off offset:256
	s_nop 0
	global_load_dwordx4 v[132:135], v[178:179], off offset:256
	v_ashrrev_i32_e32 v161, 31, v160
	v_ashrrev_i32_e32 v163, 31, v162
	v_ashrrev_i32_e32 v165, 31, v164
	s_waitcnt vmcnt(0)
	v_cvt_f32_f16_e32 v32, v170
	v_cvt_f32_f16_sdwa v170, v170 dst_sel:DWORD dst_unused:UNUSED_PAD src0_sel:WORD_1
	v_lshlrev_b64 v[178:179], 11, v[34:35]
	v_readlane_b32 s14, v252, 9
	v_max_f32_e32 v32, 0xc1f00000, v32
	v_max_f32_e32 v35, 0xc1f00000, v170
	v_cvt_f32_f16_e32 v170, v171
	v_cvt_f32_f16_sdwa v171, v171 dst_sel:DWORD dst_unused:UNUSED_PAD src0_sel:WORD_1
	v_mul_f32_e32 v35, 0xbfb8aa3b, v35
	v_exp_f32_e32 v35, v35
	v_max_f32_e32 v170, 0xc1f00000, v170
	v_mul_f32_e32 v170, 0xbfb8aa3b, v170
	v_exp_f32_e32 v180, v170
	v_max_f32_e32 v170, 0xc1f00000, v171
	v_mul_f32_e32 v170, 0xbfb8aa3b, v170
	v_cvt_f32_f16_e32 v171, v172
	v_exp_f32_e32 v181, v170
	v_cvt_f32_f16_sdwa v170, v172 dst_sel:DWORD dst_unused:UNUSED_PAD src0_sel:WORD_1
	v_mul_f32_e32 v32, 0xbfb8aa3b, v32
	v_max_f32_e32 v171, 0xc1f00000, v171
	v_mul_f32_e32 v171, 0xbfb8aa3b, v171
	v_max_f32_e32 v170, 0xc1f00000, v170
	v_mul_f32_e32 v170, 0xbfb8aa3b, v170
	v_exp_f32_e32 v182, v171
	v_cvt_f32_f16_e32 v171, v173
	v_exp_f32_e32 v183, v170
	v_cvt_f32_f16_sdwa v170, v173 dst_sel:DWORD dst_unused:UNUSED_PAD src0_sel:WORD_1
	v_exp_f32_e32 v32, v32
	v_max_f32_e32 v171, 0xc1f00000, v171
	v_mul_f32_e32 v171, 0xbfb8aa3b, v171
	v_max_f32_e32 v170, 0xc1f00000, v170
	v_mul_f32_e32 v170, 0xbfb8aa3b, v170
	v_add_f32_e32 v35, 1.0, v35
	v_exp_f32_e32 v184, v171
	v_exp_f32_e32 v185, v170
	v_rcp_f32_e32 v170, v35
	v_add_f32_e32 v35, 1.0, v180
	v_rcp_f32_e32 v171, v35
	v_add_f32_e32 v35, 1.0, v181
	v_add_f32_e32 v32, 1.0, v32
	v_rcp_f32_e32 v172, v35
	v_add_f32_e32 v35, 1.0, v182
	v_rcp_f32_e32 v32, v32
	v_rcp_f32_e32 v173, v35
	v_add_f32_e32 v35, 1.0, v183
	v_rcp_f32_e32 v180, v35
	v_add_f32_e32 v35, 1.0, v184
	v_rcp_f32_e32 v181, v35
	v_mov_b32_e32 v182, v129
	v_mov_b32_e32 v183, v130
	v_pk_mul_f32 v[170:171], v[182:183], v[170:171]
	v_pk_mov_b32 v[182:183], v[130:131], v[124:125] op_sel:[1,0]
	v_add_f32_e32 v35, 1.0, v185
	v_fma_mixlo_f16 v32, v128, v32, 0
	v_cvt_pk_f16_f32 v171, v170, v171
	v_pk_mul_f32 v[172:173], v[182:183], v[172:173]
	v_rcp_f32_e32 v35, v35
	v_pack_b32_f16 v170, v32, v171
	v_cvt_pk_f16_f32 v32, v172, v173
	v_mov_b32_e32 v172, v125
	v_mov_b32_e32 v173, v126
	v_pk_mul_f32 v[172:173], v[172:173], v[180:181]
	v_readlane_b32 s15, v252, 10
	v_cvt_pk_f16_f32 v173, v172, v173
	v_alignbit_b32 v172, v173, v32, 16
	v_lshrrev_b32_e32 v173, 16, v173
	v_lshl_add_u64 v[178:179], s[14:15], 0, v[178:179]
	v_alignbit_b32 v171, v32, v171, 16
	v_fma_mixhi_f16 v173, v127, v35, 0
	v_lshl_add_u64 v[178:179], v[178:179], 0, v[166:167]
	global_store_dwordx4 v[178:179], v[170:173], off
	v_cvt_f32_f16_sdwa v35, v174 dst_sel:DWORD dst_unused:UNUSED_PAD src0_sel:WORD_1
	v_cvt_f32_f16_e32 v32, v174
	v_cvt_f32_f16_e32 v170, v175
	v_cvt_f32_f16_sdwa v171, v175 dst_sel:DWORD dst_unused:UNUSED_PAD src0_sel:WORD_1
	v_max_f32_e32 v35, 0xc1f00000, v35
	v_mul_f32_e32 v35, 0xbfb8aa3b, v35
	v_max_f32_e32 v170, 0xc1f00000, v170
	v_mul_f32_e32 v170, 0xbfb8aa3b, v170
	v_exp_f32_e32 v172, v170
	v_max_f32_e32 v170, 0xc1f00000, v171
	v_mul_f32_e32 v170, 0xbfb8aa3b, v170
	v_cvt_f32_f16_e32 v171, v176
	v_exp_f32_e32 v173, v170
	v_cvt_f32_f16_sdwa v170, v176 dst_sel:DWORD dst_unused:UNUSED_PAD src0_sel:WORD_1
	v_exp_f32_e32 v35, v35
	v_max_f32_e32 v171, 0xc1f00000, v171
	v_mul_f32_e32 v171, 0xbfb8aa3b, v171
	v_max_f32_e32 v170, 0xc1f00000, v170
	v_mul_f32_e32 v170, 0xbfb8aa3b, v170
	v_exp_f32_e32 v174, v171
	v_cvt_f32_f16_e32 v171, v177
	v_exp_f32_e32 v175, v170
	v_cvt_f32_f16_sdwa v170, v177 dst_sel:DWORD dst_unused:UNUSED_PAD src0_sel:WORD_1
	v_max_f32_e32 v32, 0xc1f00000, v32
	v_mul_f32_e32 v32, 0xbfb8aa3b, v32
	v_exp_f32_e32 v32, v32
	v_max_f32_e32 v171, 0xc1f00000, v171
	v_max_f32_e32 v170, 0xc1f00000, v170
	v_mul_f32_e32 v171, 0xbfb8aa3b, v171
	v_mul_f32_e32 v170, 0xbfb8aa3b, v170
	v_add_f32_e32 v35, 1.0, v35
	v_exp_f32_e32 v176, v171
	v_exp_f32_e32 v177, v170
	v_rcp_f32_e32 v170, v35
	v_add_f32_e32 v35, 1.0, v172
	v_rcp_f32_e32 v171, v35
	v_add_f32_e32 v35, 1.0, v173
	v_add_f32_e32 v32, 1.0, v32
	v_rcp_f32_e32 v172, v35
	v_add_f32_e32 v35, 1.0, v174
	v_rcp_f32_e32 v32, v32
	v_rcp_f32_e32 v173, v35
	v_add_f32_e32 v35, 1.0, v175
	v_rcp_f32_e32 v174, v35
	v_add_f32_e32 v35, 1.0, v176
	v_rcp_f32_e32 v175, v35
	v_add_f32_e32 v35, 1.0, v177
	v_mov_b32_e32 v176, v97
	v_mov_b32_e32 v177, v98
	v_pk_mul_f32 v[170:171], v[176:177], v[170:171]
	v_pk_mov_b32 v[176:177], v[98:99], v[92:93] op_sel:[1,0]
	v_fma_mixlo_f16 v32, v96, v32, 0
	v_cvt_pk_f16_f32 v171, v170, v171
	v_pk_mul_f32 v[172:173], v[176:177], v[172:173]
	v_rcp_f32_e32 v35, v35
	v_pack_b32_f16 v170, v32, v171
	v_cvt_pk_f16_f32 v32, v172, v173
	v_mov_b32_e32 v172, v93
	v_mov_b32_e32 v173, v94
	v_pk_mul_f32 v[172:173], v[172:173], v[174:175]
	v_alignbit_b32 v171, v32, v171, 16
	v_cvt_pk_f16_f32 v173, v172, v173
	v_alignbit_b32 v172, v173, v32, 16
	v_lshrrev_b32_e32 v173, 16, v173
	v_fma_mixhi_f16 v173, v95, v35, 0
	v_cvt_f32_f16_e32 v32, v152
	v_cvt_f32_f16_sdwa v35, v152 dst_sel:DWORD dst_unused:UNUSED_PAD src0_sel:WORD_1
	v_cvt_f32_f16_e32 v152, v153
	v_cvt_f32_f16_sdwa v153, v153 dst_sel:DWORD dst_unused:UNUSED_PAD src0_sel:WORD_1
	global_store_dwordx4 v[178:179], v[170:173], off offset:256
	v_max_f32_e32 v35, 0xc1f00000, v35
	v_max_f32_e32 v152, 0xc1f00000, v152
	v_mul_f32_e32 v152, 0xbfb8aa3b, v152
	v_lshlrev_b64 v[170:171], 11, v[160:161]
	v_exp_f32_e32 v161, v152
	v_max_f32_e32 v152, 0xc1f00000, v153
	v_mul_f32_e32 v152, 0xbfb8aa3b, v152
	v_cvt_f32_f16_e32 v153, v154
	v_exp_f32_e32 v172, v152
	v_cvt_f32_f16_sdwa v152, v154 dst_sel:DWORD dst_unused:UNUSED_PAD src0_sel:WORD_1
	v_mul_f32_e32 v35, 0xbfb8aa3b, v35
	v_max_f32_e32 v153, 0xc1f00000, v153
	v_mul_f32_e32 v153, 0xbfb8aa3b, v153
	v_max_f32_e32 v152, 0xc1f00000, v152
	v_mul_f32_e32 v152, 0xbfb8aa3b, v152
	v_exp_f32_e32 v173, v153
	v_cvt_f32_f16_e32 v153, v155
	v_exp_f32_e32 v174, v152
	v_cvt_f32_f16_sdwa v152, v155 dst_sel:DWORD dst_unused:UNUSED_PAD src0_sel:WORD_1
	v_exp_f32_e32 v35, v35
	v_max_f32_e32 v32, 0xc1f00000, v32
	v_mul_f32_e32 v32, 0xbfb8aa3b, v32
	v_exp_f32_e32 v32, v32
	v_max_f32_e32 v153, 0xc1f00000, v153
	v_max_f32_e32 v152, 0xc1f00000, v152
	v_mul_f32_e32 v153, 0xbfb8aa3b, v153
	v_mul_f32_e32 v152, 0xbfb8aa3b, v152
	v_add_f32_e32 v35, 1.0, v35
	v_exp_f32_e32 v175, v153
	v_exp_f32_e32 v176, v152
	v_rcp_f32_e32 v152, v35
	v_add_f32_e32 v35, 1.0, v161
	v_rcp_f32_e32 v153, v35
	v_add_f32_e32 v35, 1.0, v172
	v_add_f32_e32 v32, 1.0, v32
	v_rcp_f32_e32 v154, v35
	v_add_f32_e32 v35, 1.0, v173
	v_rcp_f32_e32 v32, v32
	v_rcp_f32_e32 v155, v35
	v_add_f32_e32 v35, 1.0, v174
	v_rcp_f32_e32 v172, v35
	v_add_f32_e32 v35, 1.0, v175
	v_rcp_f32_e32 v173, v35
	v_mov_b32_e32 v174, v121
	v_mov_b32_e32 v175, v122
	v_pk_mul_f32 v[152:153], v[174:175], v[152:153]
	v_pk_mov_b32 v[174:175], v[122:123], v[116:117] op_sel:[1,0]
	v_add_f32_e32 v35, 1.0, v176
	v_fma_mixlo_f16 v32, v120, v32, 0
	v_cvt_pk_f16_f32 v153, v152, v153
	v_pk_mul_f32 v[154:155], v[174:175], v[154:155]
	v_rcp_f32_e32 v35, v35
	v_pack_b32_f16 v152, v32, v153
	v_cvt_pk_f16_f32 v32, v154, v155
	v_mov_b32_e32 v154, v117
	v_mov_b32_e32 v155, v118
	v_pk_mul_f32 v[154:155], v[154:155], v[172:173]
	v_alignbit_b32 v153, v32, v153, 16
	v_cvt_pk_f16_f32 v155, v154, v155
	v_alignbit_b32 v154, v155, v32, 16
	v_lshrrev_b32_e32 v155, 16, v155
	v_fma_mixhi_f16 v155, v119, v35, 0
	v_cvt_f32_f16_e32 v32, v148
	v_cvt_f32_f16_sdwa v35, v148 dst_sel:DWORD dst_unused:UNUSED_PAD src0_sel:WORD_1
	v_cvt_f32_f16_e32 v148, v149
	v_cvt_f32_f16_sdwa v149, v149 dst_sel:DWORD dst_unused:UNUSED_PAD src0_sel:WORD_1
	v_lshl_add_u64 v[170:171], s[14:15], 0, v[170:171]
	v_lshl_add_u64 v[170:171], v[170:171], 0, v[166:167]
	v_max_f32_e32 v148, 0xc1f00000, v148
	v_mul_f32_e32 v148, 0xbfb8aa3b, v148
	global_store_dwordx4 v[170:171], v[152:155], off
	v_max_f32_e32 v35, 0xc1f00000, v35
	v_mul_f32_e32 v35, 0xbfb8aa3b, v35
	v_exp_f32_e32 v152, v148
	v_max_f32_e32 v148, 0xc1f00000, v149
	v_mul_f32_e32 v148, 0xbfb8aa3b, v148
	v_cvt_f32_f16_e32 v149, v150
	v_exp_f32_e32 v153, v148
	v_cvt_f32_f16_sdwa v148, v150 dst_sel:DWORD dst_unused:UNUSED_PAD src0_sel:WORD_1
	v_exp_f32_e32 v35, v35
	v_max_f32_e32 v149, 0xc1f00000, v149
	v_mul_f32_e32 v149, 0xbfb8aa3b, v149
	v_max_f32_e32 v148, 0xc1f00000, v148
	v_mul_f32_e32 v148, 0xbfb8aa3b, v148
	v_exp_f32_e32 v154, v149
	v_cvt_f32_f16_e32 v149, v151
	v_exp_f32_e32 v155, v148
	v_cvt_f32_f16_sdwa v148, v151 dst_sel:DWORD dst_unused:UNUSED_PAD src0_sel:WORD_1
	v_max_f32_e32 v32, 0xc1f00000, v32
	v_mul_f32_e32 v32, 0xbfb8aa3b, v32
	v_exp_f32_e32 v32, v32
	v_max_f32_e32 v149, 0xc1f00000, v149
	v_max_f32_e32 v148, 0xc1f00000, v148
	v_mul_f32_e32 v149, 0xbfb8aa3b, v149
	v_mul_f32_e32 v148, 0xbfb8aa3b, v148
	v_add_f32_e32 v35, 1.0, v35
	v_exp_f32_e32 v161, v149
	v_exp_f32_e32 v172, v148
	v_rcp_f32_e32 v148, v35
	v_add_f32_e32 v35, 1.0, v152
	v_rcp_f32_e32 v149, v35
	v_add_f32_e32 v35, 1.0, v153
	v_add_f32_e32 v32, 1.0, v32
	v_rcp_f32_e32 v150, v35
	v_add_f32_e32 v35, 1.0, v154
	v_rcp_f32_e32 v32, v32
	v_rcp_f32_e32 v151, v35
	v_add_f32_e32 v35, 1.0, v155
	v_rcp_f32_e32 v152, v35
	v_add_f32_e32 v35, 1.0, v161
	v_rcp_f32_e32 v153, v35
	v_mov_b32_e32 v154, v89
	v_mov_b32_e32 v155, v90
	v_pk_mul_f32 v[148:149], v[154:155], v[148:149]
	v_pk_mov_b32 v[154:155], v[90:91], v[84:85] op_sel:[1,0]
	v_add_f32_e32 v35, 1.0, v172
	v_fma_mixlo_f16 v32, v88, v32, 0
	v_cvt_pk_f16_f32 v149, v148, v149
	v_pk_mul_f32 v[150:151], v[154:155], v[150:151]
	v_rcp_f32_e32 v35, v35
	v_pack_b32_f16 v148, v32, v149
	v_cvt_pk_f16_f32 v32, v150, v151
	v_mov_b32_e32 v150, v85
	v_mov_b32_e32 v151, v86
	v_pk_mul_f32 v[150:151], v[150:151], v[152:153]
	v_alignbit_b32 v149, v32, v149, 16
	v_cvt_pk_f16_f32 v151, v150, v151
	v_alignbit_b32 v150, v151, v32, 16
	v_lshrrev_b32_e32 v151, 16, v151
	v_fma_mixhi_f16 v151, v87, v35, 0
	v_cvt_f32_f16_e32 v32, v144
	v_cvt_f32_f16_sdwa v35, v144 dst_sel:DWORD dst_unused:UNUSED_PAD src0_sel:WORD_1
	v_cvt_f32_f16_e32 v144, v145
	v_cvt_f32_f16_sdwa v145, v145 dst_sel:DWORD dst_unused:UNUSED_PAD src0_sel:WORD_1
	global_store_dwordx4 v[170:171], v[148:151], off offset:256
	v_max_f32_e32 v35, 0xc1f00000, v35
	v_max_f32_e32 v144, 0xc1f00000, v144
	v_mul_f32_e32 v144, 0xbfb8aa3b, v144
	v_exp_f32_e32 v150, v144
	v_max_f32_e32 v144, 0xc1f00000, v145
	v_mul_f32_e32 v144, 0xbfb8aa3b, v144
	v_cvt_f32_f16_e32 v145, v146
	v_exp_f32_e32 v151, v144
	v_cvt_f32_f16_sdwa v144, v146 dst_sel:DWORD dst_unused:UNUSED_PAD src0_sel:WORD_1
	v_mul_f32_e32 v35, 0xbfb8aa3b, v35
	v_max_f32_e32 v145, 0xc1f00000, v145
	v_mul_f32_e32 v145, 0xbfb8aa3b, v145
	v_max_f32_e32 v144, 0xc1f00000, v144
	v_mul_f32_e32 v144, 0xbfb8aa3b, v144
	v_exp_f32_e32 v152, v145
	v_cvt_f32_f16_e32 v145, v147
	v_exp_f32_e32 v153, v144
	v_cvt_f32_f16_sdwa v144, v147 dst_sel:DWORD dst_unused:UNUSED_PAD src0_sel:WORD_1
	v_exp_f32_e32 v35, v35
	v_max_f32_e32 v32, 0xc1f00000, v32
	v_mul_f32_e32 v32, 0xbfb8aa3b, v32
	v_exp_f32_e32 v32, v32
	v_max_f32_e32 v145, 0xc1f00000, v145
	v_max_f32_e32 v144, 0xc1f00000, v144
	v_mul_f32_e32 v145, 0xbfb8aa3b, v145
	v_mul_f32_e32 v144, 0xbfb8aa3b, v144
	v_add_f32_e32 v35, 1.0, v35
	v_exp_f32_e32 v154, v145
	v_exp_f32_e32 v155, v144
	v_rcp_f32_e32 v144, v35
	v_add_f32_e32 v35, 1.0, v150
	v_rcp_f32_e32 v145, v35
	v_add_f32_e32 v35, 1.0, v151
	v_add_f32_e32 v32, 1.0, v32
	v_rcp_f32_e32 v146, v35
	v_add_f32_e32 v35, 1.0, v152
	v_rcp_f32_e32 v32, v32
	v_rcp_f32_e32 v147, v35
	v_add_f32_e32 v35, 1.0, v153
	v_rcp_f32_e32 v150, v35
	v_add_f32_e32 v35, 1.0, v154
	v_rcp_f32_e32 v151, v35
	v_mov_b32_e32 v152, v113
	v_mov_b32_e32 v153, v114
	v_pk_mul_f32 v[144:145], v[152:153], v[144:145]
	v_pk_mov_b32 v[152:153], v[114:115], v[108:109] op_sel:[1,0]
	v_add_f32_e32 v35, 1.0, v155
	v_fma_mixlo_f16 v32, v112, v32, 0
	v_cvt_pk_f16_f32 v145, v144, v145
	v_pk_mul_f32 v[146:147], v[152:153], v[146:147]
	v_rcp_f32_e32 v35, v35
	v_pack_b32_f16 v144, v32, v145
	v_cvt_pk_f16_f32 v32, v146, v147
	v_mov_b32_e32 v146, v109
	v_mov_b32_e32 v147, v110
	v_pk_mul_f32 v[146:147], v[146:147], v[150:151]
	v_alignbit_b32 v145, v32, v145, 16
	v_cvt_pk_f16_f32 v147, v146, v147
	v_alignbit_b32 v146, v147, v32, 16
	v_lshrrev_b32_e32 v147, 16, v147
	v_fma_mixhi_f16 v147, v111, v35, 0
	v_cvt_f32_f16_e32 v32, v140
	v_cvt_f32_f16_sdwa v35, v140 dst_sel:DWORD dst_unused:UNUSED_PAD src0_sel:WORD_1
	v_cvt_f32_f16_e32 v140, v141
	v_cvt_f32_f16_sdwa v141, v141 dst_sel:DWORD dst_unused:UNUSED_PAD src0_sel:WORD_1
	v_lshlrev_b64 v[148:149], 11, v[162:163]
	v_lshl_add_u64 v[148:149], s[14:15], 0, v[148:149]
	v_max_f32_e32 v140, 0xc1f00000, v140
	v_lshl_add_u64 v[148:149], v[148:149], 0, v[166:167]
	v_mul_f32_e32 v140, 0xbfb8aa3b, v140
	global_store_dwordx4 v[148:149], v[144:147], off
	v_max_f32_e32 v35, 0xc1f00000, v35
	v_mul_f32_e32 v35, 0xbfb8aa3b, v35
	v_exp_f32_e32 v144, v140
	v_max_f32_e32 v140, 0xc1f00000, v141
	v_mul_f32_e32 v140, 0xbfb8aa3b, v140
	v_cvt_f32_f16_e32 v141, v142
	v_exp_f32_e32 v145, v140
	v_cvt_f32_f16_sdwa v140, v142 dst_sel:DWORD dst_unused:UNUSED_PAD src0_sel:WORD_1
	v_exp_f32_e32 v35, v35
	v_max_f32_e32 v141, 0xc1f00000, v141
	v_mul_f32_e32 v141, 0xbfb8aa3b, v141
	v_max_f32_e32 v140, 0xc1f00000, v140
	v_mul_f32_e32 v140, 0xbfb8aa3b, v140
	v_exp_f32_e32 v146, v141
	v_cvt_f32_f16_e32 v141, v143
	v_exp_f32_e32 v147, v140
	v_cvt_f32_f16_sdwa v140, v143 dst_sel:DWORD dst_unused:UNUSED_PAD src0_sel:WORD_1
	v_max_f32_e32 v32, 0xc1f00000, v32
	v_mul_f32_e32 v32, 0xbfb8aa3b, v32
	v_exp_f32_e32 v32, v32
	v_max_f32_e32 v141, 0xc1f00000, v141
	v_max_f32_e32 v140, 0xc1f00000, v140
	v_mul_f32_e32 v141, 0xbfb8aa3b, v141
	v_mul_f32_e32 v140, 0xbfb8aa3b, v140
	v_add_f32_e32 v35, 1.0, v35
	v_exp_f32_e32 v150, v141
	v_exp_f32_e32 v151, v140
	v_rcp_f32_e32 v140, v35
	v_add_f32_e32 v35, 1.0, v144
	v_rcp_f32_e32 v141, v35
	v_add_f32_e32 v35, 1.0, v145
	v_add_f32_e32 v32, 1.0, v32
	v_rcp_f32_e32 v142, v35
	v_add_f32_e32 v35, 1.0, v146
	v_rcp_f32_e32 v32, v32
	v_rcp_f32_e32 v143, v35
	v_add_f32_e32 v35, 1.0, v147
	v_rcp_f32_e32 v144, v35
	v_add_f32_e32 v35, 1.0, v150
	v_rcp_f32_e32 v145, v35
	v_mov_b32_e32 v146, v81
	v_mov_b32_e32 v147, v82
	v_pk_mul_f32 v[140:141], v[146:147], v[140:141]
	v_pk_mov_b32 v[146:147], v[82:83], v[76:77] op_sel:[1,0]
	v_add_f32_e32 v35, 1.0, v151
	v_fma_mixlo_f16 v32, v80, v32, 0
	v_cvt_pk_f16_f32 v141, v140, v141
	v_pk_mul_f32 v[142:143], v[146:147], v[142:143]
	v_rcp_f32_e32 v35, v35
	v_pack_b32_f16 v140, v32, v141
	v_cvt_pk_f16_f32 v32, v142, v143
	v_mov_b32_e32 v142, v77
	v_mov_b32_e32 v143, v78
	v_pk_mul_f32 v[142:143], v[142:143], v[144:145]
	v_alignbit_b32 v141, v32, v141, 16
	v_cvt_pk_f16_f32 v143, v142, v143
	v_alignbit_b32 v142, v143, v32, 16
	v_lshrrev_b32_e32 v143, 16, v143
	v_fma_mixhi_f16 v143, v79, v35, 0
	v_cvt_f32_f16_e32 v32, v136
	v_cvt_f32_f16_sdwa v35, v136 dst_sel:DWORD dst_unused:UNUSED_PAD src0_sel:WORD_1
	v_cvt_f32_f16_e32 v136, v137
	v_cvt_f32_f16_sdwa v137, v137 dst_sel:DWORD dst_unused:UNUSED_PAD src0_sel:WORD_1
	global_store_dwordx4 v[148:149], v[140:143], off offset:256
	v_max_f32_e32 v35, 0xc1f00000, v35
	v_max_f32_e32 v136, 0xc1f00000, v136
	v_mul_f32_e32 v136, 0xbfb8aa3b, v136
	v_exp_f32_e32 v142, v136
	v_max_f32_e32 v136, 0xc1f00000, v137
	v_mul_f32_e32 v136, 0xbfb8aa3b, v136
	v_cvt_f32_f16_e32 v137, v138
	v_exp_f32_e32 v143, v136
	v_cvt_f32_f16_sdwa v136, v138 dst_sel:DWORD dst_unused:UNUSED_PAD src0_sel:WORD_1
	v_mul_f32_e32 v35, 0xbfb8aa3b, v35
	v_max_f32_e32 v137, 0xc1f00000, v137
	v_mul_f32_e32 v137, 0xbfb8aa3b, v137
	v_max_f32_e32 v136, 0xc1f00000, v136
	v_mul_f32_e32 v136, 0xbfb8aa3b, v136
	v_exp_f32_e32 v144, v137
	v_cvt_f32_f16_e32 v137, v139
	v_exp_f32_e32 v145, v136
	v_cvt_f32_f16_sdwa v136, v139 dst_sel:DWORD dst_unused:UNUSED_PAD src0_sel:WORD_1
	v_exp_f32_e32 v35, v35
	v_max_f32_e32 v32, 0xc1f00000, v32
	v_mul_f32_e32 v32, 0xbfb8aa3b, v32
	v_exp_f32_e32 v32, v32
	v_max_f32_e32 v137, 0xc1f00000, v137
	v_max_f32_e32 v136, 0xc1f00000, v136
	v_mul_f32_e32 v137, 0xbfb8aa3b, v137
	v_mul_f32_e32 v136, 0xbfb8aa3b, v136
	v_add_f32_e32 v35, 1.0, v35
	v_exp_f32_e32 v146, v137
	v_exp_f32_e32 v147, v136
	v_rcp_f32_e32 v136, v35
	v_add_f32_e32 v35, 1.0, v142
	v_rcp_f32_e32 v137, v35
	v_add_f32_e32 v35, 1.0, v143
	v_add_f32_e32 v32, 1.0, v32
	v_rcp_f32_e32 v138, v35
	v_add_f32_e32 v35, 1.0, v144
	v_rcp_f32_e32 v32, v32
	v_rcp_f32_e32 v139, v35
	v_add_f32_e32 v35, 1.0, v145
	v_rcp_f32_e32 v142, v35
	v_add_f32_e32 v35, 1.0, v146
	v_rcp_f32_e32 v143, v35
	v_mov_b32_e32 v144, v105
	v_mov_b32_e32 v145, v106
	v_pk_mul_f32 v[136:137], v[144:145], v[136:137]
	v_pk_mov_b32 v[144:145], v[106:107], v[100:101] op_sel:[1,0]
	v_add_f32_e32 v35, 1.0, v147
	v_fma_mixlo_f16 v32, v104, v32, 0
	v_cvt_pk_f16_f32 v137, v136, v137
	v_pk_mul_f32 v[138:139], v[144:145], v[138:139]
	v_rcp_f32_e32 v35, v35
	v_pack_b32_f16 v136, v32, v137
	v_cvt_pk_f16_f32 v32, v138, v139
	v_mov_b32_e32 v138, v101
	v_mov_b32_e32 v139, v102
	v_pk_mul_f32 v[138:139], v[138:139], v[142:143]
	v_alignbit_b32 v137, v32, v137, 16
	v_cvt_pk_f16_f32 v139, v138, v139
	v_alignbit_b32 v138, v139, v32, 16
	v_lshrrev_b32_e32 v139, 16, v139
	v_fma_mixhi_f16 v139, v103, v35, 0
	v_cvt_f32_f16_e32 v32, v132
	v_cvt_f32_f16_sdwa v35, v132 dst_sel:DWORD dst_unused:UNUSED_PAD src0_sel:WORD_1
	v_cvt_f32_f16_e32 v132, v133
	v_cvt_f32_f16_sdwa v133, v133 dst_sel:DWORD dst_unused:UNUSED_PAD src0_sel:WORD_1
	v_lshlrev_b64 v[140:141], 11, v[164:165]
	v_lshl_add_u64 v[140:141], s[14:15], 0, v[140:141]
	v_max_f32_e32 v132, 0xc1f00000, v132
	v_lshl_add_u64 v[140:141], v[140:141], 0, v[166:167]
	v_mul_f32_e32 v132, 0xbfb8aa3b, v132
	global_store_dwordx4 v[140:141], v[136:139], off
	v_max_f32_e32 v35, 0xc1f00000, v35
	v_mul_f32_e32 v35, 0xbfb8aa3b, v35
	v_exp_f32_e32 v136, v132
	v_max_f32_e32 v132, 0xc1f00000, v133
	v_mul_f32_e32 v132, 0xbfb8aa3b, v132
	v_cvt_f32_f16_e32 v133, v134
	v_exp_f32_e32 v137, v132
	v_cvt_f32_f16_sdwa v132, v134 dst_sel:DWORD dst_unused:UNUSED_PAD src0_sel:WORD_1
	v_exp_f32_e32 v35, v35
	v_max_f32_e32 v133, 0xc1f00000, v133
	v_mul_f32_e32 v133, 0xbfb8aa3b, v133
	v_max_f32_e32 v132, 0xc1f00000, v132
	v_mul_f32_e32 v132, 0xbfb8aa3b, v132
	v_exp_f32_e32 v138, v133
	v_cvt_f32_f16_e32 v133, v135
	v_exp_f32_e32 v139, v132
	v_cvt_f32_f16_sdwa v132, v135 dst_sel:DWORD dst_unused:UNUSED_PAD src0_sel:WORD_1
	v_max_f32_e32 v32, 0xc1f00000, v32
	v_mul_f32_e32 v32, 0xbfb8aa3b, v32
	v_exp_f32_e32 v32, v32
	v_max_f32_e32 v133, 0xc1f00000, v133
	v_max_f32_e32 v132, 0xc1f00000, v132
	v_mul_f32_e32 v133, 0xbfb8aa3b, v133
	v_mul_f32_e32 v132, 0xbfb8aa3b, v132
	v_add_f32_e32 v35, 1.0, v35
	v_exp_f32_e32 v142, v133
	v_exp_f32_e32 v143, v132
	v_rcp_f32_e32 v132, v35
	v_add_f32_e32 v35, 1.0, v136
	v_rcp_f32_e32 v133, v35
	v_add_f32_e32 v35, 1.0, v137
	v_add_f32_e32 v32, 1.0, v32
	v_rcp_f32_e32 v134, v35
	v_add_f32_e32 v35, 1.0, v138
	v_rcp_f32_e32 v32, v32
	v_rcp_f32_e32 v135, v35
	v_add_f32_e32 v35, 1.0, v139
	v_rcp_f32_e32 v136, v35
	v_add_f32_e32 v35, 1.0, v142
	v_rcp_f32_e32 v137, v35
	v_mov_b32_e32 v138, v73
	v_mov_b32_e32 v139, v74
	v_pk_mul_f32 v[132:133], v[138:139], v[132:133]
	v_pk_mov_b32 v[138:139], v[74:75], v[68:69] op_sel:[1,0]
	v_add_f32_e32 v35, 1.0, v143
	v_fma_mixlo_f16 v32, v72, v32, 0
	v_cvt_pk_f16_f32 v133, v132, v133
	v_pk_mul_f32 v[134:135], v[138:139], v[134:135]
	v_rcp_f32_e32 v35, v35
	v_pack_b32_f16 v132, v32, v133
	v_cvt_pk_f16_f32 v32, v134, v135
	v_mov_b32_e32 v134, v69
	v_mov_b32_e32 v135, v70
	v_pk_mul_f32 v[134:135], v[134:135], v[136:137]
	v_alignbit_b32 v133, v32, v133, 16
	v_cvt_pk_f16_f32 v135, v134, v135
	v_alignbit_b32 v134, v135, v32, 16
	v_lshrrev_b32_e32 v135, 16, v135
	v_fma_mixhi_f16 v135, v71, v35, 0
	global_store_dwordx4 v[140:141], v[132:135], off offset:256
	v_add_u32_e32 v184, 0x80, v34
	s_nop 0
	v_mad_i64_i32 v[132:133], s[12:13], v184, s33, v[168:169]
	v_lshl_add_u64 v[132:133], v[132:133], 0, v[166:167]
	v_add_u32_e32 v174, 0x90, v34
	v_lshl_add_u64 v[134:135], v[132:133], 0, s[16:17]
	v_mad_i64_i32 v[136:137], s[12:13], v174, s33, v[168:169]
	v_add_co_u32_e32 v132, vcc, s1, v132
	v_lshl_add_u64 v[136:137], v[136:137], 0, v[166:167]
	v_add_u32_e32 v172, 0xa0, v34
	v_addc_co_u32_e32 v133, vcc, 0, v133, vcc
	v_lshl_add_u64 v[138:139], v[136:137], 0, s[16:17]
	v_mad_i64_i32 v[140:141], s[12:13], v172, s33, v[168:169]
	v_add_co_u32_e32 v136, vcc, s1, v136
	v_lshl_add_u64 v[140:141], v[140:141], 0, v[166:167]
	v_add_u32_e32 v170, 0xb0, v34
	v_addc_co_u32_e32 v137, vcc, 0, v137, vcc
	v_mad_i64_i32 v[144:145], s[12:13], v170, s33, v[168:169]
	global_load_dwordx4 v[176:179], v[132:133], off offset:2048
	global_load_dwordx4 v[152:155], v[136:137], off offset:2048
	global_load_dwordx4 v[180:183], v[134:135], off offset:256
	global_load_dwordx4 v[148:151], v[138:139], off offset:256
	v_add_co_u32_e32 v132, vcc, s1, v140
	v_lshl_add_u64 v[144:145], v[144:145], 0, v[166:167]
	s_nop 0
	v_addc_co_u32_e32 v133, vcc, 0, v141, vcc
	v_add_co_u32_e32 v134, vcc, s1, v144
	v_lshl_add_u64 v[142:143], v[140:141], 0, s[16:17]
	s_nop 0
	v_addc_co_u32_e32 v135, vcc, 0, v145, vcc
	v_lshl_add_u64 v[168:169], v[144:145], 0, s[16:17]
	global_load_dwordx4 v[144:147], v[132:133], off offset:2048
	global_load_dwordx4 v[136:139], v[134:135], off offset:2048
	s_nop 0
	global_load_dwordx4 v[140:143], v[142:143], off offset:256
	s_nop 0
	global_load_dwordx4 v[132:135], v[168:169], off offset:256
	v_ashrrev_i32_e32 v185, 31, v184
	v_ashrrev_i32_e32 v175, 31, v174
	v_ashrrev_i32_e32 v173, 31, v172
	v_ashrrev_i32_e32 v171, 31, v170
	s_waitcnt vmcnt(0)
	v_cvt_f32_f16_e32 v32, v176
	v_cvt_f32_f16_sdwa v35, v176 dst_sel:DWORD dst_unused:UNUSED_PAD src0_sel:WORD_1
	v_cvt_f32_f16_sdwa v176, v178 dst_sel:DWORD dst_unused:UNUSED_PAD src0_sel:WORD_1
	v_cvt_f32_f16_e32 v161, v177
	v_cvt_f32_f16_sdwa v163, v177 dst_sel:DWORD dst_unused:UNUSED_PAD src0_sel:WORD_1
	v_cvt_f32_f16_e32 v165, v178
	v_max_f32_e32 v176, 0xc1f00000, v176
	v_max_f32_e32 v35, 0xc1f00000, v35
	v_mul_f32_e32 v176, 0xbfb8aa3b, v176
	v_lshlrev_b64 v[168:169], 11, v[184:185]
	v_mul_f32_e32 v35, 0xbfb8aa3b, v35
	v_max_f32_e32 v161, 0xc1f00000, v161
	v_cvt_f32_f16_e32 v177, v179
	v_exp_f32_e32 v184, v176
	v_cvt_f32_f16_sdwa v176, v179 dst_sel:DWORD dst_unused:UNUSED_PAD src0_sel:WORD_1
	v_exp_f32_e32 v35, v35
	v_mul_f32_e32 v161, 0xbfb8aa3b, v161
	v_max_f32_e32 v163, 0xc1f00000, v163
	v_max_f32_e32 v32, 0xc1f00000, v32
	v_exp_f32_e32 v161, v161
	v_mul_f32_e32 v163, 0xbfb8aa3b, v163
	v_max_f32_e32 v165, 0xc1f00000, v165
	v_mul_f32_e32 v32, 0xbfb8aa3b, v32
	v_exp_f32_e32 v163, v163
	v_mul_f32_e32 v165, 0xbfb8aa3b, v165
	v_exp_f32_e32 v32, v32
	v_exp_f32_e32 v165, v165
	v_max_f32_e32 v177, 0xc1f00000, v177
	v_max_f32_e32 v176, 0xc1f00000, v176
	v_mul_f32_e32 v177, 0xbfb8aa3b, v177
	v_mul_f32_e32 v176, 0xbfb8aa3b, v176
	v_add_f32_e32 v35, 1.0, v35
	v_exp_f32_e32 v185, v177
	v_exp_f32_e32 v186, v176
	v_rcp_f32_e32 v176, v35
	v_add_f32_e32 v35, 1.0, v161
	v_rcp_f32_e32 v177, v35
	v_add_f32_e32 v35, 1.0, v163
	v_add_f32_e32 v32, 1.0, v32
	v_rcp_f32_e32 v178, v35
	v_add_f32_e32 v35, 1.0, v165
	v_rcp_f32_e32 v32, v32
	v_rcp_f32_e32 v179, v35
	v_add_f32_e32 v35, 1.0, v184
	v_rcp_f32_e32 v184, v35
	v_add_f32_e32 v35, 1.0, v185
	v_rcp_f32_e32 v185, v35
	v_add_f32_e32 v35, 1.0, v186
	v_mov_b32_e32 v186, v65
	v_mov_b32_e32 v187, v66
	v_pk_mul_f32 v[176:177], v[186:187], v[176:177]
	v_pk_mov_b32 v[186:187], v[66:67], v[60:61] op_sel:[1,0]
	v_fma_mixlo_f16 v32, v64, v32, 0
	v_cvt_pk_f16_f32 v161, v176, v177
	v_pk_mul_f32 v[178:179], v[186:187], v[178:179]
	v_rcp_f32_e32 v35, v35
	v_pack_b32_f16 v176, v32, v161
	v_cvt_pk_f16_f32 v32, v178, v179
	v_mov_b32_e32 v178, v61
	v_mov_b32_e32 v179, v62
	v_pk_mul_f32 v[178:179], v[178:179], v[184:185]
	v_alignbit_b32 v177, v32, v161, 16
	v_cvt_pk_f16_f32 v161, v178, v179
	v_lshrrev_b32_e32 v179, 16, v161
	v_lshl_add_u64 v[168:169], s[14:15], 0, v[168:169]
	v_alignbit_b32 v178, v161, v32, 16
	v_fma_mixhi_f16 v179, v63, v35, 0
	v_lshl_add_u64 v[168:169], v[168:169], 0, v[166:167]
	global_store_dwordx4 v[168:169], v[176:179], off
	v_cvt_f32_f16_sdwa v35, v180 dst_sel:DWORD dst_unused:UNUSED_PAD src0_sel:WORD_1
	v_cvt_f32_f16_e32 v161, v181
	v_cvt_f32_f16_sdwa v176, v182 dst_sel:DWORD dst_unused:UNUSED_PAD src0_sel:WORD_1
	v_cvt_f32_f16_sdwa v163, v181 dst_sel:DWORD dst_unused:UNUSED_PAD src0_sel:WORD_1
	v_cvt_f32_f16_e32 v32, v180
	v_cvt_f32_f16_e32 v165, v182
	v_max_f32_e32 v176, 0xc1f00000, v176
	v_max_f32_e32 v35, 0xc1f00000, v35
	v_mul_f32_e32 v176, 0xbfb8aa3b, v176
	v_mul_f32_e32 v35, 0xbfb8aa3b, v35
	v_max_f32_e32 v161, 0xc1f00000, v161
	v_cvt_f32_f16_e32 v177, v183
	v_exp_f32_e32 v180, v176
	v_cvt_f32_f16_sdwa v176, v183 dst_sel:DWORD dst_unused:UNUSED_PAD src0_sel:WORD_1
	v_exp_f32_e32 v35, v35
	v_mul_f32_e32 v161, 0xbfb8aa3b, v161
	v_max_f32_e32 v163, 0xc1f00000, v163
	v_max_f32_e32 v32, 0xc1f00000, v32
	v_exp_f32_e32 v161, v161
	v_mul_f32_e32 v163, 0xbfb8aa3b, v163
	v_max_f32_e32 v165, 0xc1f00000, v165
	v_mul_f32_e32 v32, 0xbfb8aa3b, v32
	v_exp_f32_e32 v163, v163
	v_mul_f32_e32 v165, 0xbfb8aa3b, v165
	v_exp_f32_e32 v32, v32
	v_exp_f32_e32 v165, v165
	v_max_f32_e32 v177, 0xc1f00000, v177
	v_max_f32_e32 v176, 0xc1f00000, v176
	v_mul_f32_e32 v177, 0xbfb8aa3b, v177
	v_mul_f32_e32 v176, 0xbfb8aa3b, v176
	v_add_f32_e32 v35, 1.0, v35
	v_exp_f32_e32 v181, v177
	v_exp_f32_e32 v182, v176
	v_rcp_f32_e32 v176, v35
	v_add_f32_e32 v35, 1.0, v161
	v_rcp_f32_e32 v177, v35
	v_add_f32_e32 v35, 1.0, v163
	v_add_f32_e32 v32, 1.0, v32
	v_rcp_f32_e32 v178, v35
	v_add_f32_e32 v35, 1.0, v165
	v_rcp_f32_e32 v32, v32
	v_rcp_f32_e32 v179, v35
	v_add_f32_e32 v35, 1.0, v180
	v_rcp_f32_e32 v180, v35
	v_add_f32_e32 v35, 1.0, v181
	v_rcp_f32_e32 v181, v35
	v_add_f32_e32 v35, 1.0, v182
	v_mov_b32_e32 v182, v29
	v_mov_b32_e32 v183, v30
	v_pk_mul_f32 v[176:177], v[182:183], v[176:177]
	v_pk_mov_b32 v[182:183], v[30:31], v[24:25] op_sel:[1,0]
	v_fma_mixlo_f16 v32, v28, v32, 0
	v_cvt_pk_f16_f32 v161, v176, v177
	v_pk_mul_f32 v[178:179], v[182:183], v[178:179]
	v_rcp_f32_e32 v35, v35
	v_pack_b32_f16 v176, v32, v161
	v_cvt_pk_f16_f32 v32, v178, v179
	v_mov_b32_e32 v178, v25
	v_mov_b32_e32 v179, v26
	v_pk_mul_f32 v[178:179], v[178:179], v[180:181]
	v_alignbit_b32 v177, v32, v161, 16
	v_cvt_pk_f16_f32 v161, v178, v179
	v_lshrrev_b32_e32 v179, 16, v161
	v_alignbit_b32 v178, v161, v32, 16
	v_fma_mixhi_f16 v179, v27, v35, 0
	v_cvt_f32_f16_e32 v32, v152
	v_cvt_f32_f16_sdwa v35, v152 dst_sel:DWORD dst_unused:UNUSED_PAD src0_sel:WORD_1
	v_cvt_f32_f16_e32 v152, v153
	v_cvt_f32_f16_sdwa v153, v153 dst_sel:DWORD dst_unused:UNUSED_PAD src0_sel:WORD_1
	global_store_dwordx4 v[168:169], v[176:179], off offset:256
	v_max_f32_e32 v35, 0xc1f00000, v35
	v_max_f32_e32 v152, 0xc1f00000, v152
	v_mul_f32_e32 v152, 0xbfb8aa3b, v152
	v_exp_f32_e32 v161, v152
	v_max_f32_e32 v152, 0xc1f00000, v153
	v_mul_f32_e32 v152, 0xbfb8aa3b, v152
	v_cvt_f32_f16_e32 v153, v154
	v_exp_f32_e32 v163, v152
	v_cvt_f32_f16_sdwa v152, v154 dst_sel:DWORD dst_unused:UNUSED_PAD src0_sel:WORD_1
	v_lshlrev_b64 v[168:169], 11, v[174:175]
	v_max_f32_e32 v153, 0xc1f00000, v153
	v_mul_f32_e32 v153, 0xbfb8aa3b, v153
	v_max_f32_e32 v152, 0xc1f00000, v152
	v_mul_f32_e32 v152, 0xbfb8aa3b, v152
	v_mul_f32_e32 v35, 0xbfb8aa3b, v35
	v_exp_f32_e32 v165, v153
	v_cvt_f32_f16_e32 v153, v155
	v_exp_f32_e32 v174, v152
	v_cvt_f32_f16_sdwa v152, v155 dst_sel:DWORD dst_unused:UNUSED_PAD src0_sel:WORD_1
	v_exp_f32_e32 v35, v35
	v_max_f32_e32 v32, 0xc1f00000, v32
	v_mul_f32_e32 v32, 0xbfb8aa3b, v32
	v_exp_f32_e32 v32, v32
	v_max_f32_e32 v153, 0xc1f00000, v153
	v_max_f32_e32 v152, 0xc1f00000, v152
	v_mul_f32_e32 v153, 0xbfb8aa3b, v153
	v_mul_f32_e32 v152, 0xbfb8aa3b, v152
	v_add_f32_e32 v35, 1.0, v35
	v_exp_f32_e32 v175, v153
	v_exp_f32_e32 v176, v152
	v_rcp_f32_e32 v152, v35
	v_add_f32_e32 v35, 1.0, v161
	v_rcp_f32_e32 v153, v35
	v_add_f32_e32 v35, 1.0, v163
	v_add_f32_e32 v32, 1.0, v32
	v_rcp_f32_e32 v154, v35
	v_add_f32_e32 v35, 1.0, v165
	v_rcp_f32_e32 v32, v32
	v_rcp_f32_e32 v155, v35
	v_add_f32_e32 v35, 1.0, v174
	v_rcp_f32_e32 v174, v35
	v_add_f32_e32 v35, 1.0, v175
	v_rcp_f32_e32 v175, v35
	v_add_f32_e32 v35, 1.0, v176
	v_mov_b32_e32 v176, v57
	v_mov_b32_e32 v177, v58
	v_pk_mul_f32 v[152:153], v[176:177], v[152:153]
	v_pk_mov_b32 v[176:177], v[58:59], v[52:53] op_sel:[1,0]
	v_fma_mixlo_f16 v32, v56, v32, 0
	v_cvt_pk_f16_f32 v153, v152, v153
	v_pk_mul_f32 v[154:155], v[176:177], v[154:155]
	v_rcp_f32_e32 v35, v35
	v_pack_b32_f16 v152, v32, v153
	v_cvt_pk_f16_f32 v32, v154, v155
	v_mov_b32_e32 v154, v53
	v_mov_b32_e32 v155, v54
	v_pk_mul_f32 v[154:155], v[154:155], v[174:175]
	v_alignbit_b32 v153, v32, v153, 16
	v_cvt_pk_f16_f32 v155, v154, v155
	v_alignbit_b32 v154, v155, v32, 16
	v_lshrrev_b32_e32 v155, 16, v155
	v_fma_mixhi_f16 v155, v55, v35, 0
	v_cvt_f32_f16_e32 v32, v148
	v_cvt_f32_f16_sdwa v35, v148 dst_sel:DWORD dst_unused:UNUSED_PAD src0_sel:WORD_1
	v_cvt_f32_f16_e32 v148, v149
	v_cvt_f32_f16_sdwa v149, v149 dst_sel:DWORD dst_unused:UNUSED_PAD src0_sel:WORD_1
	v_lshl_add_u64 v[168:169], s[14:15], 0, v[168:169]
	v_lshl_add_u64 v[168:169], v[168:169], 0, v[166:167]
	v_max_f32_e32 v148, 0xc1f00000, v148
	v_mul_f32_e32 v148, 0xbfb8aa3b, v148
	global_store_dwordx4 v[168:169], v[152:155], off
	v_max_f32_e32 v35, 0xc1f00000, v35
	v_mul_f32_e32 v35, 0xbfb8aa3b, v35
	v_exp_f32_e32 v152, v148
	v_max_f32_e32 v148, 0xc1f00000, v149
	v_mul_f32_e32 v148, 0xbfb8aa3b, v148
	v_cvt_f32_f16_e32 v149, v150
	v_exp_f32_e32 v153, v148
	v_cvt_f32_f16_sdwa v148, v150 dst_sel:DWORD dst_unused:UNUSED_PAD src0_sel:WORD_1
	v_exp_f32_e32 v35, v35
	v_max_f32_e32 v149, 0xc1f00000, v149
	v_mul_f32_e32 v149, 0xbfb8aa3b, v149
	v_max_f32_e32 v148, 0xc1f00000, v148
	v_mul_f32_e32 v148, 0xbfb8aa3b, v148
	v_exp_f32_e32 v154, v149
	v_cvt_f32_f16_e32 v149, v151
	v_exp_f32_e32 v155, v148
	v_cvt_f32_f16_sdwa v148, v151 dst_sel:DWORD dst_unused:UNUSED_PAD src0_sel:WORD_1
	v_max_f32_e32 v32, 0xc1f00000, v32
	v_mul_f32_e32 v32, 0xbfb8aa3b, v32
	v_exp_f32_e32 v32, v32
	v_max_f32_e32 v149, 0xc1f00000, v149
	v_max_f32_e32 v148, 0xc1f00000, v148
	v_mul_f32_e32 v149, 0xbfb8aa3b, v149
	v_mul_f32_e32 v148, 0xbfb8aa3b, v148
	v_add_f32_e32 v35, 1.0, v35
	v_exp_f32_e32 v161, v149
	v_exp_f32_e32 v163, v148
	v_rcp_f32_e32 v148, v35
	v_add_f32_e32 v35, 1.0, v152
	v_rcp_f32_e32 v149, v35
	v_add_f32_e32 v35, 1.0, v153
	v_add_f32_e32 v32, 1.0, v32
	v_rcp_f32_e32 v150, v35
	v_add_f32_e32 v35, 1.0, v154
	v_rcp_f32_e32 v32, v32
	v_rcp_f32_e32 v151, v35
	v_add_f32_e32 v35, 1.0, v155
	v_rcp_f32_e32 v152, v35
	v_add_f32_e32 v35, 1.0, v161
	v_rcp_f32_e32 v153, v35
	v_mov_b32_e32 v154, v21
	v_mov_b32_e32 v155, v22
	v_pk_mul_f32 v[148:149], v[154:155], v[148:149]
	v_pk_mov_b32 v[154:155], v[22:23], v[16:17] op_sel:[1,0]
	v_add_f32_e32 v35, 1.0, v163
	v_fma_mixlo_f16 v32, v20, v32, 0
	v_cvt_pk_f16_f32 v149, v148, v149
	v_pk_mul_f32 v[150:151], v[154:155], v[150:151]
	v_rcp_f32_e32 v35, v35
	v_pack_b32_f16 v148, v32, v149
	v_cvt_pk_f16_f32 v32, v150, v151
	v_mov_b32_e32 v150, v17
	v_mov_b32_e32 v151, v18
	v_pk_mul_f32 v[150:151], v[150:151], v[152:153]
	v_alignbit_b32 v149, v32, v149, 16
	v_cvt_pk_f16_f32 v151, v150, v151
	v_alignbit_b32 v150, v151, v32, 16
	v_lshrrev_b32_e32 v151, 16, v151
	v_fma_mixhi_f16 v151, v19, v35, 0
	v_cvt_f32_f16_e32 v32, v144
	v_cvt_f32_f16_sdwa v35, v144 dst_sel:DWORD dst_unused:UNUSED_PAD src0_sel:WORD_1
	v_cvt_f32_f16_e32 v144, v145
	v_cvt_f32_f16_sdwa v145, v145 dst_sel:DWORD dst_unused:UNUSED_PAD src0_sel:WORD_1
	global_store_dwordx4 v[168:169], v[148:151], off offset:256
	v_max_f32_e32 v35, 0xc1f00000, v35
	v_max_f32_e32 v144, 0xc1f00000, v144
	v_mul_f32_e32 v144, 0xbfb8aa3b, v144
	v_exp_f32_e32 v150, v144
	v_max_f32_e32 v144, 0xc1f00000, v145
	v_mul_f32_e32 v144, 0xbfb8aa3b, v144
	v_cvt_f32_f16_e32 v145, v146
	v_exp_f32_e32 v151, v144
	v_cvt_f32_f16_sdwa v144, v146 dst_sel:DWORD dst_unused:UNUSED_PAD src0_sel:WORD_1
	v_mul_f32_e32 v35, 0xbfb8aa3b, v35
	v_max_f32_e32 v145, 0xc1f00000, v145
	v_mul_f32_e32 v145, 0xbfb8aa3b, v145
	v_max_f32_e32 v144, 0xc1f00000, v144
	v_mul_f32_e32 v144, 0xbfb8aa3b, v144
	v_exp_f32_e32 v152, v145
	v_cvt_f32_f16_e32 v145, v147
	v_exp_f32_e32 v153, v144
	v_cvt_f32_f16_sdwa v144, v147 dst_sel:DWORD dst_unused:UNUSED_PAD src0_sel:WORD_1
	v_exp_f32_e32 v35, v35
	v_max_f32_e32 v32, 0xc1f00000, v32
	v_mul_f32_e32 v32, 0xbfb8aa3b, v32
	v_exp_f32_e32 v32, v32
	v_max_f32_e32 v145, 0xc1f00000, v145
	v_max_f32_e32 v144, 0xc1f00000, v144
	v_mul_f32_e32 v145, 0xbfb8aa3b, v145
	v_mul_f32_e32 v144, 0xbfb8aa3b, v144
	v_add_f32_e32 v35, 1.0, v35
	v_exp_f32_e32 v154, v145
	v_exp_f32_e32 v155, v144
	v_rcp_f32_e32 v144, v35
	v_add_f32_e32 v35, 1.0, v150
	v_rcp_f32_e32 v145, v35
	v_add_f32_e32 v35, 1.0, v151
	v_add_f32_e32 v32, 1.0, v32
	v_rcp_f32_e32 v146, v35
	v_add_f32_e32 v35, 1.0, v152
	v_rcp_f32_e32 v32, v32
	v_rcp_f32_e32 v147, v35
	v_add_f32_e32 v35, 1.0, v153
	v_rcp_f32_e32 v150, v35
	v_add_f32_e32 v35, 1.0, v154
	v_rcp_f32_e32 v151, v35
	v_mov_b32_e32 v152, v49
	v_mov_b32_e32 v153, v50
	v_pk_mul_f32 v[144:145], v[152:153], v[144:145]
	v_pk_mov_b32 v[152:153], v[50:51], v[44:45] op_sel:[1,0]
	v_add_f32_e32 v35, 1.0, v155
	v_fma_mixlo_f16 v32, v48, v32, 0
	v_cvt_pk_f16_f32 v145, v144, v145
	v_pk_mul_f32 v[146:147], v[152:153], v[146:147]
	v_rcp_f32_e32 v35, v35
	v_pack_b32_f16 v144, v32, v145
	v_cvt_pk_f16_f32 v32, v146, v147
	v_mov_b32_e32 v146, v45
	v_mov_b32_e32 v147, v46
	v_pk_mul_f32 v[146:147], v[146:147], v[150:151]
	v_alignbit_b32 v145, v32, v145, 16
	v_cvt_pk_f16_f32 v147, v146, v147
	v_alignbit_b32 v146, v147, v32, 16
	v_lshrrev_b32_e32 v147, 16, v147
	v_fma_mixhi_f16 v147, v47, v35, 0
	v_cvt_f32_f16_e32 v32, v140
	v_cvt_f32_f16_sdwa v35, v140 dst_sel:DWORD dst_unused:UNUSED_PAD src0_sel:WORD_1
	v_cvt_f32_f16_e32 v140, v141
	v_cvt_f32_f16_sdwa v141, v141 dst_sel:DWORD dst_unused:UNUSED_PAD src0_sel:WORD_1
	v_lshlrev_b64 v[148:149], 11, v[172:173]
	v_lshl_add_u64 v[148:149], s[14:15], 0, v[148:149]
	v_max_f32_e32 v140, 0xc1f00000, v140
	v_lshl_add_u64 v[148:149], v[148:149], 0, v[166:167]
	v_mul_f32_e32 v140, 0xbfb8aa3b, v140
	global_store_dwordx4 v[148:149], v[144:147], off
	v_max_f32_e32 v35, 0xc1f00000, v35
	v_mul_f32_e32 v35, 0xbfb8aa3b, v35
	v_exp_f32_e32 v144, v140
	v_max_f32_e32 v140, 0xc1f00000, v141
	v_mul_f32_e32 v140, 0xbfb8aa3b, v140
	v_cvt_f32_f16_e32 v141, v142
	v_exp_f32_e32 v145, v140
	v_cvt_f32_f16_sdwa v140, v142 dst_sel:DWORD dst_unused:UNUSED_PAD src0_sel:WORD_1
	v_exp_f32_e32 v35, v35
	v_max_f32_e32 v141, 0xc1f00000, v141
	v_mul_f32_e32 v141, 0xbfb8aa3b, v141
	v_max_f32_e32 v140, 0xc1f00000, v140
	v_mul_f32_e32 v140, 0xbfb8aa3b, v140
	v_exp_f32_e32 v146, v141
	v_cvt_f32_f16_e32 v141, v143
	v_exp_f32_e32 v147, v140
	v_cvt_f32_f16_sdwa v140, v143 dst_sel:DWORD dst_unused:UNUSED_PAD src0_sel:WORD_1
	v_max_f32_e32 v32, 0xc1f00000, v32
	v_mul_f32_e32 v32, 0xbfb8aa3b, v32
	v_exp_f32_e32 v32, v32
	v_max_f32_e32 v141, 0xc1f00000, v141
	v_max_f32_e32 v140, 0xc1f00000, v140
	v_mul_f32_e32 v141, 0xbfb8aa3b, v141
	v_mul_f32_e32 v140, 0xbfb8aa3b, v140
	v_add_f32_e32 v35, 1.0, v35
	v_exp_f32_e32 v150, v141
	v_exp_f32_e32 v151, v140
	v_rcp_f32_e32 v140, v35
	v_add_f32_e32 v35, 1.0, v144
	v_rcp_f32_e32 v141, v35
	v_add_f32_e32 v35, 1.0, v145
	v_add_f32_e32 v32, 1.0, v32
	v_rcp_f32_e32 v142, v35
	v_add_f32_e32 v35, 1.0, v146
	v_rcp_f32_e32 v32, v32
	v_rcp_f32_e32 v143, v35
	v_add_f32_e32 v35, 1.0, v147
	v_rcp_f32_e32 v144, v35
	v_add_f32_e32 v35, 1.0, v150
	v_rcp_f32_e32 v145, v35
	v_mov_b32_e32 v146, v13
	v_mov_b32_e32 v147, v14
	v_pk_mul_f32 v[140:141], v[146:147], v[140:141]
	v_pk_mov_b32 v[146:147], v[14:15], v[8:9] op_sel:[1,0]
	v_add_f32_e32 v35, 1.0, v151
	v_fma_mixlo_f16 v32, v12, v32, 0
	v_cvt_pk_f16_f32 v141, v140, v141
	v_pk_mul_f32 v[142:143], v[146:147], v[142:143]
	v_rcp_f32_e32 v35, v35
	v_pack_b32_f16 v140, v32, v141
	v_cvt_pk_f16_f32 v32, v142, v143
	v_mov_b32_e32 v142, v9
	v_mov_b32_e32 v143, v10
	v_pk_mul_f32 v[142:143], v[142:143], v[144:145]
	v_alignbit_b32 v141, v32, v141, 16
	v_cvt_pk_f16_f32 v143, v142, v143
	v_alignbit_b32 v142, v143, v32, 16
	v_lshrrev_b32_e32 v143, 16, v143
	v_fma_mixhi_f16 v143, v11, v35, 0
	v_cvt_f32_f16_e32 v32, v136
	v_cvt_f32_f16_sdwa v35, v136 dst_sel:DWORD dst_unused:UNUSED_PAD src0_sel:WORD_1
	v_cvt_f32_f16_e32 v136, v137
	v_cvt_f32_f16_sdwa v137, v137 dst_sel:DWORD dst_unused:UNUSED_PAD src0_sel:WORD_1
	global_store_dwordx4 v[148:149], v[140:143], off offset:256
	v_max_f32_e32 v35, 0xc1f00000, v35
	v_max_f32_e32 v136, 0xc1f00000, v136
	v_mul_f32_e32 v136, 0xbfb8aa3b, v136
	v_exp_f32_e32 v142, v136
	v_max_f32_e32 v136, 0xc1f00000, v137
	v_mul_f32_e32 v136, 0xbfb8aa3b, v136
	v_cvt_f32_f16_e32 v137, v138
	v_exp_f32_e32 v143, v136
	v_cvt_f32_f16_sdwa v136, v138 dst_sel:DWORD dst_unused:UNUSED_PAD src0_sel:WORD_1
	v_mul_f32_e32 v35, 0xbfb8aa3b, v35
	v_max_f32_e32 v137, 0xc1f00000, v137
	v_mul_f32_e32 v137, 0xbfb8aa3b, v137
	v_max_f32_e32 v136, 0xc1f00000, v136
	v_mul_f32_e32 v136, 0xbfb8aa3b, v136
	v_exp_f32_e32 v144, v137
	v_cvt_f32_f16_e32 v137, v139
	v_exp_f32_e32 v145, v136
	v_cvt_f32_f16_sdwa v136, v139 dst_sel:DWORD dst_unused:UNUSED_PAD src0_sel:WORD_1
	v_exp_f32_e32 v35, v35
	v_max_f32_e32 v32, 0xc1f00000, v32
	v_mul_f32_e32 v32, 0xbfb8aa3b, v32
	v_exp_f32_e32 v32, v32
	v_max_f32_e32 v137, 0xc1f00000, v137
	v_max_f32_e32 v136, 0xc1f00000, v136
	v_mul_f32_e32 v137, 0xbfb8aa3b, v137
	v_mul_f32_e32 v136, 0xbfb8aa3b, v136
	v_add_f32_e32 v35, 1.0, v35
	v_exp_f32_e32 v146, v137
	v_exp_f32_e32 v147, v136
	v_rcp_f32_e32 v136, v35
	v_add_f32_e32 v35, 1.0, v142
	v_rcp_f32_e32 v137, v35
	v_add_f32_e32 v35, 1.0, v143
	v_add_f32_e32 v32, 1.0, v32
	v_rcp_f32_e32 v138, v35
	v_add_f32_e32 v35, 1.0, v144
	v_rcp_f32_e32 v32, v32
	v_rcp_f32_e32 v139, v35
	v_add_f32_e32 v35, 1.0, v145
	v_rcp_f32_e32 v142, v35
	v_add_f32_e32 v35, 1.0, v146
	v_rcp_f32_e32 v143, v35
	v_mov_b32_e32 v144, v41
	v_mov_b32_e32 v145, v42
	v_pk_mul_f32 v[136:137], v[144:145], v[136:137]
	v_pk_mov_b32 v[144:145], v[42:43], v[36:37] op_sel:[1,0]
	v_add_f32_e32 v35, 1.0, v147
	v_fma_mixlo_f16 v32, v40, v32, 0
	v_cvt_pk_f16_f32 v137, v136, v137
	v_pk_mul_f32 v[138:139], v[144:145], v[138:139]
	v_rcp_f32_e32 v35, v35
	v_pack_b32_f16 v136, v32, v137
	v_cvt_pk_f16_f32 v32, v138, v139
	v_mov_b32_e32 v138, v37
	v_mov_b32_e32 v139, v38
	v_pk_mul_f32 v[138:139], v[138:139], v[142:143]
	v_alignbit_b32 v137, v32, v137, 16
	v_cvt_pk_f16_f32 v139, v138, v139
	v_alignbit_b32 v138, v139, v32, 16
	v_lshrrev_b32_e32 v139, 16, v139
	v_fma_mixhi_f16 v139, v39, v35, 0
	v_cvt_f32_f16_e32 v32, v132
	v_cvt_f32_f16_sdwa v35, v132 dst_sel:DWORD dst_unused:UNUSED_PAD src0_sel:WORD_1
	v_cvt_f32_f16_e32 v132, v133
	v_cvt_f32_f16_sdwa v133, v133 dst_sel:DWORD dst_unused:UNUSED_PAD src0_sel:WORD_1
	v_lshlrev_b64 v[140:141], 11, v[170:171]
	v_lshl_add_u64 v[140:141], s[14:15], 0, v[140:141]
	v_max_f32_e32 v132, 0xc1f00000, v132
	v_lshl_add_u64 v[140:141], v[140:141], 0, v[166:167]
	v_mul_f32_e32 v132, 0xbfb8aa3b, v132
	global_store_dwordx4 v[140:141], v[136:139], off
	v_max_f32_e32 v35, 0xc1f00000, v35
	v_mul_f32_e32 v35, 0xbfb8aa3b, v35
	v_exp_f32_e32 v136, v132
	v_max_f32_e32 v132, 0xc1f00000, v133
	v_mul_f32_e32 v132, 0xbfb8aa3b, v132
	v_cvt_f32_f16_e32 v133, v134
	v_exp_f32_e32 v137, v132
	v_cvt_f32_f16_sdwa v132, v134 dst_sel:DWORD dst_unused:UNUSED_PAD src0_sel:WORD_1
	v_exp_f32_e32 v35, v35
	v_max_f32_e32 v133, 0xc1f00000, v133
	v_mul_f32_e32 v133, 0xbfb8aa3b, v133
	v_max_f32_e32 v132, 0xc1f00000, v132
	v_mul_f32_e32 v132, 0xbfb8aa3b, v132
	v_exp_f32_e32 v138, v133
	v_cvt_f32_f16_e32 v133, v135
	v_exp_f32_e32 v139, v132
	v_cvt_f32_f16_sdwa v132, v135 dst_sel:DWORD dst_unused:UNUSED_PAD src0_sel:WORD_1
	v_max_f32_e32 v32, 0xc1f00000, v32
	v_mul_f32_e32 v32, 0xbfb8aa3b, v32
	v_exp_f32_e32 v32, v32
	v_max_f32_e32 v133, 0xc1f00000, v133
	v_max_f32_e32 v132, 0xc1f00000, v132
	v_mul_f32_e32 v133, 0xbfb8aa3b, v133
	v_mul_f32_e32 v132, 0xbfb8aa3b, v132
	v_add_f32_e32 v35, 1.0, v35
	v_exp_f32_e32 v142, v133
	v_exp_f32_e32 v143, v132
	v_rcp_f32_e32 v132, v35
	v_add_f32_e32 v35, 1.0, v136
	v_rcp_f32_e32 v133, v35
	v_add_f32_e32 v35, 1.0, v137
	v_add_f32_e32 v32, 1.0, v32
	v_rcp_f32_e32 v134, v35
	v_add_f32_e32 v35, 1.0, v138
	v_rcp_f32_e32 v32, v32
	v_rcp_f32_e32 v135, v35
	v_add_f32_e32 v35, 1.0, v139
	v_rcp_f32_e32 v136, v35
	v_add_f32_e32 v35, 1.0, v142
	v_rcp_f32_e32 v137, v35
	v_mov_b32_e32 v138, v5
	v_mov_b32_e32 v139, v6
	v_pk_mul_f32 v[132:133], v[138:139], v[132:133]
	v_pk_mov_b32 v[138:139], v[6:7], v[0:1] op_sel:[1,0]
	v_add_f32_e32 v35, 1.0, v143
	v_fma_mixlo_f16 v32, v4, v32, 0
	v_cvt_pk_f16_f32 v133, v132, v133
	v_pk_mul_f32 v[134:135], v[138:139], v[134:135]
	v_rcp_f32_e32 v35, v35
	v_pack_b32_f16 v132, v32, v133
	v_cvt_pk_f16_f32 v32, v134, v135
	v_mov_b32_e32 v134, v1
	v_mov_b32_e32 v135, v2
	v_pk_mul_f32 v[134:135], v[134:135], v[136:137]
	v_alignbit_b32 v133, v32, v133, 16
	v_cvt_pk_f16_f32 v135, v134, v135
	v_alignbit_b32 v134, v135, v32, 16
	v_lshrrev_b32_e32 v135, 16, v135
	v_fma_mixhi_f16 v135, v3, v35, 0
	global_store_dwordx4 v[140:141], v[132:135], off offset:256
	s_cbranch_execnz .LBB0_944

.LBB0_958:
	s_add_u32 s12, s10, 0x100
	s_addc_u32 s13, s11, 0
	s_add_i32 s38, 0, 0x10000
	v_add_u32_e32 v142, s38, v196
	ds_read_b128 v[122:125], v142
	ds_read_b128 v[138:141], v142 offset:2048
	ds_read_b128 v[130:133], v142 offset:1024
	ds_read_b128 v[142:145], v142 offset:3072
	s_cmp_eq_u32 s37, 12
	s_cselect_b32 s17, s7, s13
	s_cselect_b32 s16, s6, s12
	s_cselect_b32 s15, s9, s36
	s_cselect_b32 s14, s8, s35
	v_lshl_add_u64 v[230:231], s[10:11], 0, v[188:189]
	s_add_i32 m0, s21, 0xc000
	ds_read_b128 v[146:149], v198
	ds_read_b128 v[192:195], v198 offset:2048
	ds_read_b128 v[204:207], v198 offset:4096
	ds_read_b128 v[212:215], v198 offset:6144
	ds_read_b128 v[150:153], v198 offset:1024
	ds_read_b128 v[200:203], v198 offset:3072
	ds_read_b128 v[208:211], v198 offset:5120
	ds_read_b128 v[216:219], v198 offset:7168
	global_load_lds_dwordx4 v[230:231], off
	v_lshl_add_u64 v[230:231], s[10:11], 0, v[190:191]
	s_add_i32 m0, s21, 0xe000
	s_nop 0
	global_load_lds_dwordx4 v[230:231], off
	s_waitcnt lgkmcnt(8)
	s_barrier
	s_waitcnt lgkmcnt(7)
	s_setprio 1
	v_mfma_f32_16x16x32_f16 v[134:137], v[122:125], v[146:149], v[134:137]
	v_mfma_f32_16x16x32_f16 v[126:129], v[138:141], v[146:149], v[126:129]
	s_waitcnt lgkmcnt(6)
	v_mfma_f32_16x16x32_f16 v[110:113], v[122:125], v[192:195], v[110:113]
	v_mfma_f32_16x16x32_f16 v[106:109], v[138:141], v[192:195], v[106:109]
	s_waitcnt lgkmcnt(5)
	v_mfma_f32_16x16x32_f16 v[94:97], v[122:125], v[204:207], v[94:97]
	v_mfma_f32_16x16x32_f16 v[90:93], v[138:141], v[204:207], v[90:93]
	s_waitcnt lgkmcnt(4)
	v_mfma_f32_16x16x32_f16 v[78:81], v[122:125], v[212:215], v[78:81]
	v_mfma_f32_16x16x32_f16 v[74:77], v[138:141], v[212:215], v[74:77]
	s_waitcnt lgkmcnt(3)
	v_mfma_f32_16x16x32_f16 v[134:137], v[130:133], v[150:153], v[134:137]
	v_mfma_f32_16x16x32_f16 v[126:129], v[142:145], v[150:153], v[126:129]
	s_waitcnt lgkmcnt(2)
	v_mfma_f32_16x16x32_f16 v[110:113], v[130:133], v[200:203], v[110:113]
	v_mfma_f32_16x16x32_f16 v[106:109], v[142:145], v[200:203], v[106:109]
	s_waitcnt lgkmcnt(1)
	v_mfma_f32_16x16x32_f16 v[94:97], v[130:133], v[208:211], v[94:97]
	v_mfma_f32_16x16x32_f16 v[90:93], v[142:145], v[208:211], v[90:93]
	s_waitcnt lgkmcnt(0)
	v_mfma_f32_16x16x32_f16 v[78:81], v[130:133], v[216:219], v[78:81]
	v_mfma_f32_16x16x32_f16 v[74:77], v[142:145], v[216:219], v[74:77]
	s_setprio 0
	s_barrier
	s_add_i32 s39, 0, 0x14000
	s_add_i32 s10, s38, s20
	v_add_u32_e32 v199, s39, v196
	v_lshl_add_u64 v[246:247], s[14:15], 0, v[32:33]
	s_mov_b32 m0, s10
	ds_read_b128 v[230:233], v199
	ds_read_b128 v[238:241], v199 offset:2048
	ds_read_b128 v[234:237], v199 offset:1024
	ds_read_b128 v[242:245], v199 offset:3072
	global_load_lds_dwordx4 v[246:247], off
	v_lshl_add_u64 v[248:249], s[14:15], 0, v[154:155]
	s_add_i32 m0, s10, 0x2000
	s_nop 0
	global_load_lds_dwordx4 v[248:249], off
	s_barrier
	s_waitcnt lgkmcnt(2)
	s_setprio 1
	v_mfma_f32_16x16x32_f16 v[118:121], v[230:233], v[146:149], v[118:121]
	v_mfma_f32_16x16x32_f16 v[114:117], v[238:241], v[146:149], v[114:117]
	v_mfma_f32_16x16x32_f16 v[102:105], v[230:233], v[192:195], v[102:105]
	v_mfma_f32_16x16x32_f16 v[98:101], v[238:241], v[192:195], v[98:101]
	v_mfma_f32_16x16x32_f16 v[86:89], v[230:233], v[204:207], v[86:89]
	v_mfma_f32_16x16x32_f16 v[82:85], v[238:241], v[204:207], v[82:85]
	v_mfma_f32_16x16x32_f16 v[70:73], v[230:233], v[212:215], v[70:73]
	v_mfma_f32_16x16x32_f16 v[66:69], v[238:241], v[212:215], v[66:69]
	s_waitcnt lgkmcnt(0)
	v_mfma_f32_16x16x32_f16 v[118:121], v[234:237], v[150:153], v[118:121]
	v_mfma_f32_16x16x32_f16 v[114:117], v[242:245], v[150:153], v[114:117]
	v_mfma_f32_16x16x32_f16 v[102:105], v[234:237], v[200:203], v[102:105]
	v_mfma_f32_16x16x32_f16 v[98:101], v[242:245], v[200:203], v[98:101]
	v_mfma_f32_16x16x32_f16 v[86:89], v[234:237], v[208:211], v[86:89]
	v_mfma_f32_16x16x32_f16 v[82:85], v[242:245], v[208:211], v[82:85]
	v_mfma_f32_16x16x32_f16 v[70:73], v[234:237], v[216:219], v[70:73]
	v_mfma_f32_16x16x32_f16 v[66:69], v[242:245], v[216:219], v[66:69]
	s_setprio 0
	s_mov_b32 m0, s21
	v_lshl_add_u64 v[228:229], s[16:17], 0, v[32:33]
	s_barrier
	ds_read_b128 v[146:149], v198 offset:16384
	ds_read_b128 v[192:195], v198 offset:18432
	ds_read_b128 v[204:207], v198 offset:20480
	ds_read_b128 v[212:215], v198 offset:22528
	ds_read_b128 v[150:153], v198 offset:17408
	ds_read_b128 v[200:203], v198 offset:19456
	ds_read_b128 v[208:211], v198 offset:21504
	ds_read_b128 v[216:219], v198 offset:23552
	global_load_lds_dwordx4 v[228:229], off
	v_lshl_add_u64 v[222:223], s[16:17], 0, v[154:155]
	s_mov_b32 m0, s22
	s_nop 0
	global_load_lds_dwordx4 v[222:223], off
	s_barrier
	s_waitcnt lgkmcnt(4)
	s_setprio 1
	v_mfma_f32_16x16x32_f16 v[62:65], v[122:125], v[146:149], v[62:65]
	v_mfma_f32_16x16x32_f16 v[58:61], v[138:141], v[146:149], v[58:61]
	v_mfma_f32_16x16x32_f16 v[46:49], v[122:125], v[192:195], v[46:49]
	v_mfma_f32_16x16x32_f16 v[42:45], v[138:141], v[192:195], v[42:45]
	v_mfma_f32_16x16x32_f16 v[28:31], v[122:125], v[204:207], v[28:31]
	v_mfma_f32_16x16x32_f16 v[24:27], v[138:141], v[204:207], v[24:27]
	v_mfma_f32_16x16x32_f16 v[12:15], v[122:125], v[212:215], v[12:15]
	v_mfma_f32_16x16x32_f16 v[8:11], v[138:141], v[212:215], v[8:11]
	s_waitcnt lgkmcnt(0)
	v_mfma_f32_16x16x32_f16 v[62:65], v[130:133], v[150:153], v[62:65]
	v_mfma_f32_16x16x32_f16 v[58:61], v[142:145], v[150:153], v[58:61]
	v_mfma_f32_16x16x32_f16 v[46:49], v[130:133], v[200:203], v[46:49]
	v_mfma_f32_16x16x32_f16 v[42:45], v[142:145], v[200:203], v[42:45]
	v_mfma_f32_16x16x32_f16 v[28:31], v[130:133], v[208:211], v[28:31]
	v_mfma_f32_16x16x32_f16 v[24:27], v[142:145], v[208:211], v[24:27]
	v_mfma_f32_16x16x32_f16 v[12:15], v[130:133], v[216:219], v[12:15]
	v_mfma_f32_16x16x32_f16 v[8:11], v[142:145], v[216:219], v[8:11]
	s_setprio 0
	s_barrier
	s_add_u32 s10, s14, 0x40000
	s_addc_u32 s11, s15, 0
	s_add_i32 s38, s39, s20
	v_lshl_add_u64 v[122:123], s[10:11], 0, v[32:33]
	s_mov_b32 m0, s38
	s_nop 0
	global_load_lds_dwordx4 v[122:123], off
	v_lshl_add_u64 v[122:123], s[10:11], 0, v[154:155]
	s_add_i32 m0, s38, 0x2000
	s_nop 0
	global_load_lds_dwordx4 v[122:123], off
	s_waitcnt vmcnt(6)
	s_barrier
	s_setprio 1
	v_mfma_f32_16x16x32_f16 v[54:57], v[230:233], v[146:149], v[54:57]
	v_mfma_f32_16x16x32_f16 v[50:53], v[238:241], v[146:149], v[50:53]
	v_mfma_f32_16x16x32_f16 v[38:41], v[230:233], v[192:195], v[38:41]
	v_mfma_f32_16x16x32_f16 v[34:37], v[238:241], v[192:195], v[34:37]
	v_mfma_f32_16x16x32_f16 v[20:23], v[230:233], v[204:207], v[20:23]
	v_mfma_f32_16x16x32_f16 v[16:19], v[238:241], v[204:207], v[16:19]
	v_mfma_f32_16x16x32_f16 v[4:7], v[230:233], v[212:215], v[4:7]
	v_mfma_f32_16x16x32_f16 v[0:3], v[238:241], v[212:215], v[0:3]
	v_mfma_f32_16x16x32_f16 v[54:57], v[234:237], v[150:153], v[54:57]
	v_mfma_f32_16x16x32_f16 v[50:53], v[242:245], v[150:153], v[50:53]
	v_mfma_f32_16x16x32_f16 v[38:41], v[234:237], v[200:203], v[38:41]
	v_mfma_f32_16x16x32_f16 v[34:37], v[242:245], v[200:203], v[34:37]
	v_mfma_f32_16x16x32_f16 v[20:23], v[234:237], v[208:211], v[20:23]
	v_mfma_f32_16x16x32_f16 v[16:19], v[242:245], v[208:211], v[16:19]
	v_mfma_f32_16x16x32_f16 v[4:7], v[234:237], v[216:219], v[4:7]
	v_mfma_f32_16x16x32_f16 v[0:3], v[242:245], v[216:219], v[0:3]
	s_setprio 0
	s_add_i32 s38, 0, 0x18000
	v_add_u32_e32 v142, s38, v196
	s_barrier
	ds_read_b128 v[122:125], v142
	ds_read_b128 v[138:141], v142 offset:2048
	ds_read_b128 v[130:133], v142 offset:1024
	ds_read_b128 v[142:145], v142 offset:3072
	s_add_u32 s10, s16, 0x40000
	s_addc_u32 s11, s17, 0
	s_mov_b32 m0, s23
	v_lshl_add_u64 v[230:231], s[10:11], 0, v[32:33]
	ds_read_b128 v[146:149], v198 offset:32768
	ds_read_b128 v[192:195], v198 offset:34816
	ds_read_b128 v[204:207], v198 offset:36864
	ds_read_b128 v[212:215], v198 offset:38912
	ds_read_b128 v[150:153], v198 offset:33792
	ds_read_b128 v[200:203], v198 offset:35840
	ds_read_b128 v[208:211], v198 offset:37888
	ds_read_b128 v[216:219], v198 offset:39936
	global_load_lds_dwordx4 v[230:231], off
	v_lshl_add_u64 v[230:231], s[10:11], 0, v[154:155]
	s_mov_b32 m0, s24
	s_nop 0
	global_load_lds_dwordx4 v[230:231], off
	s_waitcnt lgkmcnt(8)
	s_barrier
	s_waitcnt lgkmcnt(7)
	s_setprio 1
	v_mfma_f32_16x16x32_f16 v[134:137], v[122:125], v[146:149], v[134:137]
	v_mfma_f32_16x16x32_f16 v[126:129], v[138:141], v[146:149], v[126:129]
	s_waitcnt lgkmcnt(6)
	v_mfma_f32_16x16x32_f16 v[110:113], v[122:125], v[192:195], v[110:113]
	v_mfma_f32_16x16x32_f16 v[106:109], v[138:141], v[192:195], v[106:109]
	s_waitcnt lgkmcnt(5)
	v_mfma_f32_16x16x32_f16 v[94:97], v[122:125], v[204:207], v[94:97]
	v_mfma_f32_16x16x32_f16 v[90:93], v[138:141], v[204:207], v[90:93]
	s_waitcnt lgkmcnt(4)
	v_mfma_f32_16x16x32_f16 v[78:81], v[122:125], v[212:215], v[78:81]
	v_mfma_f32_16x16x32_f16 v[74:77], v[138:141], v[212:215], v[74:77]
	s_waitcnt lgkmcnt(3)
	v_mfma_f32_16x16x32_f16 v[134:137], v[130:133], v[150:153], v[134:137]
	v_mfma_f32_16x16x32_f16 v[126:129], v[142:145], v[150:153], v[126:129]
	s_waitcnt lgkmcnt(2)
	v_mfma_f32_16x16x32_f16 v[110:113], v[130:133], v[200:203], v[110:113]
	v_mfma_f32_16x16x32_f16 v[106:109], v[142:145], v[200:203], v[106:109]
	s_waitcnt lgkmcnt(1)
	v_mfma_f32_16x16x32_f16 v[94:97], v[130:133], v[208:211], v[94:97]
	v_mfma_f32_16x16x32_f16 v[90:93], v[142:145], v[208:211], v[90:93]
	s_waitcnt lgkmcnt(0)
	v_mfma_f32_16x16x32_f16 v[78:81], v[130:133], v[216:219], v[78:81]
	v_mfma_f32_16x16x32_f16 v[74:77], v[142:145], v[216:219], v[74:77]
	s_setprio 0
	s_barrier
	s_add_i32 s16, 0, 0x1c000
	s_add_i32 s10, s38, s20
	v_add_u32_e32 v199, s16, v196
	v_lshl_add_u64 v[246:247], v[246:247], 0, s[84:85]
	s_mov_b32 m0, s10
	ds_read_b128 v[230:233], v199
	ds_read_b128 v[238:241], v199 offset:2048
	ds_read_b128 v[234:237], v199 offset:1024
	ds_read_b128 v[242:245], v199 offset:3072
	global_load_lds_dwordx4 v[246:247], off
	v_lshl_add_u64 v[246:247], v[248:249], 0, s[84:85]
	s_add_i32 m0, s10, 0x2000
	s_nop 0
	global_load_lds_dwordx4 v[246:247], off
	s_barrier
	s_waitcnt lgkmcnt(2)
	s_setprio 1
	v_mfma_f32_16x16x32_f16 v[118:121], v[230:233], v[146:149], v[118:121]
	v_mfma_f32_16x16x32_f16 v[114:117], v[238:241], v[146:149], v[114:117]
	v_mfma_f32_16x16x32_f16 v[102:105], v[230:233], v[192:195], v[102:105]
	v_mfma_f32_16x16x32_f16 v[98:101], v[238:241], v[192:195], v[98:101]
	v_mfma_f32_16x16x32_f16 v[86:89], v[230:233], v[204:207], v[86:89]
	v_mfma_f32_16x16x32_f16 v[82:85], v[238:241], v[204:207], v[82:85]
	v_mfma_f32_16x16x32_f16 v[70:73], v[230:233], v[212:215], v[70:73]
	v_mfma_f32_16x16x32_f16 v[66:69], v[238:241], v[212:215], v[66:69]
	s_waitcnt lgkmcnt(0)
	v_mfma_f32_16x16x32_f16 v[118:121], v[234:237], v[150:153], v[118:121]
	v_mfma_f32_16x16x32_f16 v[114:117], v[242:245], v[150:153], v[114:117]
	v_mfma_f32_16x16x32_f16 v[102:105], v[234:237], v[200:203], v[102:105]
	v_mfma_f32_16x16x32_f16 v[98:101], v[242:245], v[200:203], v[98:101]
	v_mfma_f32_16x16x32_f16 v[86:89], v[234:237], v[208:211], v[86:89]
	v_mfma_f32_16x16x32_f16 v[82:85], v[242:245], v[208:211], v[82:85]
	v_mfma_f32_16x16x32_f16 v[70:73], v[234:237], v[216:219], v[70:73]
	v_mfma_f32_16x16x32_f16 v[66:69], v[242:245], v[216:219], v[66:69]
	s_setprio 0
	s_mov_b32 m0, s25
	v_lshl_add_u64 v[228:229], v[228:229], 0, s[84:85]
	s_barrier
	ds_read_b128 v[146:149], v198 offset:49152
	ds_read_b128 v[192:195], v198 offset:51200
	ds_read_b128 v[204:207], v198 offset:53248
	ds_read_b128 v[212:215], v198 offset:55296
	ds_read_b128 v[150:153], v198 offset:50176
	ds_read_b128 v[200:203], v198 offset:52224
	ds_read_b128 v[208:211], v198 offset:54272
	ds_read_b128 v[216:219], v198 offset:56320
	global_load_lds_dwordx4 v[228:229], off
	v_lshl_add_u64 v[222:223], v[222:223], 0, s[84:85]
	s_mov_b32 m0, s27
	s_nop 0
	global_load_lds_dwordx4 v[222:223], off
	s_barrier
	s_waitcnt lgkmcnt(4)
	s_setprio 1
	v_mfma_f32_16x16x32_f16 v[62:65], v[122:125], v[146:149], v[62:65]
	v_mfma_f32_16x16x32_f16 v[58:61], v[138:141], v[146:149], v[58:61]
	v_mfma_f32_16x16x32_f16 v[46:49], v[122:125], v[192:195], v[46:49]
	v_mfma_f32_16x16x32_f16 v[42:45], v[138:141], v[192:195], v[42:45]
	v_mfma_f32_16x16x32_f16 v[28:31], v[122:125], v[204:207], v[28:31]
	v_mfma_f32_16x16x32_f16 v[24:27], v[138:141], v[204:207], v[24:27]
	v_mfma_f32_16x16x32_f16 v[12:15], v[122:125], v[212:215], v[12:15]
	v_mfma_f32_16x16x32_f16 v[8:11], v[138:141], v[212:215], v[8:11]
	s_waitcnt lgkmcnt(0)
	v_mfma_f32_16x16x32_f16 v[62:65], v[130:133], v[150:153], v[62:65]
	v_mfma_f32_16x16x32_f16 v[58:61], v[142:145], v[150:153], v[58:61]
	v_mfma_f32_16x16x32_f16 v[46:49], v[130:133], v[200:203], v[46:49]
	v_mfma_f32_16x16x32_f16 v[42:45], v[142:145], v[200:203], v[42:45]
	v_mfma_f32_16x16x32_f16 v[28:31], v[130:133], v[208:211], v[28:31]
	v_mfma_f32_16x16x32_f16 v[24:27], v[142:145], v[208:211], v[24:27]
	v_mfma_f32_16x16x32_f16 v[12:15], v[130:133], v[216:219], v[12:15]
	v_mfma_f32_16x16x32_f16 v[8:11], v[142:145], v[216:219], v[8:11]
	s_setprio 0
	s_barrier
	s_add_u32 s10, s14, 0x40080
	s_addc_u32 s11, s15, 0
	s_add_i32 s14, s16, s20
	v_lshl_add_u64 v[122:123], s[10:11], 0, v[32:33]
	s_mov_b32 m0, s14
	s_nop 0
	global_load_lds_dwordx4 v[122:123], off
	v_lshl_add_u64 v[122:123], s[10:11], 0, v[154:155]
	s_add_i32 m0, s14, 0x2000
	s_nop 0
	global_load_lds_dwordx4 v[122:123], off
	s_waitcnt vmcnt(6)
	s_barrier
	s_setprio 1
	v_mfma_f32_16x16x32_f16 v[54:57], v[230:233], v[146:149], v[54:57]
	v_mfma_f32_16x16x32_f16 v[50:53], v[238:241], v[146:149], v[50:53]
	v_mfma_f32_16x16x32_f16 v[38:41], v[230:233], v[192:195], v[38:41]
	v_mfma_f32_16x16x32_f16 v[34:37], v[238:241], v[192:195], v[34:37]
	v_mfma_f32_16x16x32_f16 v[20:23], v[230:233], v[204:207], v[20:23]
	v_mfma_f32_16x16x32_f16 v[16:19], v[238:241], v[204:207], v[16:19]
	v_mfma_f32_16x16x32_f16 v[4:7], v[230:233], v[212:215], v[4:7]
	v_mfma_f32_16x16x32_f16 v[0:3], v[238:241], v[212:215], v[0:3]
	v_mfma_f32_16x16x32_f16 v[54:57], v[234:237], v[150:153], v[54:57]
	v_mfma_f32_16x16x32_f16 v[50:53], v[242:245], v[150:153], v[50:53]
	v_mfma_f32_16x16x32_f16 v[38:41], v[234:237], v[200:203], v[38:41]
	v_mfma_f32_16x16x32_f16 v[34:37], v[242:245], v[200:203], v[34:37]
	v_mfma_f32_16x16x32_f16 v[20:23], v[234:237], v[208:211], v[20:23]
	v_mfma_f32_16x16x32_f16 v[16:19], v[242:245], v[208:211], v[16:19]
	v_mfma_f32_16x16x32_f16 v[4:7], v[234:237], v[216:219], v[4:7]
	v_mfma_f32_16x16x32_f16 v[0:3], v[242:245], v[216:219], v[0:3]
	s_setprio 0
	s_add_i32 s37, s37, 2
	s_add_u32 s35, s35, 0x100
	s_addc_u32 s36, s36, 0
	s_cmp_gt_u32 s37, 13
	s_mov_b64 s[10:11], s[12:13]
	s_barrier
	s_cbranch_scc0 .LBB0_958
	s_cmp_eq_u32 s34, 2
	s_movk_i32 s6, 0x2800
	v_lshl_or_b32 v122, s31, 8, v197
	s_cselect_b32 s6, 0x2000, s6
	s_mov_b32 s7, 0x23a3c000
	s_cselect_b32 s8, s7, 0x23abc000
	s_add_u32 s6, s70, s6
	v_ashrrev_i32_e32 v123, 31, v122
	s_addc_u32 s7, s71, 0
	v_lshlrev_b64 v[192:193], 1, v[122:123]
	v_lshl_add_u64 v[194:195], s[6:7], 0, v[192:193]
	v_lshl_add_u64 v[122:123], v[194:195], 0, v[156:157]
	v_lshl_add_u64 v[124:125], v[194:195], 0, v[158:159]
	v_lshl_add_u64 v[130:131], v[194:195], 0, v[160:161]
	v_lshl_add_u64 v[208:209], v[194:195], 0, v[162:163]
	global_load_dwordx4 v[200:203], v[122:123], off
	global_load_dwordx4 v[204:207], v[122:123], off offset:256
	global_load_dwordx4 v[150:153], v[124:125], off
	global_load_dwordx4 v[146:149], v[124:125], off offset:256
	global_load_dwordx4 v[142:145], v[130:131], off
	global_load_dwordx4 v[138:141], v[130:131], off offset:256
	s_nop 0
	global_load_dwordx4 v[130:133], v[208:209], off
	global_load_dwordx4 v[122:125], v[208:209], off offset:256
	v_readlane_b32 s36, v252, 26
	v_readlane_b32 s42, v252, 32
	v_readlane_b32 s43, v252, 33
	s_add_u32 s6, s42, s8
	s_addc_u32 s7, s43, 0
	v_readlane_b32 s37, v252, 27
	v_readlane_b32 s38, v252, 28
	v_readlane_b32 s39, v252, 29
	v_readlane_b32 s40, v252, 30
	v_readlane_b32 s41, v252, 31
	v_lshl_add_u64 v[192:193], s[6:7], 0, v[192:193]
	s_waitcnt vmcnt(0)
	v_cvt_f32_f16_e32 v199, v200
	v_cvt_f32_f16_sdwa v200, v200 dst_sel:DWORD dst_unused:UNUSED_PAD src0_sel:WORD_1
	v_cvt_f32_f16_e32 v210, v201
	v_lshl_add_u64 v[208:209], v[192:193], 0, v[164:165]
	v_max_f32_e32 v199, 0xc1f00000, v199
	v_mul_f32_e32 v199, 0xbfb8aa3b, v199
	v_exp_f32_e32 v199, v199
	v_max_f32_e32 v200, 0xc1f00000, v200
	v_max_f32_e32 v210, 0xc1f00000, v210
	v_mul_f32_e32 v200, 0xbfb8aa3b, v200
	v_add_f32_e32 v199, 1.0, v199
	v_rcp_f32_e32 v199, v199
	v_exp_f32_e32 v200, v200
	v_mul_f32_e32 v210, 0xbfb8aa3b, v210
	v_exp_f32_e32 v211, v210
	v_fma_mixlo_f16 v199, v134, v199, 0
	v_add_f32_e32 v134, 1.0, v200
	v_rcp_f32_e32 v210, v134
	v_add_f32_e32 v134, 1.0, v211
	v_cvt_f32_f16_sdwa v200, v201 dst_sel:DWORD dst_unused:UNUSED_PAD src0_sel:WORD_1
	v_rcp_f32_e32 v211, v134
	v_mov_b32_e32 v134, v135
	v_mov_b32_e32 v135, v136
	v_cvt_f32_f16_e32 v136, v202
	v_max_f32_e32 v200, 0xc1f00000, v200
	v_mul_f32_e32 v200, 0xbfb8aa3b, v200
	v_exp_f32_e32 v200, v200
	v_max_f32_e32 v136, 0xc1f00000, v136
	v_mul_f32_e32 v136, 0xbfb8aa3b, v136
	v_exp_f32_e32 v136, v136
	v_pk_mul_f32 v[134:135], v[134:135], v[210:211]
	s_nop 0
	v_cvt_pk_f16_f32 v135, v134, v135
	v_add_f32_e32 v134, 1.0, v200
	v_rcp_f32_e32 v200, v134
	v_add_f32_e32 v134, 1.0, v136
	v_rcp_f32_e32 v201, v134
	v_pk_mov_b32 v[136:137], v[136:137], v[126:127] op_sel:[1,0]
	v_cvt_f32_f16_sdwa v126, v202 dst_sel:DWORD dst_unused:UNUSED_PAD src0_sel:WORD_1
	v_pack_b32_f16 v134, v199, v135
	v_pk_mul_f32 v[136:137], v[136:137], v[200:201]
	v_cvt_f32_f16_sdwa v200, v203 dst_sel:DWORD dst_unused:UNUSED_PAD src0_sel:WORD_1
	v_cvt_pk_f16_f32 v199, v136, v137
	v_cvt_f32_f16_e32 v136, v203
	v_max_f32_e32 v126, 0xc1f00000, v126
	v_mul_f32_e32 v126, 0xbfb8aa3b, v126
	v_exp_f32_e32 v126, v126
	v_max_f32_e32 v136, 0xc1f00000, v136
	v_mul_f32_e32 v136, 0xbfb8aa3b, v136
	v_exp_f32_e32 v137, v136
	v_add_f32_e32 v126, 1.0, v126
	v_rcp_f32_e32 v136, v126
	v_alignbit_b32 v135, v199, v135, 16
	v_add_f32_e32 v126, 1.0, v137
	v_rcp_f32_e32 v137, v126
	v_mov_b32_e32 v126, v127
	v_mov_b32_e32 v127, v128
	v_cvt_f32_f16_e32 v128, v204
	v_pk_mul_f32 v[126:127], v[126:127], v[136:137]
	s_nop 0
	v_cvt_pk_f16_f32 v126, v126, v127
	v_max_f32_e32 v127, 0xc1f00000, v200
	v_mul_f32_e32 v127, 0xbfb8aa3b, v127
	v_exp_f32_e32 v127, v127
	v_alignbit_b32 v136, v126, v199, 16
	v_lshrrev_b32_e32 v137, 16, v126
	v_add_f32_e32 v126, 1.0, v127
	v_rcp_f32_e32 v126, v126
	v_max_f32_e32 v127, 0xc1f00000, v128
	v_mul_f32_e32 v127, 0xbfb8aa3b, v127
	v_exp_f32_e32 v127, v127
	v_fma_mixhi_f16 v137, v129, v126, 0
	v_cvt_f32_f16_sdwa v126, v204 dst_sel:DWORD dst_unused:UNUSED_PAD src0_sel:WORD_1
	v_cvt_f32_f16_e32 v128, v205
	v_add_f32_e32 v127, 1.0, v127
	v_rcp_f32_e32 v127, v127
	v_max_f32_e32 v126, 0xc1f00000, v126
	v_mul_f32_e32 v126, 0xbfb8aa3b, v126
	v_max_f32_e32 v128, 0xc1f00000, v128
	v_exp_f32_e32 v126, v126
	v_mul_f32_e32 v128, 0xbfb8aa3b, v128
	v_exp_f32_e32 v128, v128
	v_fma_mixlo_f16 v129, v118, v127, 0
	v_add_f32_e32 v118, 1.0, v126
	v_rcp_f32_e32 v126, v118
	v_add_f32_e32 v118, 1.0, v128
	v_rcp_f32_e32 v127, v118
	v_cvt_f32_f16_sdwa v128, v205 dst_sel:DWORD dst_unused:UNUSED_PAD src0_sel:WORD_1
	v_mov_b32_e32 v118, v119
	v_mov_b32_e32 v119, v120
	v_cvt_f32_f16_e32 v120, v206
	v_max_f32_e32 v128, 0xc1f00000, v128
	v_mul_f32_e32 v128, 0xbfb8aa3b, v128
	v_exp_f32_e32 v128, v128
	v_max_f32_e32 v120, 0xc1f00000, v120
	v_mul_f32_e32 v120, 0xbfb8aa3b, v120
	v_exp_f32_e32 v120, v120
	v_pk_mul_f32 v[118:119], v[118:119], v[126:127]
	v_add_f32_e32 v126, 1.0, v128
	v_rcp_f32_e32 v126, v126
	v_add_f32_e32 v120, 1.0, v120
	v_rcp_f32_e32 v127, v120
	v_pk_mov_b32 v[120:121], v[120:121], v[114:115] op_sel:[1,0]
	v_cvt_f32_f16_sdwa v114, v206 dst_sel:DWORD dst_unused:UNUSED_PAD src0_sel:WORD_1
	v_cvt_pk_f16_f32 v119, v118, v119
	v_pk_mul_f32 v[120:121], v[120:121], v[126:127]
	v_cvt_f32_f16_sdwa v127, v207 dst_sel:DWORD dst_unused:UNUSED_PAD src0_sel:WORD_1
	v_cvt_pk_f16_f32 v126, v120, v121
	v_cvt_f32_f16_e32 v120, v207
	v_max_f32_e32 v114, 0xc1f00000, v114
	v_mul_f32_e32 v114, 0xbfb8aa3b, v114
	v_exp_f32_e32 v114, v114
	v_max_f32_e32 v120, 0xc1f00000, v120
	v_mul_f32_e32 v120, 0xbfb8aa3b, v120
	v_exp_f32_e32 v121, v120
	v_add_f32_e32 v114, 1.0, v114
	v_rcp_f32_e32 v120, v114
	v_pack_b32_f16 v118, v129, v119
	v_add_f32_e32 v114, 1.0, v121
	v_rcp_f32_e32 v121, v114
	v_mov_b32_e32 v114, v115
	v_max_f32_e32 v115, 0xc1f00000, v127
	v_mul_f32_e32 v115, 0xbfb8aa3b, v115
	v_exp_f32_e32 v127, v115
	v_mov_b32_e32 v115, v116
	v_pk_mul_f32 v[114:115], v[114:115], v[120:121]
	v_cvt_f32_f16_e32 v116, v150
	v_cvt_pk_f16_f32 v114, v114, v115
	v_add_f32_e32 v115, 1.0, v127
	v_rcp_f32_e32 v115, v115
	v_alignbit_b32 v120, v114, v126, 16
	v_lshrrev_b32_e32 v121, 16, v114
	v_max_f32_e32 v114, 0xc1f00000, v116
	v_alignbit_b32 v119, v126, v119, 16
	v_fma_mixhi_f16 v121, v117, v115, 0
	v_mul_f32_e32 v114, 0xbfb8aa3b, v114
	v_cvt_f32_f16_sdwa v117, v150 dst_sel:DWORD dst_unused:UNUSED_PAD src0_sel:WORD_1
	v_exp_f32_e32 v116, v114
	global_store_dwordx4 v[208:209], v[118:121], off offset:256
	v_lshl_add_u64 v[114:115], v[192:193], 0, v[166:167]
	v_max_f32_e32 v117, 0xc1f00000, v117
	v_cvt_f32_f16_e32 v118, v151
	v_add_f32_e32 v116, 1.0, v116
	v_mul_f32_e32 v117, 0xbfb8aa3b, v117
	v_rcp_f32_e32 v116, v116
	v_max_f32_e32 v118, 0xc1f00000, v118
	v_exp_f32_e32 v117, v117
	v_mul_f32_e32 v118, 0xbfb8aa3b, v118
	v_exp_f32_e32 v118, v118
	v_fma_mixlo_f16 v119, v110, v116, 0
	v_add_f32_e32 v110, 1.0, v117
	v_rcp_f32_e32 v116, v110
	v_add_f32_e32 v110, 1.0, v118
	v_rcp_f32_e32 v117, v110
	v_cvt_f32_f16_sdwa v118, v151 dst_sel:DWORD dst_unused:UNUSED_PAD src0_sel:WORD_1
	v_mov_b32_e32 v110, v111
	v_mov_b32_e32 v111, v112
	v_cvt_f32_f16_e32 v112, v152
	v_pk_mul_f32 v[110:111], v[110:111], v[116:117]
	v_max_f32_e32 v116, 0xc1f00000, v118
	v_mul_f32_e32 v116, 0xbfb8aa3b, v116
	v_max_f32_e32 v112, 0xc1f00000, v112
	v_exp_f32_e32 v116, v116
	v_mul_f32_e32 v112, 0xbfb8aa3b, v112
	v_exp_f32_e32 v112, v112
	v_cvt_pk_f16_f32 v111, v110, v111
	v_add_f32_e32 v110, 1.0, v116
	v_rcp_f32_e32 v116, v110
	v_add_f32_e32 v110, 1.0, v112
	v_rcp_f32_e32 v117, v110
	v_pk_mov_b32 v[112:113], v[112:113], v[106:107] op_sel:[1,0]
	v_cvt_f32_f16_sdwa v106, v152 dst_sel:DWORD dst_unused:UNUSED_PAD src0_sel:WORD_1
	v_pack_b32_f16 v110, v119, v111
	v_pk_mul_f32 v[112:113], v[112:113], v[116:117]
	v_cvt_f32_f16_sdwa v117, v153 dst_sel:DWORD dst_unused:UNUSED_PAD src0_sel:WORD_1
	v_cvt_pk_f16_f32 v116, v112, v113
	v_cvt_f32_f16_e32 v112, v153
	v_max_f32_e32 v106, 0xc1f00000, v106
	v_mul_f32_e32 v106, 0xbfb8aa3b, v106
	v_exp_f32_e32 v106, v106
	v_max_f32_e32 v112, 0xc1f00000, v112
	v_mul_f32_e32 v112, 0xbfb8aa3b, v112
	v_exp_f32_e32 v113, v112
	v_add_f32_e32 v106, 1.0, v106
	v_rcp_f32_e32 v112, v106
	v_alignbit_b32 v111, v116, v111, 16
	v_add_f32_e32 v106, 1.0, v113
	v_rcp_f32_e32 v113, v106
	v_mov_b32_e32 v106, v107
	v_mov_b32_e32 v107, v108
	v_cvt_f32_f16_e32 v108, v146
	v_pk_mul_f32 v[106:107], v[106:107], v[112:113]
	global_store_dwordx4 v[208:209], v[134:137], off
	v_cvt_pk_f16_f32 v106, v106, v107
	v_max_f32_e32 v107, 0xc1f00000, v117
	v_mul_f32_e32 v107, 0xbfb8aa3b, v107
	v_exp_f32_e32 v107, v107
	v_alignbit_b32 v112, v106, v116, 16
	v_lshrrev_b32_e32 v113, 16, v106
	v_add_f32_e32 v106, 1.0, v107
	v_rcp_f32_e32 v106, v106
	v_max_f32_e32 v107, 0xc1f00000, v108
	v_mul_f32_e32 v107, 0xbfb8aa3b, v107
	v_exp_f32_e32 v107, v107
	v_fma_mixhi_f16 v113, v109, v106, 0
	v_cvt_f32_f16_sdwa v106, v146 dst_sel:DWORD dst_unused:UNUSED_PAD src0_sel:WORD_1
	v_cvt_f32_f16_e32 v108, v147
	v_add_f32_e32 v107, 1.0, v107
	v_rcp_f32_e32 v107, v107
	v_max_f32_e32 v106, 0xc1f00000, v106
	v_mul_f32_e32 v106, 0xbfb8aa3b, v106
	v_max_f32_e32 v108, 0xc1f00000, v108
	v_exp_f32_e32 v106, v106
	v_mul_f32_e32 v108, 0xbfb8aa3b, v108
	v_exp_f32_e32 v108, v108
	v_fma_mixlo_f16 v109, v102, v107, 0
	v_add_f32_e32 v102, 1.0, v106
	v_rcp_f32_e32 v106, v102
	v_add_f32_e32 v102, 1.0, v108
	v_rcp_f32_e32 v107, v102
	v_cvt_f32_f16_sdwa v108, v147 dst_sel:DWORD dst_unused:UNUSED_PAD src0_sel:WORD_1
	v_mov_b32_e32 v102, v103
	v_mov_b32_e32 v103, v104
	v_cvt_f32_f16_e32 v104, v148
	v_max_f32_e32 v108, 0xc1f00000, v108
	v_mul_f32_e32 v108, 0xbfb8aa3b, v108
	v_exp_f32_e32 v108, v108
	v_max_f32_e32 v104, 0xc1f00000, v104
	v_mul_f32_e32 v104, 0xbfb8aa3b, v104
	v_exp_f32_e32 v104, v104
	v_pk_mul_f32 v[102:103], v[102:103], v[106:107]
	v_add_f32_e32 v106, 1.0, v108
	v_rcp_f32_e32 v106, v106
	v_add_f32_e32 v104, 1.0, v104
	v_rcp_f32_e32 v107, v104
	v_pk_mov_b32 v[104:105], v[104:105], v[98:99] op_sel:[1,0]
	v_cvt_f32_f16_sdwa v98, v148 dst_sel:DWORD dst_unused:UNUSED_PAD src0_sel:WORD_1
	v_cvt_pk_f16_f32 v103, v102, v103
	v_pk_mul_f32 v[104:105], v[104:105], v[106:107]
	v_cvt_f32_f16_sdwa v107, v149 dst_sel:DWORD dst_unused:UNUSED_PAD src0_sel:WORD_1
	v_cvt_pk_f16_f32 v106, v104, v105
	v_cvt_f32_f16_e32 v104, v149
	v_max_f32_e32 v98, 0xc1f00000, v98
	v_mul_f32_e32 v98, 0xbfb8aa3b, v98
	v_exp_f32_e32 v98, v98
	v_max_f32_e32 v104, 0xc1f00000, v104
	v_mul_f32_e32 v104, 0xbfb8aa3b, v104
	v_exp_f32_e32 v105, v104
	v_add_f32_e32 v98, 1.0, v98
	v_rcp_f32_e32 v104, v98
	v_pack_b32_f16 v102, v109, v103
	v_add_f32_e32 v98, 1.0, v105
	v_rcp_f32_e32 v105, v98
	v_mov_b32_e32 v98, v99
	v_max_f32_e32 v99, 0xc1f00000, v107
	v_mul_f32_e32 v99, 0xbfb8aa3b, v99
	v_exp_f32_e32 v107, v99
	v_mov_b32_e32 v99, v100
	v_pk_mul_f32 v[98:99], v[98:99], v[104:105]
	v_cvt_f32_f16_e32 v100, v142
	v_cvt_pk_f16_f32 v98, v98, v99
	v_add_f32_e32 v99, 1.0, v107
	v_rcp_f32_e32 v99, v99
	v_alignbit_b32 v104, v98, v106, 16
	v_lshrrev_b32_e32 v105, 16, v98
	v_max_f32_e32 v98, 0xc1f00000, v100
	v_alignbit_b32 v103, v106, v103, 16
	v_fma_mixhi_f16 v105, v101, v99, 0
	v_mul_f32_e32 v98, 0xbfb8aa3b, v98
	v_cvt_f32_f16_sdwa v101, v142 dst_sel:DWORD dst_unused:UNUSED_PAD src0_sel:WORD_1
	v_exp_f32_e32 v100, v98
	global_store_dwordx4 v[114:115], v[102:105], off offset:256
	v_lshl_add_u64 v[98:99], v[192:193], 0, v[168:169]
	v_max_f32_e32 v101, 0xc1f00000, v101
	v_cvt_f32_f16_e32 v102, v143
	v_add_f32_e32 v100, 1.0, v100
	v_mul_f32_e32 v101, 0xbfb8aa3b, v101
	v_rcp_f32_e32 v100, v100
	v_max_f32_e32 v102, 0xc1f00000, v102
	v_exp_f32_e32 v101, v101
	v_mul_f32_e32 v102, 0xbfb8aa3b, v102
	v_exp_f32_e32 v102, v102
	v_fma_mixlo_f16 v103, v94, v100, 0
	v_add_f32_e32 v94, 1.0, v101
	v_rcp_f32_e32 v100, v94
	v_add_f32_e32 v94, 1.0, v102
	v_rcp_f32_e32 v101, v94
	v_cvt_f32_f16_sdwa v102, v143 dst_sel:DWORD dst_unused:UNUSED_PAD src0_sel:WORD_1
	v_mov_b32_e32 v94, v95
	v_mov_b32_e32 v95, v96
	v_cvt_f32_f16_e32 v96, v144
	v_pk_mul_f32 v[94:95], v[94:95], v[100:101]
	v_max_f32_e32 v100, 0xc1f00000, v102
	v_mul_f32_e32 v100, 0xbfb8aa3b, v100
	v_max_f32_e32 v96, 0xc1f00000, v96
	v_exp_f32_e32 v100, v100
	v_mul_f32_e32 v96, 0xbfb8aa3b, v96
	v_exp_f32_e32 v96, v96
	v_cvt_pk_f16_f32 v95, v94, v95
	v_add_f32_e32 v94, 1.0, v100
	v_rcp_f32_e32 v100, v94
	v_add_f32_e32 v94, 1.0, v96
	v_rcp_f32_e32 v101, v94
	v_pk_mov_b32 v[96:97], v[96:97], v[90:91] op_sel:[1,0]
	v_cvt_f32_f16_sdwa v90, v144 dst_sel:DWORD dst_unused:UNUSED_PAD src0_sel:WORD_1
	v_pack_b32_f16 v94, v103, v95
	v_pk_mul_f32 v[96:97], v[96:97], v[100:101]
	v_cvt_f32_f16_sdwa v101, v145 dst_sel:DWORD dst_unused:UNUSED_PAD src0_sel:WORD_1
	v_cvt_pk_f16_f32 v100, v96, v97
	v_cvt_f32_f16_e32 v96, v145
	v_max_f32_e32 v90, 0xc1f00000, v90
	v_mul_f32_e32 v90, 0xbfb8aa3b, v90
	v_exp_f32_e32 v90, v90
	v_max_f32_e32 v96, 0xc1f00000, v96
	v_mul_f32_e32 v96, 0xbfb8aa3b, v96
	v_exp_f32_e32 v97, v96
	v_add_f32_e32 v90, 1.0, v90
	v_rcp_f32_e32 v96, v90
	v_alignbit_b32 v95, v100, v95, 16
	v_add_f32_e32 v90, 1.0, v97
	v_rcp_f32_e32 v97, v90
	v_mov_b32_e32 v90, v91
	v_mov_b32_e32 v91, v92
	v_cvt_f32_f16_e32 v92, v138
	v_pk_mul_f32 v[90:91], v[90:91], v[96:97]
	global_store_dwordx4 v[114:115], v[110:113], off
	v_cvt_pk_f16_f32 v90, v90, v91
	v_max_f32_e32 v91, 0xc1f00000, v101
	v_mul_f32_e32 v91, 0xbfb8aa3b, v91
	v_exp_f32_e32 v91, v91
	v_alignbit_b32 v96, v90, v100, 16
	v_lshrrev_b32_e32 v97, 16, v90
	v_add_f32_e32 v90, 1.0, v91
	v_rcp_f32_e32 v90, v90
	v_max_f32_e32 v91, 0xc1f00000, v92
	v_mul_f32_e32 v91, 0xbfb8aa3b, v91
	v_exp_f32_e32 v91, v91
	v_fma_mixhi_f16 v97, v93, v90, 0
	v_cvt_f32_f16_sdwa v90, v138 dst_sel:DWORD dst_unused:UNUSED_PAD src0_sel:WORD_1
	v_cvt_f32_f16_e32 v92, v139
	v_add_f32_e32 v91, 1.0, v91
	v_rcp_f32_e32 v91, v91
	v_max_f32_e32 v90, 0xc1f00000, v90
	v_mul_f32_e32 v90, 0xbfb8aa3b, v90
	v_max_f32_e32 v92, 0xc1f00000, v92
	v_exp_f32_e32 v90, v90
	v_mul_f32_e32 v92, 0xbfb8aa3b, v92
	v_exp_f32_e32 v92, v92
	v_fma_mixlo_f16 v93, v86, v91, 0
	v_add_f32_e32 v86, 1.0, v90
	v_rcp_f32_e32 v90, v86
	v_add_f32_e32 v86, 1.0, v92
	v_rcp_f32_e32 v91, v86
	v_cvt_f32_f16_sdwa v92, v139 dst_sel:DWORD dst_unused:UNUSED_PAD src0_sel:WORD_1
	v_mov_b32_e32 v86, v87
	v_mov_b32_e32 v87, v88
	v_cvt_f32_f16_e32 v88, v140
	v_max_f32_e32 v92, 0xc1f00000, v92
	v_mul_f32_e32 v92, 0xbfb8aa3b, v92
	v_exp_f32_e32 v92, v92
	v_max_f32_e32 v88, 0xc1f00000, v88
	v_mul_f32_e32 v88, 0xbfb8aa3b, v88
	v_exp_f32_e32 v88, v88
	v_pk_mul_f32 v[86:87], v[86:87], v[90:91]
	v_add_f32_e32 v90, 1.0, v92
	v_rcp_f32_e32 v90, v90
	v_add_f32_e32 v88, 1.0, v88
	v_rcp_f32_e32 v91, v88
	v_pk_mov_b32 v[88:89], v[88:89], v[82:83] op_sel:[1,0]
	v_cvt_f32_f16_sdwa v82, v140 dst_sel:DWORD dst_unused:UNUSED_PAD src0_sel:WORD_1
	v_cvt_pk_f16_f32 v87, v86, v87
	v_pk_mul_f32 v[88:89], v[88:89], v[90:91]
	v_cvt_f32_f16_sdwa v91, v141 dst_sel:DWORD dst_unused:UNUSED_PAD src0_sel:WORD_1
	v_cvt_pk_f16_f32 v90, v88, v89
	v_cvt_f32_f16_e32 v88, v141
	v_max_f32_e32 v82, 0xc1f00000, v82
	v_mul_f32_e32 v82, 0xbfb8aa3b, v82
	v_exp_f32_e32 v82, v82
	v_max_f32_e32 v88, 0xc1f00000, v88
	v_mul_f32_e32 v88, 0xbfb8aa3b, v88
	v_exp_f32_e32 v89, v88
	v_add_f32_e32 v82, 1.0, v82
	v_rcp_f32_e32 v88, v82
	v_pack_b32_f16 v86, v93, v87
	v_add_f32_e32 v82, 1.0, v89
	v_rcp_f32_e32 v89, v82
	v_mov_b32_e32 v82, v83
	v_max_f32_e32 v83, 0xc1f00000, v91
	v_mul_f32_e32 v83, 0xbfb8aa3b, v83
	v_exp_f32_e32 v91, v83
	v_mov_b32_e32 v83, v84
	v_pk_mul_f32 v[82:83], v[82:83], v[88:89]
	v_cvt_f32_f16_e32 v84, v130
	v_cvt_pk_f16_f32 v82, v82, v83
	v_add_f32_e32 v83, 1.0, v91
	v_rcp_f32_e32 v83, v83
	v_alignbit_b32 v88, v82, v90, 16
	v_lshrrev_b32_e32 v89, 16, v82
	v_max_f32_e32 v82, 0xc1f00000, v84
	v_alignbit_b32 v87, v90, v87, 16
	v_fma_mixhi_f16 v89, v85, v83, 0
	v_mul_f32_e32 v82, 0xbfb8aa3b, v82
	v_cvt_f32_f16_sdwa v85, v130 dst_sel:DWORD dst_unused:UNUSED_PAD src0_sel:WORD_1
	v_exp_f32_e32 v84, v82
	global_store_dwordx4 v[98:99], v[86:89], off offset:256
	v_lshl_add_u64 v[82:83], v[192:193], 0, v[170:171]
	v_max_f32_e32 v85, 0xc1f00000, v85
	v_cvt_f32_f16_e32 v86, v131
	v_add_f32_e32 v84, 1.0, v84
	v_mul_f32_e32 v85, 0xbfb8aa3b, v85
	v_rcp_f32_e32 v84, v84
	v_max_f32_e32 v86, 0xc1f00000, v86
	v_exp_f32_e32 v85, v85
	v_mul_f32_e32 v86, 0xbfb8aa3b, v86
	v_exp_f32_e32 v86, v86
	v_fma_mixlo_f16 v87, v78, v84, 0
	v_add_f32_e32 v78, 1.0, v85
	v_rcp_f32_e32 v84, v78
	v_add_f32_e32 v78, 1.0, v86
	v_rcp_f32_e32 v85, v78
	v_cvt_f32_f16_sdwa v86, v131 dst_sel:DWORD dst_unused:UNUSED_PAD src0_sel:WORD_1
	v_mov_b32_e32 v78, v79
	v_mov_b32_e32 v79, v80
	v_cvt_f32_f16_e32 v80, v132
	v_pk_mul_f32 v[78:79], v[78:79], v[84:85]
	v_max_f32_e32 v84, 0xc1f00000, v86
	v_mul_f32_e32 v84, 0xbfb8aa3b, v84
	v_max_f32_e32 v80, 0xc1f00000, v80
	v_exp_f32_e32 v84, v84
	v_mul_f32_e32 v80, 0xbfb8aa3b, v80
	v_exp_f32_e32 v80, v80
	v_cvt_pk_f16_f32 v79, v78, v79
	v_add_f32_e32 v78, 1.0, v84
	v_rcp_f32_e32 v84, v78
	v_add_f32_e32 v78, 1.0, v80
	v_rcp_f32_e32 v85, v78
	v_pk_mov_b32 v[80:81], v[80:81], v[74:75] op_sel:[1,0]
	v_cvt_f32_f16_sdwa v74, v132 dst_sel:DWORD dst_unused:UNUSED_PAD src0_sel:WORD_1
	v_pack_b32_f16 v78, v87, v79
	v_pk_mul_f32 v[80:81], v[80:81], v[84:85]
	v_cvt_f32_f16_sdwa v85, v133 dst_sel:DWORD dst_unused:UNUSED_PAD src0_sel:WORD_1
	v_cvt_pk_f16_f32 v84, v80, v81
	v_cvt_f32_f16_e32 v80, v133
	v_max_f32_e32 v74, 0xc1f00000, v74
	v_mul_f32_e32 v74, 0xbfb8aa3b, v74
	v_exp_f32_e32 v74, v74
	v_max_f32_e32 v80, 0xc1f00000, v80
	v_mul_f32_e32 v80, 0xbfb8aa3b, v80
	v_exp_f32_e32 v81, v80
	v_add_f32_e32 v74, 1.0, v74
	v_rcp_f32_e32 v80, v74
	v_alignbit_b32 v79, v84, v79, 16
	v_add_f32_e32 v74, 1.0, v81
	v_rcp_f32_e32 v81, v74
	v_mov_b32_e32 v74, v75
	v_mov_b32_e32 v75, v76
	v_cvt_f32_f16_e32 v76, v122
	v_pk_mul_f32 v[74:75], v[74:75], v[80:81]
	global_store_dwordx4 v[98:99], v[94:97], off
	v_cvt_pk_f16_f32 v74, v74, v75
	v_max_f32_e32 v75, 0xc1f00000, v85
	v_mul_f32_e32 v75, 0xbfb8aa3b, v75
	v_exp_f32_e32 v75, v75
	v_alignbit_b32 v80, v74, v84, 16
	v_lshrrev_b32_e32 v81, 16, v74
	v_add_f32_e32 v74, 1.0, v75
	v_rcp_f32_e32 v74, v74
	v_max_f32_e32 v75, 0xc1f00000, v76
	v_mul_f32_e32 v75, 0xbfb8aa3b, v75
	v_exp_f32_e32 v75, v75
	v_fma_mixhi_f16 v81, v77, v74, 0
	v_cvt_f32_f16_sdwa v74, v122 dst_sel:DWORD dst_unused:UNUSED_PAD src0_sel:WORD_1
	v_cvt_f32_f16_e32 v76, v123
	v_add_f32_e32 v75, 1.0, v75
	v_rcp_f32_e32 v75, v75
	v_max_f32_e32 v74, 0xc1f00000, v74
	v_mul_f32_e32 v74, 0xbfb8aa3b, v74
	v_max_f32_e32 v76, 0xc1f00000, v76
	v_exp_f32_e32 v74, v74
	v_mul_f32_e32 v76, 0xbfb8aa3b, v76
	v_exp_f32_e32 v76, v76
	v_fma_mixlo_f16 v77, v70, v75, 0
	v_add_f32_e32 v70, 1.0, v74
	v_rcp_f32_e32 v74, v70
	v_add_f32_e32 v70, 1.0, v76
	v_rcp_f32_e32 v75, v70
	v_cvt_f32_f16_sdwa v76, v123 dst_sel:DWORD dst_unused:UNUSED_PAD src0_sel:WORD_1
	v_mov_b32_e32 v70, v71
	v_mov_b32_e32 v71, v72
	v_cvt_f32_f16_e32 v72, v124
	v_max_f32_e32 v76, 0xc1f00000, v76
	v_mul_f32_e32 v76, 0xbfb8aa3b, v76
	v_exp_f32_e32 v76, v76
	v_max_f32_e32 v72, 0xc1f00000, v72
	v_mul_f32_e32 v72, 0xbfb8aa3b, v72
	v_exp_f32_e32 v72, v72
	v_pk_mul_f32 v[70:71], v[70:71], v[74:75]
	v_add_f32_e32 v74, 1.0, v76
	v_rcp_f32_e32 v74, v74
	v_add_f32_e32 v72, 1.0, v72
	v_rcp_f32_e32 v75, v72
	v_pk_mov_b32 v[72:73], v[72:73], v[66:67] op_sel:[1,0]
	v_cvt_f32_f16_sdwa v66, v124 dst_sel:DWORD dst_unused:UNUSED_PAD src0_sel:WORD_1
	v_cvt_pk_f16_f32 v71, v70, v71
	v_pk_mul_f32 v[72:73], v[72:73], v[74:75]
	v_cvt_f32_f16_sdwa v75, v125 dst_sel:DWORD dst_unused:UNUSED_PAD src0_sel:WORD_1
	v_cvt_pk_f16_f32 v74, v72, v73
	v_cvt_f32_f16_e32 v72, v125
	v_max_f32_e32 v66, 0xc1f00000, v66
	v_mul_f32_e32 v66, 0xbfb8aa3b, v66
	v_exp_f32_e32 v66, v66
	v_max_f32_e32 v72, 0xc1f00000, v72
	v_mul_f32_e32 v72, 0xbfb8aa3b, v72
	v_exp_f32_e32 v73, v72
	v_add_f32_e32 v66, 1.0, v66
	v_rcp_f32_e32 v72, v66
	v_pack_b32_f16 v70, v77, v71
	v_add_f32_e32 v66, 1.0, v73
	v_rcp_f32_e32 v73, v66
	v_max_f32_e32 v66, 0xc1f00000, v75
	v_mul_f32_e32 v66, 0xbfb8aa3b, v66
	v_exp_f32_e32 v75, v66
	v_mov_b32_e32 v66, v67
	v_mov_b32_e32 v67, v68
	v_pk_mul_f32 v[66:67], v[66:67], v[72:73]
	v_add_f32_e32 v68, 1.0, v75
	v_rcp_f32_e32 v68, v68
	v_cvt_pk_f16_f32 v66, v66, v67
	v_lshrrev_b32_e32 v73, 16, v66
	v_alignbit_b32 v71, v74, v71, 16
	v_alignbit_b32 v72, v66, v74, 16
	v_fma_mixhi_f16 v73, v69, v68, 0
	global_store_dwordx4 v[82:83], v[78:81], off
	global_store_dwordx4 v[82:83], v[70:73], off offset:256
	v_lshl_add_u64 v[66:67], v[194:195], 0, v[172:173]
	v_lshl_add_u64 v[68:69], v[194:195], 0, v[174:175]
	v_lshl_add_u64 v[70:71], v[194:195], 0, v[176:177]
	v_lshl_add_u64 v[98:99], v[194:195], 0, v[178:179]
	global_load_dwordx4 v[90:93], v[66:67], off
	global_load_dwordx4 v[94:97], v[66:67], off offset:256
	global_load_dwordx4 v[86:89], v[68:69], off
	global_load_dwordx4 v[82:85], v[68:69], off offset:256
	global_load_dwordx4 v[78:81], v[70:71], off
	global_load_dwordx4 v[74:77], v[70:71], off offset:256
	s_nop 0
	global_load_dwordx4 v[70:73], v[98:99], off
	global_load_dwordx4 v[66:69], v[98:99], off offset:256
	s_waitcnt vmcnt(0)
	v_cvt_f32_f16_e32 v100, v90
	v_cvt_f32_f16_sdwa v90, v90 dst_sel:DWORD dst_unused:UNUSED_PAD src0_sel:WORD_1
	v_cvt_f32_f16_e32 v101, v91
	v_lshl_add_u64 v[98:99], v[192:193], 0, v[180:181]
	v_max_f32_e32 v100, 0xc1f00000, v100
	v_mul_f32_e32 v100, 0xbfb8aa3b, v100
	v_exp_f32_e32 v100, v100
	v_max_f32_e32 v90, 0xc1f00000, v90
	v_max_f32_e32 v101, 0xc1f00000, v101
	v_mul_f32_e32 v90, 0xbfb8aa3b, v90
	v_add_f32_e32 v100, 1.0, v100
	v_rcp_f32_e32 v100, v100
	v_exp_f32_e32 v90, v90
	v_mul_f32_e32 v101, 0xbfb8aa3b, v101
	v_exp_f32_e32 v101, v101
	v_fma_mixlo_f16 v102, v62, v100, 0
	v_add_f32_e32 v62, 1.0, v90
	v_rcp_f32_e32 v100, v62
	v_add_f32_e32 v62, 1.0, v101
	v_cvt_f32_f16_sdwa v90, v91 dst_sel:DWORD dst_unused:UNUSED_PAD src0_sel:WORD_1
	v_rcp_f32_e32 v101, v62
	v_mov_b32_e32 v62, v63
	v_mov_b32_e32 v63, v64
	v_cvt_f32_f16_e32 v64, v92
	v_max_f32_e32 v90, 0xc1f00000, v90
	v_mul_f32_e32 v90, 0xbfb8aa3b, v90
	v_exp_f32_e32 v90, v90
	v_max_f32_e32 v64, 0xc1f00000, v64
	v_mul_f32_e32 v64, 0xbfb8aa3b, v64
	v_exp_f32_e32 v64, v64
	v_pk_mul_f32 v[62:63], v[62:63], v[100:101]
	s_nop 0
	v_cvt_pk_f16_f32 v63, v62, v63
	v_add_f32_e32 v62, 1.0, v90
	v_rcp_f32_e32 v90, v62
	v_add_f32_e32 v62, 1.0, v64
	v_rcp_f32_e32 v91, v62
	v_pk_mov_b32 v[64:65], v[64:65], v[58:59] op_sel:[1,0]
	v_cvt_f32_f16_sdwa v58, v92 dst_sel:DWORD dst_unused:UNUSED_PAD src0_sel:WORD_1
	v_pack_b32_f16 v62, v102, v63
	v_pk_mul_f32 v[64:65], v[64:65], v[90:91]
	v_cvt_f32_f16_sdwa v91, v93 dst_sel:DWORD dst_unused:UNUSED_PAD src0_sel:WORD_1
	v_cvt_pk_f16_f32 v90, v64, v65
	v_cvt_f32_f16_e32 v64, v93
	v_max_f32_e32 v58, 0xc1f00000, v58
	v_mul_f32_e32 v58, 0xbfb8aa3b, v58
	v_exp_f32_e32 v58, v58
	v_max_f32_e32 v64, 0xc1f00000, v64
	v_mul_f32_e32 v64, 0xbfb8aa3b, v64
	v_exp_f32_e32 v65, v64
	v_add_f32_e32 v58, 1.0, v58
	v_rcp_f32_e32 v64, v58
	v_alignbit_b32 v63, v90, v63, 16
	v_add_f32_e32 v58, 1.0, v65
	v_rcp_f32_e32 v65, v58
	v_mov_b32_e32 v58, v59
	v_mov_b32_e32 v59, v60
	v_cvt_f32_f16_e32 v60, v94
	v_pk_mul_f32 v[58:59], v[58:59], v[64:65]
	s_nop 0
	v_cvt_pk_f16_f32 v58, v58, v59
	v_max_f32_e32 v59, 0xc1f00000, v91
	v_mul_f32_e32 v59, 0xbfb8aa3b, v59
	v_exp_f32_e32 v59, v59
	v_alignbit_b32 v64, v58, v90, 16
	v_lshrrev_b32_e32 v65, 16, v58
	v_add_f32_e32 v58, 1.0, v59
	v_rcp_f32_e32 v58, v58
	v_max_f32_e32 v59, 0xc1f00000, v60
	v_mul_f32_e32 v59, 0xbfb8aa3b, v59
	v_exp_f32_e32 v59, v59
	v_fma_mixhi_f16 v65, v61, v58, 0
	v_cvt_f32_f16_sdwa v58, v94 dst_sel:DWORD dst_unused:UNUSED_PAD src0_sel:WORD_1
	v_cvt_f32_f16_e32 v60, v95
	v_add_f32_e32 v59, 1.0, v59
	v_rcp_f32_e32 v59, v59
	v_max_f32_e32 v58, 0xc1f00000, v58
	v_mul_f32_e32 v58, 0xbfb8aa3b, v58
	v_max_f32_e32 v60, 0xc1f00000, v60
	v_exp_f32_e32 v58, v58
	v_mul_f32_e32 v60, 0xbfb8aa3b, v60
	v_exp_f32_e32 v60, v60
	v_fma_mixlo_f16 v61, v54, v59, 0
	v_add_f32_e32 v54, 1.0, v58
	v_rcp_f32_e32 v58, v54
	v_add_f32_e32 v54, 1.0, v60
	v_rcp_f32_e32 v59, v54
	v_cvt_f32_f16_sdwa v60, v95 dst_sel:DWORD dst_unused:UNUSED_PAD src0_sel:WORD_1
	v_mov_b32_e32 v54, v55
	v_mov_b32_e32 v55, v56
	v_cvt_f32_f16_e32 v56, v96
	v_max_f32_e32 v60, 0xc1f00000, v60
	v_mul_f32_e32 v60, 0xbfb8aa3b, v60
	v_exp_f32_e32 v60, v60
	v_max_f32_e32 v56, 0xc1f00000, v56
	v_mul_f32_e32 v56, 0xbfb8aa3b, v56
	v_exp_f32_e32 v56, v56
	v_pk_mul_f32 v[54:55], v[54:55], v[58:59]
	v_add_f32_e32 v58, 1.0, v60
	v_rcp_f32_e32 v58, v58
	v_add_f32_e32 v56, 1.0, v56
	v_rcp_f32_e32 v59, v56
	v_pk_mov_b32 v[56:57], v[56:57], v[50:51] op_sel:[1,0]
	v_cvt_f32_f16_sdwa v50, v96 dst_sel:DWORD dst_unused:UNUSED_PAD src0_sel:WORD_1
	v_cvt_pk_f16_f32 v55, v54, v55
	v_pk_mul_f32 v[56:57], v[56:57], v[58:59]
	v_cvt_f32_f16_sdwa v59, v97 dst_sel:DWORD dst_unused:UNUSED_PAD src0_sel:WORD_1
	v_cvt_pk_f16_f32 v58, v56, v57
	v_cvt_f32_f16_e32 v56, v97
	v_max_f32_e32 v50, 0xc1f00000, v50
	v_mul_f32_e32 v50, 0xbfb8aa3b, v50
	v_exp_f32_e32 v50, v50
	v_max_f32_e32 v56, 0xc1f00000, v56
	v_mul_f32_e32 v56, 0xbfb8aa3b, v56
	v_exp_f32_e32 v57, v56
	v_add_f32_e32 v50, 1.0, v50
	v_rcp_f32_e32 v56, v50
	v_pack_b32_f16 v54, v61, v55
	v_add_f32_e32 v50, 1.0, v57
	v_rcp_f32_e32 v57, v50
	v_mov_b32_e32 v50, v51
	v_max_f32_e32 v51, 0xc1f00000, v59
	v_mul_f32_e32 v51, 0xbfb8aa3b, v51
	v_exp_f32_e32 v59, v51
	v_mov_b32_e32 v51, v52
	v_pk_mul_f32 v[50:51], v[50:51], v[56:57]
	v_cvt_f32_f16_e32 v52, v86
	v_cvt_pk_f16_f32 v50, v50, v51
	v_add_f32_e32 v51, 1.0, v59
	v_rcp_f32_e32 v51, v51
	v_alignbit_b32 v56, v50, v58, 16
	v_lshrrev_b32_e32 v57, 16, v50
	v_max_f32_e32 v50, 0xc1f00000, v52
	v_alignbit_b32 v55, v58, v55, 16
	v_fma_mixhi_f16 v57, v53, v51, 0
	v_mul_f32_e32 v50, 0xbfb8aa3b, v50
	v_cvt_f32_f16_sdwa v53, v86 dst_sel:DWORD dst_unused:UNUSED_PAD src0_sel:WORD_1
	v_exp_f32_e32 v52, v50
	global_store_dwordx4 v[98:99], v[54:57], off offset:256
	v_lshl_add_u64 v[50:51], v[192:193], 0, v[182:183]
	v_max_f32_e32 v53, 0xc1f00000, v53
	v_cvt_f32_f16_e32 v54, v87
	v_add_f32_e32 v52, 1.0, v52
	v_mul_f32_e32 v53, 0xbfb8aa3b, v53
	v_rcp_f32_e32 v52, v52
	v_max_f32_e32 v54, 0xc1f00000, v54
	v_exp_f32_e32 v53, v53
	v_mul_f32_e32 v54, 0xbfb8aa3b, v54
	v_exp_f32_e32 v54, v54
	v_fma_mixlo_f16 v55, v46, v52, 0
	v_add_f32_e32 v46, 1.0, v53
	v_rcp_f32_e32 v52, v46
	v_add_f32_e32 v46, 1.0, v54
	v_rcp_f32_e32 v53, v46
	v_cvt_f32_f16_sdwa v54, v87 dst_sel:DWORD dst_unused:UNUSED_PAD src0_sel:WORD_1
	v_mov_b32_e32 v46, v47
	v_mov_b32_e32 v47, v48
	v_cvt_f32_f16_e32 v48, v88
	v_pk_mul_f32 v[46:47], v[46:47], v[52:53]
	v_max_f32_e32 v52, 0xc1f00000, v54
	v_mul_f32_e32 v52, 0xbfb8aa3b, v52
	v_max_f32_e32 v48, 0xc1f00000, v48
	v_exp_f32_e32 v52, v52
	v_mul_f32_e32 v48, 0xbfb8aa3b, v48
	v_exp_f32_e32 v48, v48
	v_cvt_pk_f16_f32 v47, v46, v47
	v_add_f32_e32 v46, 1.0, v52
	v_rcp_f32_e32 v52, v46
	v_add_f32_e32 v46, 1.0, v48
	v_rcp_f32_e32 v53, v46
	v_pk_mov_b32 v[48:49], v[48:49], v[42:43] op_sel:[1,0]
	v_cvt_f32_f16_sdwa v42, v88 dst_sel:DWORD dst_unused:UNUSED_PAD src0_sel:WORD_1
	v_pack_b32_f16 v46, v55, v47
	v_pk_mul_f32 v[48:49], v[48:49], v[52:53]
	v_cvt_f32_f16_sdwa v53, v89 dst_sel:DWORD dst_unused:UNUSED_PAD src0_sel:WORD_1
	v_cvt_pk_f16_f32 v52, v48, v49
	v_cvt_f32_f16_e32 v48, v89
	v_max_f32_e32 v42, 0xc1f00000, v42
	v_mul_f32_e32 v42, 0xbfb8aa3b, v42
	v_exp_f32_e32 v42, v42
	v_max_f32_e32 v48, 0xc1f00000, v48
	v_mul_f32_e32 v48, 0xbfb8aa3b, v48
	v_exp_f32_e32 v49, v48
	v_add_f32_e32 v42, 1.0, v42
	v_rcp_f32_e32 v48, v42
	v_alignbit_b32 v47, v52, v47, 16
	v_add_f32_e32 v42, 1.0, v49
	v_rcp_f32_e32 v49, v42
	v_mov_b32_e32 v42, v43
	v_mov_b32_e32 v43, v44
	v_cvt_f32_f16_e32 v44, v82
	v_pk_mul_f32 v[42:43], v[42:43], v[48:49]
	global_store_dwordx4 v[98:99], v[62:65], off
	v_cvt_pk_f16_f32 v42, v42, v43
	v_max_f32_e32 v43, 0xc1f00000, v53
	v_mul_f32_e32 v43, 0xbfb8aa3b, v43
	v_exp_f32_e32 v43, v43
	v_alignbit_b32 v48, v42, v52, 16
	v_lshrrev_b32_e32 v49, 16, v42
	v_add_f32_e32 v42, 1.0, v43
	v_rcp_f32_e32 v42, v42
	v_max_f32_e32 v43, 0xc1f00000, v44
	v_mul_f32_e32 v43, 0xbfb8aa3b, v43
	v_exp_f32_e32 v43, v43
	v_fma_mixhi_f16 v49, v45, v42, 0
	v_cvt_f32_f16_sdwa v42, v82 dst_sel:DWORD dst_unused:UNUSED_PAD src0_sel:WORD_1
	v_cvt_f32_f16_e32 v44, v83
	v_add_f32_e32 v43, 1.0, v43
	v_rcp_f32_e32 v43, v43
	v_max_f32_e32 v42, 0xc1f00000, v42
	v_mul_f32_e32 v42, 0xbfb8aa3b, v42
	v_max_f32_e32 v44, 0xc1f00000, v44
	v_exp_f32_e32 v42, v42
	v_mul_f32_e32 v44, 0xbfb8aa3b, v44
	v_exp_f32_e32 v44, v44
	v_fma_mixlo_f16 v45, v38, v43, 0
	v_add_f32_e32 v38, 1.0, v42
	v_rcp_f32_e32 v42, v38
	v_add_f32_e32 v38, 1.0, v44
	v_rcp_f32_e32 v43, v38
	v_cvt_f32_f16_sdwa v44, v83 dst_sel:DWORD dst_unused:UNUSED_PAD src0_sel:WORD_1
	v_mov_b32_e32 v38, v39
	v_mov_b32_e32 v39, v40
	v_cvt_f32_f16_e32 v40, v84
	v_max_f32_e32 v44, 0xc1f00000, v44
	v_mul_f32_e32 v44, 0xbfb8aa3b, v44
	v_exp_f32_e32 v44, v44
	v_max_f32_e32 v40, 0xc1f00000, v40
	v_mul_f32_e32 v40, 0xbfb8aa3b, v40
	v_exp_f32_e32 v40, v40
	v_pk_mul_f32 v[38:39], v[38:39], v[42:43]
	v_add_f32_e32 v42, 1.0, v44
	v_rcp_f32_e32 v42, v42
	v_add_f32_e32 v40, 1.0, v40
	v_rcp_f32_e32 v43, v40
	v_pk_mov_b32 v[40:41], v[40:41], v[34:35] op_sel:[1,0]
	v_cvt_f32_f16_sdwa v34, v84 dst_sel:DWORD dst_unused:UNUSED_PAD src0_sel:WORD_1
	v_cvt_pk_f16_f32 v39, v38, v39
	v_pk_mul_f32 v[40:41], v[40:41], v[42:43]
	v_cvt_f32_f16_sdwa v43, v85 dst_sel:DWORD dst_unused:UNUSED_PAD src0_sel:WORD_1
	v_cvt_pk_f16_f32 v42, v40, v41
	v_cvt_f32_f16_e32 v40, v85
	v_max_f32_e32 v34, 0xc1f00000, v34
	v_mul_f32_e32 v34, 0xbfb8aa3b, v34
	v_exp_f32_e32 v34, v34
	v_max_f32_e32 v40, 0xc1f00000, v40
	v_mul_f32_e32 v40, 0xbfb8aa3b, v40
	v_exp_f32_e32 v41, v40
	v_add_f32_e32 v34, 1.0, v34
	v_rcp_f32_e32 v40, v34
	v_pack_b32_f16 v38, v45, v39
	v_add_f32_e32 v34, 1.0, v41
	v_rcp_f32_e32 v41, v34
	v_mov_b32_e32 v34, v35
	v_max_f32_e32 v35, 0xc1f00000, v43
	v_mul_f32_e32 v35, 0xbfb8aa3b, v35
	v_exp_f32_e32 v43, v35
	v_mov_b32_e32 v35, v36
	v_pk_mul_f32 v[34:35], v[34:35], v[40:41]
	v_cvt_f32_f16_e32 v36, v78
	v_cvt_pk_f16_f32 v34, v34, v35
	v_add_f32_e32 v35, 1.0, v43
	v_rcp_f32_e32 v35, v35
	v_alignbit_b32 v40, v34, v42, 16
	v_lshrrev_b32_e32 v41, 16, v34
	v_max_f32_e32 v34, 0xc1f00000, v36
	v_alignbit_b32 v39, v42, v39, 16
	v_fma_mixhi_f16 v41, v37, v35, 0
	v_mul_f32_e32 v34, 0xbfb8aa3b, v34
	v_cvt_f32_f16_sdwa v37, v78 dst_sel:DWORD dst_unused:UNUSED_PAD src0_sel:WORD_1
	v_exp_f32_e32 v36, v34
	global_store_dwordx4 v[50:51], v[38:41], off offset:256
	v_lshl_add_u64 v[34:35], v[192:193], 0, v[184:185]
	v_max_f32_e32 v37, 0xc1f00000, v37
	v_cvt_f32_f16_e32 v38, v79
	v_add_f32_e32 v36, 1.0, v36
	v_mul_f32_e32 v37, 0xbfb8aa3b, v37
	v_rcp_f32_e32 v36, v36
	v_max_f32_e32 v38, 0xc1f00000, v38
	v_exp_f32_e32 v37, v37
	v_mul_f32_e32 v38, 0xbfb8aa3b, v38
	v_exp_f32_e32 v38, v38
	v_fma_mixlo_f16 v39, v28, v36, 0
	v_add_f32_e32 v28, 1.0, v37
	v_rcp_f32_e32 v36, v28
	v_add_f32_e32 v28, 1.0, v38
	v_rcp_f32_e32 v37, v28
	v_cvt_f32_f16_sdwa v38, v79 dst_sel:DWORD dst_unused:UNUSED_PAD src0_sel:WORD_1
	v_mov_b32_e32 v28, v29
	v_mov_b32_e32 v29, v30
	v_cvt_f32_f16_e32 v30, v80
	v_pk_mul_f32 v[28:29], v[28:29], v[36:37]
	v_max_f32_e32 v36, 0xc1f00000, v38
	v_mul_f32_e32 v36, 0xbfb8aa3b, v36
	v_max_f32_e32 v30, 0xc1f00000, v30
	v_exp_f32_e32 v36, v36
	v_mul_f32_e32 v30, 0xbfb8aa3b, v30
	v_exp_f32_e32 v30, v30
	v_cvt_pk_f16_f32 v29, v28, v29
	v_add_f32_e32 v28, 1.0, v36
	v_rcp_f32_e32 v36, v28
	v_add_f32_e32 v28, 1.0, v30
	v_rcp_f32_e32 v37, v28
	v_pk_mov_b32 v[30:31], v[30:31], v[24:25] op_sel:[1,0]
	v_cvt_f32_f16_sdwa v24, v80 dst_sel:DWORD dst_unused:UNUSED_PAD src0_sel:WORD_1
	v_pack_b32_f16 v28, v39, v29
	v_pk_mul_f32 v[30:31], v[30:31], v[36:37]
	v_cvt_f32_f16_sdwa v37, v81 dst_sel:DWORD dst_unused:UNUSED_PAD src0_sel:WORD_1
	v_cvt_pk_f16_f32 v36, v30, v31
	v_cvt_f32_f16_e32 v30, v81
	v_max_f32_e32 v24, 0xc1f00000, v24
	v_mul_f32_e32 v24, 0xbfb8aa3b, v24
	v_exp_f32_e32 v24, v24
	v_max_f32_e32 v30, 0xc1f00000, v30
	v_mul_f32_e32 v30, 0xbfb8aa3b, v30
	v_exp_f32_e32 v31, v30
	v_add_f32_e32 v24, 1.0, v24
	v_rcp_f32_e32 v30, v24
	v_alignbit_b32 v29, v36, v29, 16
	v_add_f32_e32 v24, 1.0, v31
	v_rcp_f32_e32 v31, v24
	v_mov_b32_e32 v24, v25
	v_mov_b32_e32 v25, v26
	v_cvt_f32_f16_e32 v26, v74
	v_pk_mul_f32 v[24:25], v[24:25], v[30:31]
	global_store_dwordx4 v[50:51], v[46:49], off
	v_cvt_pk_f16_f32 v24, v24, v25
	v_max_f32_e32 v25, 0xc1f00000, v37
	v_mul_f32_e32 v25, 0xbfb8aa3b, v25
	v_exp_f32_e32 v25, v25
	v_alignbit_b32 v30, v24, v36, 16
	v_lshrrev_b32_e32 v31, 16, v24
	v_add_f32_e32 v24, 1.0, v25
	v_rcp_f32_e32 v24, v24
	v_max_f32_e32 v25, 0xc1f00000, v26
	v_mul_f32_e32 v25, 0xbfb8aa3b, v25
	v_exp_f32_e32 v25, v25
	v_fma_mixhi_f16 v31, v27, v24, 0
	v_cvt_f32_f16_sdwa v24, v74 dst_sel:DWORD dst_unused:UNUSED_PAD src0_sel:WORD_1
	v_cvt_f32_f16_e32 v26, v75
	v_add_f32_e32 v25, 1.0, v25
	v_rcp_f32_e32 v25, v25
	v_max_f32_e32 v24, 0xc1f00000, v24
	v_mul_f32_e32 v24, 0xbfb8aa3b, v24
	v_max_f32_e32 v26, 0xc1f00000, v26
	v_exp_f32_e32 v24, v24
	v_mul_f32_e32 v26, 0xbfb8aa3b, v26
	v_exp_f32_e32 v26, v26
	v_fma_mixlo_f16 v27, v20, v25, 0
	v_add_f32_e32 v20, 1.0, v24
	v_rcp_f32_e32 v24, v20
	v_add_f32_e32 v20, 1.0, v26
	v_rcp_f32_e32 v25, v20
	v_cvt_f32_f16_sdwa v26, v75 dst_sel:DWORD dst_unused:UNUSED_PAD src0_sel:WORD_1
	v_mov_b32_e32 v20, v21
	v_mov_b32_e32 v21, v22
	v_cvt_f32_f16_e32 v22, v76
	v_max_f32_e32 v26, 0xc1f00000, v26
	v_mul_f32_e32 v26, 0xbfb8aa3b, v26
	v_exp_f32_e32 v26, v26
	v_max_f32_e32 v22, 0xc1f00000, v22
	v_mul_f32_e32 v22, 0xbfb8aa3b, v22
	v_exp_f32_e32 v22, v22
	v_pk_mul_f32 v[20:21], v[20:21], v[24:25]
	v_add_f32_e32 v24, 1.0, v26
	v_rcp_f32_e32 v24, v24
	v_add_f32_e32 v22, 1.0, v22
	v_rcp_f32_e32 v25, v22
	v_pk_mov_b32 v[22:23], v[22:23], v[16:17] op_sel:[1,0]
	v_cvt_f32_f16_sdwa v16, v76 dst_sel:DWORD dst_unused:UNUSED_PAD src0_sel:WORD_1
	v_cvt_pk_f16_f32 v21, v20, v21
	v_pk_mul_f32 v[22:23], v[22:23], v[24:25]
	v_cvt_f32_f16_sdwa v25, v77 dst_sel:DWORD dst_unused:UNUSED_PAD src0_sel:WORD_1
	v_cvt_pk_f16_f32 v24, v22, v23
	v_cvt_f32_f16_e32 v22, v77
	v_max_f32_e32 v16, 0xc1f00000, v16
	v_mul_f32_e32 v16, 0xbfb8aa3b, v16
	v_exp_f32_e32 v16, v16
	v_max_f32_e32 v22, 0xc1f00000, v22
	v_mul_f32_e32 v22, 0xbfb8aa3b, v22
	v_exp_f32_e32 v23, v22
	v_add_f32_e32 v16, 1.0, v16
	v_rcp_f32_e32 v22, v16
	v_pack_b32_f16 v20, v27, v21
	v_add_f32_e32 v16, 1.0, v23
	v_rcp_f32_e32 v23, v16
	v_mov_b32_e32 v16, v17
	v_max_f32_e32 v17, 0xc1f00000, v25
	v_mul_f32_e32 v17, 0xbfb8aa3b, v17
	v_exp_f32_e32 v25, v17
	v_mov_b32_e32 v17, v18
	v_pk_mul_f32 v[16:17], v[16:17], v[22:23]
	v_cvt_f32_f16_e32 v18, v70
	v_cvt_pk_f16_f32 v16, v16, v17
	v_add_f32_e32 v17, 1.0, v25
	v_rcp_f32_e32 v17, v17
	v_alignbit_b32 v22, v16, v24, 16
	v_lshrrev_b32_e32 v23, 16, v16
	v_max_f32_e32 v16, 0xc1f00000, v18
	v_alignbit_b32 v21, v24, v21, 16
	v_fma_mixhi_f16 v23, v19, v17, 0
	v_mul_f32_e32 v16, 0xbfb8aa3b, v16
	v_cvt_f32_f16_sdwa v19, v70 dst_sel:DWORD dst_unused:UNUSED_PAD src0_sel:WORD_1
	v_exp_f32_e32 v18, v16
	global_store_dwordx4 v[34:35], v[20:23], off offset:256
	v_lshl_add_u64 v[16:17], v[192:193], 0, v[186:187]
	v_max_f32_e32 v19, 0xc1f00000, v19
	v_cvt_f32_f16_e32 v20, v71
	v_add_f32_e32 v18, 1.0, v18
	v_mul_f32_e32 v19, 0xbfb8aa3b, v19
	v_rcp_f32_e32 v18, v18
	v_max_f32_e32 v20, 0xc1f00000, v20
	v_exp_f32_e32 v19, v19
	v_mul_f32_e32 v20, 0xbfb8aa3b, v20
	v_exp_f32_e32 v20, v20
	v_fma_mixlo_f16 v21, v12, v18, 0
	v_add_f32_e32 v12, 1.0, v19
	v_rcp_f32_e32 v18, v12
	v_add_f32_e32 v12, 1.0, v20
	v_rcp_f32_e32 v19, v12
	v_cvt_f32_f16_sdwa v20, v71 dst_sel:DWORD dst_unused:UNUSED_PAD src0_sel:WORD_1
	v_mov_b32_e32 v12, v13
	v_mov_b32_e32 v13, v14
	v_cvt_f32_f16_e32 v14, v72
	v_pk_mul_f32 v[12:13], v[12:13], v[18:19]
	v_max_f32_e32 v18, 0xc1f00000, v20
	v_mul_f32_e32 v18, 0xbfb8aa3b, v18
	v_max_f32_e32 v14, 0xc1f00000, v14
	v_exp_f32_e32 v18, v18
	v_mul_f32_e32 v14, 0xbfb8aa3b, v14
	v_exp_f32_e32 v14, v14
	v_cvt_pk_f16_f32 v13, v12, v13
	v_add_f32_e32 v12, 1.0, v18
	v_rcp_f32_e32 v18, v12
	v_add_f32_e32 v12, 1.0, v14
	v_rcp_f32_e32 v19, v12
	v_pk_mov_b32 v[14:15], v[14:15], v[8:9] op_sel:[1,0]
	v_cvt_f32_f16_sdwa v8, v72 dst_sel:DWORD dst_unused:UNUSED_PAD src0_sel:WORD_1
	v_pack_b32_f16 v12, v21, v13
	v_pk_mul_f32 v[14:15], v[14:15], v[18:19]
	v_cvt_f32_f16_sdwa v19, v73 dst_sel:DWORD dst_unused:UNUSED_PAD src0_sel:WORD_1
	v_cvt_pk_f16_f32 v18, v14, v15
	v_cvt_f32_f16_e32 v14, v73
	v_max_f32_e32 v8, 0xc1f00000, v8
	v_mul_f32_e32 v8, 0xbfb8aa3b, v8
	v_exp_f32_e32 v8, v8
	v_max_f32_e32 v14, 0xc1f00000, v14
	v_mul_f32_e32 v14, 0xbfb8aa3b, v14
	v_exp_f32_e32 v15, v14
	v_add_f32_e32 v8, 1.0, v8
	v_rcp_f32_e32 v14, v8
	v_alignbit_b32 v13, v18, v13, 16
	v_add_f32_e32 v8, 1.0, v15
	v_rcp_f32_e32 v15, v8
	v_mov_b32_e32 v8, v9
	v_mov_b32_e32 v9, v10
	v_cvt_f32_f16_e32 v10, v66
	v_pk_mul_f32 v[8:9], v[8:9], v[14:15]
	global_store_dwordx4 v[34:35], v[28:31], off
	v_cvt_pk_f16_f32 v8, v8, v9
	v_max_f32_e32 v9, 0xc1f00000, v19
	v_mul_f32_e32 v9, 0xbfb8aa3b, v9
	v_exp_f32_e32 v9, v9
	v_alignbit_b32 v14, v8, v18, 16
	v_lshrrev_b32_e32 v15, 16, v8
	v_add_f32_e32 v8, 1.0, v9
	v_rcp_f32_e32 v8, v8
	v_max_f32_e32 v9, 0xc1f00000, v10
	v_mul_f32_e32 v9, 0xbfb8aa3b, v9
	v_exp_f32_e32 v9, v9
	v_fma_mixhi_f16 v15, v11, v8, 0
	v_cvt_f32_f16_sdwa v8, v66 dst_sel:DWORD dst_unused:UNUSED_PAD src0_sel:WORD_1
	v_cvt_f32_f16_e32 v10, v67
	v_add_f32_e32 v9, 1.0, v9
	v_rcp_f32_e32 v9, v9
	v_max_f32_e32 v8, 0xc1f00000, v8
	v_mul_f32_e32 v8, 0xbfb8aa3b, v8
	v_max_f32_e32 v10, 0xc1f00000, v10
	v_exp_f32_e32 v8, v8
	v_mul_f32_e32 v10, 0xbfb8aa3b, v10
	v_exp_f32_e32 v10, v10
	v_fma_mixlo_f16 v11, v4, v9, 0
	v_add_f32_e32 v4, 1.0, v8
	v_rcp_f32_e32 v8, v4
	v_add_f32_e32 v4, 1.0, v10
	v_rcp_f32_e32 v9, v4
	v_cvt_f32_f16_sdwa v10, v67 dst_sel:DWORD dst_unused:UNUSED_PAD src0_sel:WORD_1
	v_mov_b32_e32 v4, v5
	v_mov_b32_e32 v5, v6
	v_cvt_f32_f16_e32 v6, v68
	v_max_f32_e32 v10, 0xc1f00000, v10
	v_mul_f32_e32 v10, 0xbfb8aa3b, v10
	v_exp_f32_e32 v10, v10
	v_max_f32_e32 v6, 0xc1f00000, v6
	v_mul_f32_e32 v6, 0xbfb8aa3b, v6
	v_exp_f32_e32 v6, v6
	v_pk_mul_f32 v[4:5], v[4:5], v[8:9]
	v_add_f32_e32 v8, 1.0, v10
	v_rcp_f32_e32 v8, v8
	v_add_f32_e32 v6, 1.0, v6
	v_rcp_f32_e32 v9, v6
	v_pk_mov_b32 v[6:7], v[6:7], v[0:1] op_sel:[1,0]
	v_cvt_f32_f16_sdwa v0, v68 dst_sel:DWORD dst_unused:UNUSED_PAD src0_sel:WORD_1
	v_cvt_pk_f16_f32 v5, v4, v5
	v_pk_mul_f32 v[6:7], v[6:7], v[8:9]
	v_cvt_f32_f16_sdwa v9, v69 dst_sel:DWORD dst_unused:UNUSED_PAD src0_sel:WORD_1
	v_cvt_pk_f16_f32 v8, v6, v7
	v_cvt_f32_f16_e32 v6, v69
	v_max_f32_e32 v0, 0xc1f00000, v0
	v_mul_f32_e32 v0, 0xbfb8aa3b, v0
	v_exp_f32_e32 v0, v0
	v_max_f32_e32 v6, 0xc1f00000, v6
	v_mul_f32_e32 v6, 0xbfb8aa3b, v6
	v_exp_f32_e32 v7, v6
	v_add_f32_e32 v0, 1.0, v0
	v_rcp_f32_e32 v6, v0
	v_pack_b32_f16 v4, v11, v5
	v_add_f32_e32 v0, 1.0, v7
	v_rcp_f32_e32 v7, v0
	v_max_f32_e32 v0, 0xc1f00000, v9
	v_mul_f32_e32 v0, 0xbfb8aa3b, v0
	v_exp_f32_e32 v9, v0
	v_mov_b32_e32 v0, v1
	v_mov_b32_e32 v1, v2
	v_pk_mul_f32 v[0:1], v[0:1], v[6:7]
	v_add_f32_e32 v2, 1.0, v9
	v_rcp_f32_e32 v2, v2
	v_cvt_pk_f16_f32 v0, v0, v1
	v_lshrrev_b32_e32 v7, 16, v0
	v_alignbit_b32 v5, v8, v5, 16
	v_alignbit_b32 v6, v0, v8, 16
	v_fma_mixhi_f16 v7, v3, v2, 0
	global_store_dwordx4 v[16:17], v[12:15], off
	global_store_dwordx4 v[16:17], v[4:7], off offset:256
	s_and_b64 vcc, exec, s[4:5]
	s_mov_b32 s31, s30
	s_mov_b32 s34, s29
	s_mov_b64 s[12:13], s[0:1]
	s_mov_b64 s[10:11], s[2:3]
	s_cbranch_vccz .LBB0_955
	s_waitcnt vmcnt(0)
	s_cmpk_gt_u32 s19, 0xff
	s_cbranch_scc1 .LBB0_962
	s_barrier

.LBB0_1117:
	s_add_i32 s41, s22, 2
	s_add_u32 s20, s14, 0x100
	s_addc_u32 s21, s15, 0
	s_add_i32 s42, 0, 0x10000
	s_waitcnt vmcnt(0)
	v_add_u32_e32 v102, s42, v230
	ds_read_b128 v[78:81], v102
	ds_read_b128 v[94:97], v102 offset:2048
	ds_read_b128 v[86:89], v102 offset:1024
	ds_read_b128 v[102:105], v102 offset:3072
	s_cmp_eq_u32 s38, s22
	s_cselect_b32 s22, s18, s39
	s_cselect_b32 s25, s17, s21
	s_cselect_b32 s24, s16, s20
	s_cselect_b32 s23, s19, s40
	v_lshl_add_u64 v[178:179], s[14:15], 0, v[200:201]
	s_add_i32 m0, s28, 0xc000
	ds_read_b128 v[122:125], v232
	ds_read_b128 v[130:133], v232 offset:2048
	ds_read_b128 v[154:157], v232 offset:4096
	ds_read_b128 v[170:173], v232 offset:6144
	ds_read_b128 v[126:129], v232 offset:1024
	ds_read_b128 v[134:137], v232 offset:3072
	ds_read_b128 v[158:161], v232 offset:5120
	ds_read_b128 v[174:177], v232 offset:7168
	global_load_lds_dwordx4 v[178:179], off
	v_lshl_add_u64 v[178:179], s[14:15], 0, v[202:203]
	s_add_i32 m0, s28, 0xe000
	s_nop 0
	global_load_lds_dwordx4 v[178:179], off
	s_waitcnt lgkmcnt(8)
	s_barrier
	s_waitcnt lgkmcnt(7)
	s_setprio 1
	v_mfma_f32_16x16x32_f16 v[166:169], v[78:81], v[122:125], v[166:169]
	v_mfma_f32_16x16x32_f16 v[162:165], v[94:97], v[122:125], v[162:165]
	s_waitcnt lgkmcnt(6)
	v_mfma_f32_16x16x32_f16 v[150:153], v[78:81], v[130:133], v[150:153]
	v_mfma_f32_16x16x32_f16 v[142:145], v[94:97], v[130:133], v[142:145]
	s_waitcnt lgkmcnt(5)
	v_mfma_f32_16x16x32_f16 v[110:113], v[78:81], v[154:157], v[110:113]
	v_mfma_f32_16x16x32_f16 v[106:109], v[94:97], v[154:157], v[106:109]
	s_waitcnt lgkmcnt(4)
	v_mfma_f32_16x16x32_f16 v[82:85], v[78:81], v[170:173], v[82:85]
	v_mfma_f32_16x16x32_f16 v[74:77], v[94:97], v[170:173], v[74:77]
	s_waitcnt lgkmcnt(3)
	v_mfma_f32_16x16x32_f16 v[166:169], v[86:89], v[126:129], v[166:169]
	v_mfma_f32_16x16x32_f16 v[162:165], v[102:105], v[126:129], v[162:165]
	s_waitcnt lgkmcnt(2)
	v_mfma_f32_16x16x32_f16 v[150:153], v[86:89], v[134:137], v[150:153]
	v_mfma_f32_16x16x32_f16 v[142:145], v[102:105], v[134:137], v[142:145]
	s_waitcnt lgkmcnt(1)
	v_mfma_f32_16x16x32_f16 v[110:113], v[86:89], v[158:161], v[110:113]
	v_mfma_f32_16x16x32_f16 v[106:109], v[102:105], v[158:161], v[106:109]
	s_waitcnt lgkmcnt(0)
	v_mfma_f32_16x16x32_f16 v[82:85], v[86:89], v[174:177], v[82:85]
	v_mfma_f32_16x16x32_f16 v[74:77], v[102:105], v[174:177], v[74:77]
	s_setprio 0
	s_barrier
	s_add_i32 s43, 0, 0x14000
	s_add_i32 s14, s42, s13
	v_add_u32_e32 v190, s43, v230
	v_lshl_add_u64 v[204:205], s[22:23], 0, v[32:33]
	s_mov_b32 m0, s14
	ds_read_b128 v[178:181], v190
	ds_read_b128 v[186:189], v190 offset:2048
	ds_read_b128 v[182:185], v190 offset:1024
	ds_read_b128 v[190:193], v190 offset:3072
	global_load_lds_dwordx4 v[204:205], off
	v_lshl_add_u64 v[206:207], s[22:23], 0, v[198:199]
	s_add_i32 m0, s14, 0x2000
	s_nop 0
	global_load_lds_dwordx4 v[206:207], off
	s_barrier
	s_waitcnt lgkmcnt(1)
	s_setprio 1
	v_mfma_f32_16x16x32_f16 v[146:149], v[178:181], v[122:125], v[146:149]
	v_mfma_f32_16x16x32_f16 v[118:121], v[178:181], v[130:133], v[118:121]
	v_mfma_f32_16x16x32_f16 v[114:117], v[186:189], v[130:133], v[114:117]
	v_mfma_f32_16x16x32_f16 v[98:101], v[178:181], v[154:157], v[98:101]
	v_mfma_f32_16x16x32_f16 v[90:93], v[186:189], v[154:157], v[90:93]
	v_mfma_f32_16x16x32_f16 v[70:73], v[178:181], v[170:173], v[70:73]
	v_mfma_f32_16x16x32_f16 v[66:69], v[186:189], v[170:173], v[66:69]
	v_mfma_f32_16x16x32_f16 v[146:149], v[182:185], v[126:129], v[146:149]
	s_waitcnt lgkmcnt(0)
	v_mfma_f32_16x16x32_f16 v[122:125], v[186:189], v[122:125], v[138:141]
	v_mfma_f32_16x16x32_f16 v[118:121], v[182:185], v[134:137], v[118:121]
	v_mfma_f32_16x16x32_f16 v[114:117], v[190:193], v[134:137], v[114:117]
	v_mfma_f32_16x16x32_f16 v[98:101], v[182:185], v[158:161], v[98:101]
	v_mfma_f32_16x16x32_f16 v[90:93], v[190:193], v[158:161], v[90:93]
	v_mfma_f32_16x16x32_f16 v[70:73], v[182:185], v[174:177], v[70:73]
	v_mfma_f32_16x16x32_f16 v[66:69], v[190:193], v[174:177], v[66:69]
	v_mfma_f32_16x16x32_f16 v[122:125], v[190:193], v[126:129], v[122:125]
	s_setprio 0
	s_mov_b32 m0, s28
	v_lshl_add_u64 v[208:209], s[24:25], 0, v[32:33]
	s_barrier
	ds_read_b128 v[126:129], v232 offset:16384
	ds_read_b128 v[134:137], v232 offset:18432
	ds_read_b128 v[154:157], v232 offset:20480
	ds_read_b128 v[170:173], v232 offset:22528
	ds_read_b128 v[130:133], v232 offset:17408
	ds_read_b128 v[138:141], v232 offset:19456
	ds_read_b128 v[158:161], v232 offset:21504
	ds_read_b128 v[174:177], v232 offset:23552
	global_load_lds_dwordx4 v[208:209], off
	v_lshl_add_u64 v[210:211], s[24:25], 0, v[198:199]
	s_mov_b32 m0, s29
	s_nop 0
	global_load_lds_dwordx4 v[210:211], off
	s_barrier
	s_waitcnt lgkmcnt(4)
	s_setprio 1
	v_mfma_f32_16x16x32_f16 v[62:65], v[78:81], v[126:129], v[62:65]
	v_mfma_f32_16x16x32_f16 v[58:61], v[94:97], v[126:129], v[58:61]
	v_mfma_f32_16x16x32_f16 v[46:49], v[78:81], v[134:137], v[46:49]
	v_mfma_f32_16x16x32_f16 v[42:45], v[94:97], v[134:137], v[42:45]
	v_mfma_f32_16x16x32_f16 v[28:31], v[78:81], v[154:157], v[28:31]
	v_mfma_f32_16x16x32_f16 v[24:27], v[94:97], v[154:157], v[24:27]
	v_mfma_f32_16x16x32_f16 v[12:15], v[78:81], v[170:173], v[12:15]
	v_mfma_f32_16x16x32_f16 v[8:11], v[94:97], v[170:173], v[8:11]
	s_waitcnt lgkmcnt(0)
	v_mfma_f32_16x16x32_f16 v[62:65], v[86:89], v[130:133], v[62:65]
	v_mfma_f32_16x16x32_f16 v[58:61], v[102:105], v[130:133], v[58:61]
	v_mfma_f32_16x16x32_f16 v[46:49], v[86:89], v[138:141], v[46:49]
	v_mfma_f32_16x16x32_f16 v[42:45], v[102:105], v[138:141], v[42:45]
	v_mfma_f32_16x16x32_f16 v[28:31], v[86:89], v[158:161], v[28:31]
	v_mfma_f32_16x16x32_f16 v[24:27], v[102:105], v[158:161], v[24:27]
	v_mfma_f32_16x16x32_f16 v[12:15], v[86:89], v[174:177], v[12:15]
	v_mfma_f32_16x16x32_f16 v[8:11], v[102:105], v[174:177], v[8:11]
	s_setprio 0
	s_barrier
	s_add_u32 s14, s22, 0x40000
	s_addc_u32 s15, s23, 0
	s_add_i32 s42, s43, s13
	v_lshl_add_u64 v[78:79], s[14:15], 0, v[32:33]
	s_mov_b32 m0, s42
	s_nop 0
	global_load_lds_dwordx4 v[78:79], off
	v_lshl_add_u64 v[78:79], s[14:15], 0, v[198:199]
	s_add_i32 m0, s42, 0x2000
	s_nop 0
	global_load_lds_dwordx4 v[78:79], off
	s_waitcnt vmcnt(6)
	s_barrier
	s_setprio 1
	v_mfma_f32_16x16x32_f16 v[54:57], v[178:181], v[126:129], v[54:57]
	v_mfma_f32_16x16x32_f16 v[50:53], v[186:189], v[126:129], v[50:53]
	v_mfma_f32_16x16x32_f16 v[38:41], v[178:181], v[134:137], v[38:41]
	v_mfma_f32_16x16x32_f16 v[34:37], v[186:189], v[134:137], v[34:37]
	v_mfma_f32_16x16x32_f16 v[20:23], v[178:181], v[154:157], v[20:23]
	v_mfma_f32_16x16x32_f16 v[16:19], v[186:189], v[154:157], v[16:19]
	v_mfma_f32_16x16x32_f16 v[4:7], v[178:181], v[170:173], v[4:7]
	v_mfma_f32_16x16x32_f16 v[0:3], v[186:189], v[170:173], v[0:3]
	v_mfma_f32_16x16x32_f16 v[54:57], v[182:185], v[130:133], v[54:57]
	v_mfma_f32_16x16x32_f16 v[50:53], v[190:193], v[130:133], v[50:53]
	v_mfma_f32_16x16x32_f16 v[38:41], v[182:185], v[138:141], v[38:41]
	v_mfma_f32_16x16x32_f16 v[34:37], v[190:193], v[138:141], v[34:37]
	v_mfma_f32_16x16x32_f16 v[20:23], v[182:185], v[158:161], v[20:23]
	v_mfma_f32_16x16x32_f16 v[16:19], v[190:193], v[158:161], v[16:19]
	v_mfma_f32_16x16x32_f16 v[4:7], v[182:185], v[174:177], v[4:7]
	v_mfma_f32_16x16x32_f16 v[0:3], v[190:193], v[174:177], v[0:3]
	s_setprio 0
	s_add_i32 s42, 0, 0x18000
	v_add_u32_e32 v102, s42, v230
	s_barrier
	ds_read_b128 v[78:81], v102
	ds_read_b128 v[86:89], v102 offset:1024
	ds_read_b128 v[94:97], v102 offset:2048
	ds_read_b128 v[102:105], v102 offset:3072
	s_add_u32 s14, s24, 0x40000
	s_addc_u32 s15, s25, 0
	s_mov_b32 m0, s30
	v_lshl_add_u64 v[138:139], s[14:15], 0, v[32:33]
	ds_read_b128 v[126:129], v232 offset:32768
	ds_read_b128 v[130:133], v232 offset:33792
	ds_read_b128 v[134:137], v232 offset:34816
	ds_read_b128 v[154:157], v232 offset:35840
	ds_read_b128 v[158:161], v232 offset:36864
	ds_read_b128 v[174:177], v232 offset:38912
	ds_read_b128 v[170:173], v232 offset:37888
	ds_read_b128 v[178:181], v232 offset:39936
	global_load_lds_dwordx4 v[138:139], off
	v_lshl_add_u64 v[138:139], s[14:15], 0, v[198:199]
	s_mov_b32 m0, s31
	s_nop 0
	global_load_lds_dwordx4 v[138:139], off
	s_waitcnt lgkmcnt(8)
	s_barrier
	s_waitcnt lgkmcnt(6)
	s_setprio 1
	v_mfma_f32_16x16x32_f16 v[138:141], v[78:81], v[126:129], v[166:169]
	v_mfma_f32_16x16x32_f16 v[166:169], v[86:89], v[130:133], v[138:141]
	v_mfma_f32_16x16x32_f16 v[138:141], v[94:97], v[126:129], v[162:165]
	v_mfma_f32_16x16x32_f16 v[162:165], v[102:105], v[130:133], v[138:141]
	s_waitcnt lgkmcnt(4)
	v_mfma_f32_16x16x32_f16 v[138:141], v[78:81], v[134:137], v[150:153]
	v_mfma_f32_16x16x32_f16 v[150:153], v[86:89], v[154:157], v[138:141]
	s_waitcnt lgkmcnt(3)
	v_mfma_f32_16x16x32_f16 v[138:141], v[94:97], v[134:137], v[142:145]
	v_mfma_f32_16x16x32_f16 v[110:113], v[78:81], v[158:161], v[110:113]
	s_waitcnt lgkmcnt(2)
	v_mfma_f32_16x16x32_f16 v[106:109], v[94:97], v[158:161], v[106:109]
	v_mfma_f32_16x16x32_f16 v[82:85], v[78:81], v[174:177], v[82:85]
	v_mfma_f32_16x16x32_f16 v[74:77], v[94:97], v[174:177], v[74:77]
	v_mfma_f32_16x16x32_f16 v[142:145], v[102:105], v[154:157], v[138:141]
	s_waitcnt lgkmcnt(1)
	v_mfma_f32_16x16x32_f16 v[110:113], v[86:89], v[170:173], v[110:113]
	v_mfma_f32_16x16x32_f16 v[106:109], v[102:105], v[170:173], v[106:109]
	s_waitcnt lgkmcnt(0)
	v_mfma_f32_16x16x32_f16 v[82:85], v[86:89], v[178:181], v[82:85]
	v_mfma_f32_16x16x32_f16 v[74:77], v[102:105], v[178:181], v[74:77]
	s_setprio 0
	s_barrier
	s_add_i32 s24, 0, 0x1c000
	v_add_u32_e32 v138, s24, v230
	s_add_i32 s14, s42, s13
	ds_read_b128 v[182:185], v138
	ds_read_b128 v[190:193], v138 offset:2048
	ds_read_b128 v[186:189], v138 offset:1024
	ds_read_b128 v[194:197], v138 offset:3072
	v_lshl_add_u64 v[138:139], v[204:205], 0, s[84:85]
	s_mov_b32 m0, s14
	s_nop 0
	global_load_lds_dwordx4 v[138:139], off
	v_lshl_add_u64 v[138:139], v[206:207], 0, s[84:85]
	s_add_i32 m0, s14, 0x2000
	s_nop 0
	global_load_lds_dwordx4 v[138:139], off
	s_barrier
	s_waitcnt lgkmcnt(2)
	s_setprio 1
	v_mfma_f32_16x16x32_f16 v[138:141], v[182:185], v[126:129], v[146:149]
	v_mfma_f32_16x16x32_f16 v[122:125], v[190:193], v[126:129], v[122:125]
	v_mfma_f32_16x16x32_f16 v[118:121], v[182:185], v[134:137], v[118:121]
	v_mfma_f32_16x16x32_f16 v[114:117], v[190:193], v[134:137], v[114:117]
	v_mfma_f32_16x16x32_f16 v[98:101], v[182:185], v[158:161], v[98:101]
	v_mfma_f32_16x16x32_f16 v[90:93], v[190:193], v[158:161], v[90:93]
	v_mfma_f32_16x16x32_f16 v[70:73], v[182:185], v[174:177], v[70:73]
	v_mfma_f32_16x16x32_f16 v[66:69], v[190:193], v[174:177], v[66:69]
	s_waitcnt lgkmcnt(0)
	v_mfma_f32_16x16x32_f16 v[146:149], v[186:189], v[130:133], v[138:141]
	v_mfma_f32_16x16x32_f16 v[138:141], v[194:197], v[130:133], v[122:125]
	v_mfma_f32_16x16x32_f16 v[118:121], v[186:189], v[154:157], v[118:121]
	v_mfma_f32_16x16x32_f16 v[114:117], v[194:197], v[154:157], v[114:117]
	v_mfma_f32_16x16x32_f16 v[98:101], v[186:189], v[170:173], v[98:101]
	v_mfma_f32_16x16x32_f16 v[90:93], v[194:197], v[170:173], v[90:93]
	v_mfma_f32_16x16x32_f16 v[70:73], v[186:189], v[178:181], v[70:73]
	v_mfma_f32_16x16x32_f16 v[66:69], v[194:197], v[178:181], v[66:69]
	s_setprio 0
	s_mov_b32 m0, s34
	v_lshl_add_u64 v[178:179], v[208:209], 0, s[84:85]
	s_barrier
	ds_read_b128 v[122:125], v232 offset:49152
	ds_read_b128 v[130:133], v232 offset:51200
	ds_read_b128 v[154:157], v232 offset:53248
	ds_read_b128 v[170:173], v232 offset:55296
	ds_read_b128 v[126:129], v232 offset:50176
	ds_read_b128 v[134:137], v232 offset:52224
	ds_read_b128 v[158:161], v232 offset:54272
	ds_read_b128 v[174:177], v232 offset:56320
	global_load_lds_dwordx4 v[178:179], off
	v_lshl_add_u64 v[178:179], v[210:211], 0, s[84:85]
	s_mov_b32 m0, s35
	s_nop 0
	global_load_lds_dwordx4 v[178:179], off
	s_barrier
	s_waitcnt lgkmcnt(4)
	s_setprio 1
	v_mfma_f32_16x16x32_f16 v[62:65], v[78:81], v[122:125], v[62:65]
	v_mfma_f32_16x16x32_f16 v[58:61], v[94:97], v[122:125], v[58:61]
	v_mfma_f32_16x16x32_f16 v[46:49], v[78:81], v[130:133], v[46:49]
	v_mfma_f32_16x16x32_f16 v[42:45], v[94:97], v[130:133], v[42:45]
	v_mfma_f32_16x16x32_f16 v[28:31], v[78:81], v[154:157], v[28:31]
	v_mfma_f32_16x16x32_f16 v[24:27], v[94:97], v[154:157], v[24:27]
	v_mfma_f32_16x16x32_f16 v[12:15], v[78:81], v[170:173], v[12:15]
	v_mfma_f32_16x16x32_f16 v[8:11], v[94:97], v[170:173], v[8:11]
	s_waitcnt lgkmcnt(0)
	v_mfma_f32_16x16x32_f16 v[62:65], v[86:89], v[126:129], v[62:65]
	v_mfma_f32_16x16x32_f16 v[58:61], v[102:105], v[126:129], v[58:61]
	v_mfma_f32_16x16x32_f16 v[46:49], v[86:89], v[134:137], v[46:49]
	v_mfma_f32_16x16x32_f16 v[42:45], v[102:105], v[134:137], v[42:45]
	v_mfma_f32_16x16x32_f16 v[28:31], v[86:89], v[158:161], v[28:31]
	v_mfma_f32_16x16x32_f16 v[24:27], v[102:105], v[158:161], v[24:27]
	v_mfma_f32_16x16x32_f16 v[12:15], v[86:89], v[174:177], v[12:15]
	v_mfma_f32_16x16x32_f16 v[8:11], v[102:105], v[174:177], v[8:11]
	s_setprio 0
	s_barrier
	s_add_u32 s14, s22, 0x40080
	s_addc_u32 s15, s23, 0
	s_add_i32 s22, s24, s13
	v_lshl_add_u64 v[78:79], s[14:15], 0, v[32:33]
	s_mov_b32 m0, s22
	s_nop 0
	global_load_lds_dwordx4 v[78:79], off
	v_lshl_add_u64 v[78:79], s[14:15], 0, v[198:199]
	s_add_i32 m0, s22, 0x2000
	s_nop 0
	global_load_lds_dwordx4 v[78:79], off
	s_waitcnt vmcnt(6)
	s_barrier
	s_setprio 1
	v_mfma_f32_16x16x32_f16 v[54:57], v[182:185], v[122:125], v[54:57]
	v_mfma_f32_16x16x32_f16 v[50:53], v[190:193], v[122:125], v[50:53]
	v_mfma_f32_16x16x32_f16 v[38:41], v[182:185], v[130:133], v[38:41]
	v_mfma_f32_16x16x32_f16 v[34:37], v[190:193], v[130:133], v[34:37]
	v_mfma_f32_16x16x32_f16 v[20:23], v[182:185], v[154:157], v[20:23]
	v_mfma_f32_16x16x32_f16 v[16:19], v[190:193], v[154:157], v[16:19]
	v_mfma_f32_16x16x32_f16 v[4:7], v[182:185], v[170:173], v[4:7]
	v_mfma_f32_16x16x32_f16 v[0:3], v[190:193], v[170:173], v[0:3]
	v_mfma_f32_16x16x32_f16 v[54:57], v[186:189], v[126:129], v[54:57]
	v_mfma_f32_16x16x32_f16 v[50:53], v[194:197], v[126:129], v[50:53]
	v_mfma_f32_16x16x32_f16 v[38:41], v[186:189], v[134:137], v[38:41]
	v_mfma_f32_16x16x32_f16 v[34:37], v[194:197], v[134:137], v[34:37]
	v_mfma_f32_16x16x32_f16 v[20:23], v[186:189], v[158:161], v[20:23]
	v_mfma_f32_16x16x32_f16 v[16:19], v[194:197], v[158:161], v[16:19]
	v_mfma_f32_16x16x32_f16 v[4:7], v[186:189], v[174:177], v[4:7]
	v_mfma_f32_16x16x32_f16 v[0:3], v[194:197], v[174:177], v[0:3]
	s_setprio 0
	s_add_u32 s39, s39, 0x100
	s_addc_u32 s40, s40, 0
	s_cmp_ge_u32 s41, s37
	s_mov_b64 s[14:15], s[20:21]
	s_mov_b32 s22, s41
	s_barrier
	s_cbranch_scc0 .LBB0_1117
	v_lshl_or_b32 v124, s12, 8, v231
	s_cmp_eq_u32 s10, 0
	s_movk_i32 s12, 0x5000
	s_cselect_b32 s12, 0xe000, s12
	v_readlane_b32 s14, v252, 51
	s_add_u32 s14, s14, s12
	v_readlane_b32 s12, v252, 52
	s_addc_u32 s15, s12, 0
	v_ashrrev_i32_e32 v125, 31, v124
	v_lshl_add_u64 v[86:87], v[124:125], 2, s[14:15]
	global_load_dwordx4 v[94:97], v[86:87], off offset:16
	global_load_dwordx4 v[102:105], v[86:87], off
	global_load_dwordx4 v[78:81], v[86:87], off offset:528
	s_nop 0
	global_load_dwordx4 v[86:89], v[86:87], off offset:512
	v_lshl_add_u32 v130, s10, 8, v229
	v_or_b32_e32 v128, 16, v130
	v_or_b32_e32 v126, 32, v130
	v_or_b32_e32 v122, 48, v130
	s_cmp_eq_u32 s11, 0
	v_ashrrev_i32_e32 v131, 31, v130
	v_ashrrev_i32_e32 v129, 31, v128
	v_ashrrev_i32_e32 v127, 31, v126
	v_ashrrev_i32_e32 v123, 31, v122
	s_cbranch_scc1 .LBB0_1120
	s_add_i32 s96, s11, -1
	s_lshl_b64 s[10:11], s[96:97], 20
	v_readlane_b32 s14, v252, 11
	v_readlane_b32 s15, v252, 12
	s_add_u32 s10, s14, s10
	s_addc_u32 s11, s15, s11
	v_lshlrev_b64 v[132:133], 2, v[124:125]
	v_lshrrev_b32_e32 v134, 5, v220
	v_mul_u32_u24_e32 v134, 48, v134
	s_nop 0
	v_sub_co_u32_e32 v132, vcc, v132, v134
	s_nop 1
	v_subbrev_co_u32_e32 v133, vcc, 0, v133, vcc
	v_lshl_add_u64 v[132:133], s[10:11], 0, v[132:133]
	s_mov_b64 s[10:11], 0x80000
	v_lshlrev_b64 v[204:205], 12, v[130:131]
	v_lshl_add_u64 v[204:205], v[204:205], 0, v[132:133]
	v_lshl_add_u64 v[212:213], v[204:205], 0, s[10:11]
	v_lshlrev_b64 v[206:207], 12, v[128:129]
	v_lshl_add_u64 v[206:207], v[206:207], 0, v[132:133]
	v_lshl_add_u64 v[214:215], v[206:207], 0, s[10:11]
	v_lshlrev_b64 v[208:209], 12, v[126:127]
	v_lshl_add_u64 v[208:209], v[208:209], 0, v[132:133]
	v_lshl_add_u64 v[216:217], v[208:209], 0, s[10:11]
	v_lshlrev_b64 v[210:211], 12, v[122:123]
	v_lshl_add_u64 v[210:211], v[210:211], 0, v[132:133]
	v_lshl_add_u64 v[218:219], v[210:211], 0, s[10:11]
	s_waitcnt vmcnt(0)
	v_pk_mul_f32 v[172:173], v[166:167], v[102:103]
	v_pk_mul_f32 v[174:175], v[168:169], v[104:105]
	v_pk_mul_f32 v[176:177], v[162:163], v[94:95]
	v_pk_mul_f32 v[178:179], v[164:165], v[96:97]
	s_nop 1
	v_permlane32_swap_b32_e32 v172, v176
	v_permlane32_swap_b32_e32 v173, v177
	v_permlane32_swap_b32_e32 v174, v178
	v_permlane32_swap_b32_e32 v175, v179
	s_nop 0
	global_store_dwordx4 v[204:205], v[172:175], off
	global_store_dwordx4 v[204:205], v[176:179], off offset:64
	v_pk_mul_f32 v[180:181], v[146:147], v[86:87]
	v_pk_mul_f32 v[182:183], v[148:149], v[88:89]
	v_pk_mul_f32 v[184:185], v[138:139], v[78:79]
	v_pk_mul_f32 v[186:187], v[140:141], v[80:81]
	s_nop 1
	v_permlane32_swap_b32_e32 v180, v184
	v_permlane32_swap_b32_e32 v181, v185
	v_permlane32_swap_b32_e32 v182, v186
	v_permlane32_swap_b32_e32 v183, v187
	s_nop 0
	global_store_dwordx4 v[204:205], v[180:183], off offset:512
	global_store_dwordx4 v[204:205], v[184:187], off offset:576
	v_pk_mul_f32 v[188:189], v[150:151], v[102:103]
	v_pk_mul_f32 v[190:191], v[152:153], v[104:105]
	v_pk_mul_f32 v[192:193], v[142:143], v[94:95]
	v_pk_mul_f32 v[194:195], v[144:145], v[96:97]
	s_nop 1
	v_permlane32_swap_b32_e32 v188, v192
	v_permlane32_swap_b32_e32 v189, v193
	v_permlane32_swap_b32_e32 v190, v194
	v_permlane32_swap_b32_e32 v191, v195
	s_nop 0
	global_store_dwordx4 v[206:207], v[188:191], off
	global_store_dwordx4 v[206:207], v[192:195], off offset:64
	v_pk_mul_f32 v[154:155], v[118:119], v[86:87]
	v_pk_mul_f32 v[156:157], v[120:121], v[88:89]
	v_pk_mul_f32 v[158:159], v[114:115], v[78:79]
	v_pk_mul_f32 v[160:161], v[116:117], v[80:81]
	s_nop 1
	v_permlane32_swap_b32_e32 v154, v158
	v_permlane32_swap_b32_e32 v155, v159
	v_permlane32_swap_b32_e32 v156, v160
	v_permlane32_swap_b32_e32 v157, v161
	s_nop 0
	global_store_dwordx4 v[206:207], v[154:157], off offset:512
	global_store_dwordx4 v[206:207], v[158:161], off offset:576
	v_pk_mul_f32 v[172:173], v[110:111], v[102:103]
	v_pk_mul_f32 v[174:175], v[112:113], v[104:105]
	v_pk_mul_f32 v[176:177], v[106:107], v[94:95]
	v_pk_mul_f32 v[178:179], v[108:109], v[96:97]
	s_nop 1
	v_permlane32_swap_b32_e32 v172, v176
	v_permlane32_swap_b32_e32 v173, v177
	v_permlane32_swap_b32_e32 v174, v178
	v_permlane32_swap_b32_e32 v175, v179
	s_nop 0
	global_store_dwordx4 v[208:209], v[172:175], off
	global_store_dwordx4 v[208:209], v[176:179], off offset:64
	v_pk_mul_f32 v[180:181], v[98:99], v[86:87]
	v_pk_mul_f32 v[182:183], v[100:101], v[88:89]
	v_pk_mul_f32 v[184:185], v[90:91], v[78:79]
	v_pk_mul_f32 v[186:187], v[92:93], v[80:81]
	s_nop 1
	v_permlane32_swap_b32_e32 v180, v184
	v_permlane32_swap_b32_e32 v181, v185
	v_permlane32_swap_b32_e32 v182, v186
	v_permlane32_swap_b32_e32 v183, v187
	s_nop 0
	global_store_dwordx4 v[208:209], v[180:183], off offset:512
	global_store_dwordx4 v[208:209], v[184:187], off offset:576
	v_pk_mul_f32 v[188:189], v[82:83], v[102:103]
	v_pk_mul_f32 v[190:191], v[84:85], v[104:105]
	v_pk_mul_f32 v[192:193], v[74:75], v[94:95]
	v_pk_mul_f32 v[194:195], v[76:77], v[96:97]
	s_nop 1
	v_permlane32_swap_b32_e32 v188, v192
	v_permlane32_swap_b32_e32 v189, v193
	v_permlane32_swap_b32_e32 v190, v194
	v_permlane32_swap_b32_e32 v191, v195
	s_nop 0
	global_store_dwordx4 v[210:211], v[188:191], off
	global_store_dwordx4 v[210:211], v[192:195], off offset:64
	v_pk_mul_f32 v[154:155], v[70:71], v[86:87]
	v_pk_mul_f32 v[156:157], v[72:73], v[88:89]
	v_pk_mul_f32 v[158:159], v[66:67], v[78:79]
	v_pk_mul_f32 v[160:161], v[68:69], v[80:81]
	s_nop 1
	v_permlane32_swap_b32_e32 v154, v158
	v_permlane32_swap_b32_e32 v155, v159
	v_permlane32_swap_b32_e32 v156, v160
	v_permlane32_swap_b32_e32 v157, v161
	s_nop 0
	global_store_dwordx4 v[210:211], v[154:157], off offset:512
	global_store_dwordx4 v[210:211], v[158:161], off offset:576
	v_pk_mul_f32 v[172:173], v[62:63], v[102:103]
	v_pk_mul_f32 v[174:175], v[64:65], v[104:105]
	v_pk_mul_f32 v[176:177], v[58:59], v[94:95]
	v_pk_mul_f32 v[178:179], v[60:61], v[96:97]
	s_nop 1
	v_permlane32_swap_b32_e32 v172, v176
	v_permlane32_swap_b32_e32 v173, v177
	v_permlane32_swap_b32_e32 v174, v178
	v_permlane32_swap_b32_e32 v175, v179
	s_nop 0
	global_store_dwordx4 v[212:213], v[172:175], off
	global_store_dwordx4 v[212:213], v[176:179], off offset:64
	v_pk_mul_f32 v[180:181], v[54:55], v[86:87]
	v_pk_mul_f32 v[182:183], v[56:57], v[88:89]
	v_pk_mul_f32 v[184:185], v[50:51], v[78:79]
	v_pk_mul_f32 v[186:187], v[52:53], v[80:81]
	s_nop 1
	v_permlane32_swap_b32_e32 v180, v184
	v_permlane32_swap_b32_e32 v181, v185
	v_permlane32_swap_b32_e32 v182, v186
	v_permlane32_swap_b32_e32 v183, v187
	s_nop 0
	global_store_dwordx4 v[212:213], v[180:183], off offset:512
	global_store_dwordx4 v[212:213], v[184:187], off offset:576
	v_pk_mul_f32 v[188:189], v[46:47], v[102:103]
	v_pk_mul_f32 v[190:191], v[48:49], v[104:105]
	v_pk_mul_f32 v[192:193], v[42:43], v[94:95]
	v_pk_mul_f32 v[194:195], v[44:45], v[96:97]
	s_nop 1
	v_permlane32_swap_b32_e32 v188, v192
	v_permlane32_swap_b32_e32 v189, v193
	v_permlane32_swap_b32_e32 v190, v194
	v_permlane32_swap_b32_e32 v191, v195
	s_nop 0
	global_store_dwordx4 v[214:215], v[188:191], off
	global_store_dwordx4 v[214:215], v[192:195], off offset:64
	v_pk_mul_f32 v[154:155], v[38:39], v[86:87]
	v_pk_mul_f32 v[156:157], v[40:41], v[88:89]
	v_pk_mul_f32 v[158:159], v[34:35], v[78:79]
	v_pk_mul_f32 v[160:161], v[36:37], v[80:81]
	s_nop 1
	v_permlane32_swap_b32_e32 v154, v158
	v_permlane32_swap_b32_e32 v155, v159
	v_permlane32_swap_b32_e32 v156, v160
	v_permlane32_swap_b32_e32 v157, v161
	s_nop 0
	global_store_dwordx4 v[214:215], v[154:157], off offset:512
	global_store_dwordx4 v[214:215], v[158:161], off offset:576
	v_pk_mul_f32 v[172:173], v[28:29], v[102:103]
	v_pk_mul_f32 v[174:175], v[30:31], v[104:105]
	v_pk_mul_f32 v[176:177], v[24:25], v[94:95]
	v_pk_mul_f32 v[178:179], v[26:27], v[96:97]
	s_nop 1
	v_permlane32_swap_b32_e32 v172, v176
	v_permlane32_swap_b32_e32 v173, v177
	v_permlane32_swap_b32_e32 v174, v178
	v_permlane32_swap_b32_e32 v175, v179
	s_nop 0
	global_store_dwordx4 v[216:217], v[172:175], off
	global_store_dwordx4 v[216:217], v[176:179], off offset:64
	v_pk_mul_f32 v[180:181], v[20:21], v[86:87]
	v_pk_mul_f32 v[182:183], v[22:23], v[88:89]
	v_pk_mul_f32 v[184:185], v[16:17], v[78:79]
	v_pk_mul_f32 v[186:187], v[18:19], v[80:81]
	s_nop 1
	v_permlane32_swap_b32_e32 v180, v184
	v_permlane32_swap_b32_e32 v181, v185
	v_permlane32_swap_b32_e32 v182, v186
	v_permlane32_swap_b32_e32 v183, v187
	s_nop 0
	global_store_dwordx4 v[216:217], v[180:183], off offset:512
	global_store_dwordx4 v[216:217], v[184:187], off offset:576
	v_pk_mul_f32 v[188:189], v[12:13], v[102:103]
	v_pk_mul_f32 v[190:191], v[14:15], v[104:105]
	v_pk_mul_f32 v[192:193], v[8:9], v[94:95]
	v_pk_mul_f32 v[194:195], v[10:11], v[96:97]
	s_nop 1
	v_permlane32_swap_b32_e32 v188, v192
	v_permlane32_swap_b32_e32 v189, v193
	v_permlane32_swap_b32_e32 v190, v194
	v_permlane32_swap_b32_e32 v191, v195
	s_nop 0
	global_store_dwordx4 v[218:219], v[188:191], off
	global_store_dwordx4 v[218:219], v[192:195], off offset:64
	v_pk_mul_f32 v[154:155], v[4:5], v[86:87]
	v_pk_mul_f32 v[156:157], v[6:7], v[88:89]
	v_pk_mul_f32 v[158:159], v[0:1], v[78:79]
	v_pk_mul_f32 v[160:161], v[2:3], v[80:81]
	s_nop 1
	v_permlane32_swap_b32_e32 v154, v158
	v_permlane32_swap_b32_e32 v155, v159
	v_permlane32_swap_b32_e32 v156, v160
	v_permlane32_swap_b32_e32 v157, v161
	s_nop 0
	global_store_dwordx4 v[218:219], v[154:157], off offset:512
	global_store_dwordx4 v[218:219], v[158:161], off offset:576
	s_cbranch_execnz .LBB0_1104
	s_branch .LBB0_1103

.LBB0_1276:
	s_add_u32 s16, s14, 0x100
	s_addc_u32 s17, s15, 0
	s_add_i32 s39, 0, 0x10000
	v_add_u32_e32 v152, s39, v137
	ds_read_b128 v[140:143], v152
	ds_read_b128 v[148:151], v152 offset:2048
	ds_read_b128 v[144:147], v152 offset:1024
	ds_read_b128 v[152:155], v152 offset:3072
	s_cmp_eq_u32 s38, 12
	s_cselect_b32 s21, s11, s17
	s_cselect_b32 s20, s10, s16
	s_cselect_b32 s19, s13, s37
	s_cselect_b32 s18, s12, s3
	v_lshl_add_u64 v[188:189], s[14:15], 0, v[132:133]
	s_add_i32 m0, s9, 0xc000
	ds_read_b128 v[156:159], v139
	ds_read_b128 v[164:167], v139 offset:2048
	ds_read_b128 v[172:175], v139 offset:4096
	ds_read_b128 v[180:183], v139 offset:6144
	ds_read_b128 v[160:163], v139 offset:1024
	ds_read_b128 v[168:171], v139 offset:3072
	ds_read_b128 v[176:179], v139 offset:5120
	ds_read_b128 v[184:187], v139 offset:7168
	global_load_lds_dwordx4 v[188:189], off
	v_lshl_add_u64 v[188:189], s[14:15], 0, v[134:135]
	s_add_i32 m0, s9, 0xe000
	s_nop 0
	global_load_lds_dwordx4 v[188:189], off
	s_waitcnt lgkmcnt(8)
	s_barrier
	s_waitcnt lgkmcnt(7)
	s_setprio 1
	v_mfma_f32_16x16x32_f16 v[126:129], v[140:143], v[156:159], v[126:129]
	v_mfma_f32_16x16x32_f16 v[122:125], v[148:151], v[156:159], v[122:125]
	s_waitcnt lgkmcnt(6)
	v_mfma_f32_16x16x32_f16 v[110:113], v[140:143], v[164:167], v[110:113]
	v_mfma_f32_16x16x32_f16 v[106:109], v[148:151], v[164:167], v[106:109]
	s_waitcnt lgkmcnt(5)
	v_mfma_f32_16x16x32_f16 v[94:97], v[140:143], v[172:175], v[94:97]
	v_mfma_f32_16x16x32_f16 v[90:93], v[148:151], v[172:175], v[90:93]
	s_waitcnt lgkmcnt(4)
	v_mfma_f32_16x16x32_f16 v[78:81], v[140:143], v[180:183], v[78:81]
	v_mfma_f32_16x16x32_f16 v[74:77], v[148:151], v[180:183], v[74:77]
	s_waitcnt lgkmcnt(3)
	v_mfma_f32_16x16x32_f16 v[126:129], v[144:147], v[160:163], v[126:129]
	v_mfma_f32_16x16x32_f16 v[122:125], v[152:155], v[160:163], v[122:125]
	s_waitcnt lgkmcnt(2)
	v_mfma_f32_16x16x32_f16 v[110:113], v[144:147], v[168:171], v[110:113]
	v_mfma_f32_16x16x32_f16 v[106:109], v[152:155], v[168:171], v[106:109]
	s_waitcnt lgkmcnt(1)
	v_mfma_f32_16x16x32_f16 v[94:97], v[144:147], v[176:179], v[94:97]
	v_mfma_f32_16x16x32_f16 v[90:93], v[152:155], v[176:179], v[90:93]
	s_waitcnt lgkmcnt(0)
	v_mfma_f32_16x16x32_f16 v[78:81], v[144:147], v[184:187], v[78:81]
	v_mfma_f32_16x16x32_f16 v[74:77], v[152:155], v[184:187], v[74:77]
	s_setprio 0
	s_barrier
	s_add_i32 s40, 0, 0x14000
	s_add_i32 s14, s39, s26
	v_add_u32_e32 v200, s40, v137
	v_lshl_add_u64 v[204:205], s[18:19], 0, v[32:33]
	s_mov_b32 m0, s14
	ds_read_b128 v[188:191], v200
	ds_read_b128 v[196:199], v200 offset:2048
	ds_read_b128 v[192:195], v200 offset:1024
	ds_read_b128 v[200:203], v200 offset:3072
	global_load_lds_dwordx4 v[204:205], off
	v_lshl_add_u64 v[206:207], s[18:19], 0, v[130:131]
	s_add_i32 m0, s14, 0x2000
	s_nop 0
	global_load_lds_dwordx4 v[206:207], off
	s_barrier
	s_waitcnt lgkmcnt(2)
	s_setprio 1
	v_mfma_f32_16x16x32_f16 v[118:121], v[188:191], v[156:159], v[118:121]
	v_mfma_f32_16x16x32_f16 v[114:117], v[196:199], v[156:159], v[114:117]
	v_mfma_f32_16x16x32_f16 v[102:105], v[188:191], v[164:167], v[102:105]
	v_mfma_f32_16x16x32_f16 v[98:101], v[196:199], v[164:167], v[98:101]
	v_mfma_f32_16x16x32_f16 v[86:89], v[188:191], v[172:175], v[86:89]
	v_mfma_f32_16x16x32_f16 v[82:85], v[196:199], v[172:175], v[82:85]
	v_mfma_f32_16x16x32_f16 v[70:73], v[188:191], v[180:183], v[70:73]
	v_mfma_f32_16x16x32_f16 v[66:69], v[196:199], v[180:183], v[66:69]
	s_waitcnt lgkmcnt(0)
	v_mfma_f32_16x16x32_f16 v[118:121], v[192:195], v[160:163], v[118:121]
	v_mfma_f32_16x16x32_f16 v[114:117], v[200:203], v[160:163], v[114:117]
	v_mfma_f32_16x16x32_f16 v[102:105], v[192:195], v[168:171], v[102:105]
	v_mfma_f32_16x16x32_f16 v[98:101], v[200:203], v[168:171], v[98:101]
	v_mfma_f32_16x16x32_f16 v[86:89], v[192:195], v[176:179], v[86:89]
	v_mfma_f32_16x16x32_f16 v[82:85], v[200:203], v[176:179], v[82:85]
	v_mfma_f32_16x16x32_f16 v[70:73], v[192:195], v[184:187], v[70:73]
	v_mfma_f32_16x16x32_f16 v[66:69], v[200:203], v[184:187], v[66:69]
	s_setprio 0
	s_mov_b32 m0, s9
	v_lshl_add_u64 v[208:209], s[20:21], 0, v[32:33]
	s_barrier
	ds_read_b128 v[156:159], v139 offset:16384
	ds_read_b128 v[164:167], v139 offset:18432
	ds_read_b128 v[172:175], v139 offset:20480
	ds_read_b128 v[180:183], v139 offset:22528
	ds_read_b128 v[160:163], v139 offset:17408
	ds_read_b128 v[168:171], v139 offset:19456
	ds_read_b128 v[176:179], v139 offset:21504
	ds_read_b128 v[184:187], v139 offset:23552
	global_load_lds_dwordx4 v[208:209], off
	v_lshl_add_u64 v[210:211], s[20:21], 0, v[130:131]
	s_mov_b32 m0, s27
	s_nop 0
	global_load_lds_dwordx4 v[210:211], off
	s_barrier
	s_waitcnt lgkmcnt(4)
	s_setprio 1
	v_mfma_f32_16x16x32_f16 v[62:65], v[140:143], v[156:159], v[62:65]
	v_mfma_f32_16x16x32_f16 v[58:61], v[148:151], v[156:159], v[58:61]
	v_mfma_f32_16x16x32_f16 v[46:49], v[140:143], v[164:167], v[46:49]
	v_mfma_f32_16x16x32_f16 v[42:45], v[148:151], v[164:167], v[42:45]
	v_mfma_f32_16x16x32_f16 v[28:31], v[140:143], v[172:175], v[28:31]
	v_mfma_f32_16x16x32_f16 v[24:27], v[148:151], v[172:175], v[24:27]
	v_mfma_f32_16x16x32_f16 v[12:15], v[140:143], v[180:183], v[12:15]
	v_mfma_f32_16x16x32_f16 v[8:11], v[148:151], v[180:183], v[8:11]
	s_waitcnt lgkmcnt(0)
	v_mfma_f32_16x16x32_f16 v[62:65], v[144:147], v[160:163], v[62:65]
	v_mfma_f32_16x16x32_f16 v[58:61], v[152:155], v[160:163], v[58:61]
	v_mfma_f32_16x16x32_f16 v[46:49], v[144:147], v[168:171], v[46:49]
	v_mfma_f32_16x16x32_f16 v[42:45], v[152:155], v[168:171], v[42:45]
	v_mfma_f32_16x16x32_f16 v[28:31], v[144:147], v[176:179], v[28:31]
	v_mfma_f32_16x16x32_f16 v[24:27], v[152:155], v[176:179], v[24:27]
	v_mfma_f32_16x16x32_f16 v[12:15], v[144:147], v[184:187], v[12:15]
	v_mfma_f32_16x16x32_f16 v[8:11], v[152:155], v[184:187], v[8:11]
	s_setprio 0
	s_barrier
	s_add_u32 s14, s18, 0x40000
	s_addc_u32 s15, s19, 0
	s_add_i32 s39, s40, s26
	v_lshl_add_u64 v[140:141], s[14:15], 0, v[32:33]
	s_mov_b32 m0, s39
	s_nop 0
	global_load_lds_dwordx4 v[140:141], off
	v_lshl_add_u64 v[140:141], s[14:15], 0, v[130:131]
	s_add_i32 m0, s39, 0x2000
	s_nop 0
	global_load_lds_dwordx4 v[140:141], off
	s_waitcnt vmcnt(6)
	s_barrier
	s_setprio 1
	v_mfma_f32_16x16x32_f16 v[54:57], v[188:191], v[156:159], v[54:57]
	v_mfma_f32_16x16x32_f16 v[50:53], v[196:199], v[156:159], v[50:53]
	v_mfma_f32_16x16x32_f16 v[38:41], v[188:191], v[164:167], v[38:41]
	v_mfma_f32_16x16x32_f16 v[34:37], v[196:199], v[164:167], v[34:37]
	v_mfma_f32_16x16x32_f16 v[20:23], v[188:191], v[172:175], v[20:23]
	v_mfma_f32_16x16x32_f16 v[16:19], v[196:199], v[172:175], v[16:19]
	v_mfma_f32_16x16x32_f16 v[4:7], v[188:191], v[180:183], v[4:7]
	v_mfma_f32_16x16x32_f16 v[0:3], v[196:199], v[180:183], v[0:3]
	v_mfma_f32_16x16x32_f16 v[54:57], v[192:195], v[160:163], v[54:57]
	v_mfma_f32_16x16x32_f16 v[50:53], v[200:203], v[160:163], v[50:53]
	v_mfma_f32_16x16x32_f16 v[38:41], v[192:195], v[168:171], v[38:41]
	v_mfma_f32_16x16x32_f16 v[34:37], v[200:203], v[168:171], v[34:37]
	v_mfma_f32_16x16x32_f16 v[20:23], v[192:195], v[176:179], v[20:23]
	v_mfma_f32_16x16x32_f16 v[16:19], v[200:203], v[176:179], v[16:19]
	v_mfma_f32_16x16x32_f16 v[4:7], v[192:195], v[184:187], v[4:7]
	v_mfma_f32_16x16x32_f16 v[0:3], v[200:203], v[184:187], v[0:3]
	s_setprio 0
	s_add_i32 s39, 0, 0x18000
	v_add_u32_e32 v152, s39, v137
	s_barrier
	ds_read_b128 v[140:143], v152
	ds_read_b128 v[148:151], v152 offset:2048
	ds_read_b128 v[144:147], v152 offset:1024
	ds_read_b128 v[152:155], v152 offset:3072
	s_add_u32 s14, s20, 0x40000
	s_addc_u32 s15, s21, 0
	s_mov_b32 m0, s28
	v_lshl_add_u64 v[188:189], s[14:15], 0, v[32:33]
	ds_read_b128 v[156:159], v139 offset:32768
	ds_read_b128 v[164:167], v139 offset:34816
	ds_read_b128 v[172:175], v139 offset:36864
	ds_read_b128 v[180:183], v139 offset:38912
	ds_read_b128 v[160:163], v139 offset:33792
	ds_read_b128 v[168:171], v139 offset:35840
	ds_read_b128 v[176:179], v139 offset:37888
	ds_read_b128 v[184:187], v139 offset:39936
	global_load_lds_dwordx4 v[188:189], off
	v_lshl_add_u64 v[188:189], s[14:15], 0, v[130:131]
	s_mov_b32 m0, s29
	s_nop 0
	global_load_lds_dwordx4 v[188:189], off
	s_waitcnt lgkmcnt(8)
	s_barrier
	s_waitcnt lgkmcnt(7)
	s_setprio 1
	v_mfma_f32_16x16x32_f16 v[126:129], v[140:143], v[156:159], v[126:129]
	v_mfma_f32_16x16x32_f16 v[122:125], v[148:151], v[156:159], v[122:125]
	s_waitcnt lgkmcnt(6)
	v_mfma_f32_16x16x32_f16 v[110:113], v[140:143], v[164:167], v[110:113]
	v_mfma_f32_16x16x32_f16 v[106:109], v[148:151], v[164:167], v[106:109]
	s_waitcnt lgkmcnt(5)
	v_mfma_f32_16x16x32_f16 v[94:97], v[140:143], v[172:175], v[94:97]
	v_mfma_f32_16x16x32_f16 v[90:93], v[148:151], v[172:175], v[90:93]
	s_waitcnt lgkmcnt(4)
	v_mfma_f32_16x16x32_f16 v[78:81], v[140:143], v[180:183], v[78:81]
	v_mfma_f32_16x16x32_f16 v[74:77], v[148:151], v[180:183], v[74:77]
	s_waitcnt lgkmcnt(3)
	v_mfma_f32_16x16x32_f16 v[126:129], v[144:147], v[160:163], v[126:129]
	v_mfma_f32_16x16x32_f16 v[122:125], v[152:155], v[160:163], v[122:125]
	s_waitcnt lgkmcnt(2)
	v_mfma_f32_16x16x32_f16 v[110:113], v[144:147], v[168:171], v[110:113]
	v_mfma_f32_16x16x32_f16 v[106:109], v[152:155], v[168:171], v[106:109]
	s_waitcnt lgkmcnt(1)
	v_mfma_f32_16x16x32_f16 v[94:97], v[144:147], v[176:179], v[94:97]
	v_mfma_f32_16x16x32_f16 v[90:93], v[152:155], v[176:179], v[90:93]
	s_waitcnt lgkmcnt(0)
	v_mfma_f32_16x16x32_f16 v[78:81], v[144:147], v[184:187], v[78:81]
	v_mfma_f32_16x16x32_f16 v[74:77], v[152:155], v[184:187], v[74:77]
	s_setprio 0
	s_barrier
	s_add_i32 s20, 0, 0x1c000
	s_add_i32 s14, s39, s26
	v_add_u32_e32 v200, s20, v137
	v_lshl_add_u64 v[204:205], v[204:205], 0, s[84:85]
	s_mov_b32 m0, s14
	ds_read_b128 v[188:191], v200
	ds_read_b128 v[196:199], v200 offset:2048
	ds_read_b128 v[192:195], v200 offset:1024
	ds_read_b128 v[200:203], v200 offset:3072
	global_load_lds_dwordx4 v[204:205], off
	v_lshl_add_u64 v[204:205], v[206:207], 0, s[84:85]
	s_add_i32 m0, s14, 0x2000
	s_nop 0
	global_load_lds_dwordx4 v[204:205], off
	s_barrier
	s_waitcnt lgkmcnt(2)
	s_setprio 1
	v_mfma_f32_16x16x32_f16 v[118:121], v[188:191], v[156:159], v[118:121]
	v_mfma_f32_16x16x32_f16 v[114:117], v[196:199], v[156:159], v[114:117]
	v_mfma_f32_16x16x32_f16 v[102:105], v[188:191], v[164:167], v[102:105]
	v_mfma_f32_16x16x32_f16 v[98:101], v[196:199], v[164:167], v[98:101]
	v_mfma_f32_16x16x32_f16 v[86:89], v[188:191], v[172:175], v[86:89]
	v_mfma_f32_16x16x32_f16 v[82:85], v[196:199], v[172:175], v[82:85]
	v_mfma_f32_16x16x32_f16 v[70:73], v[188:191], v[180:183], v[70:73]
	v_mfma_f32_16x16x32_f16 v[66:69], v[196:199], v[180:183], v[66:69]
	s_waitcnt lgkmcnt(0)
	v_mfma_f32_16x16x32_f16 v[118:121], v[192:195], v[160:163], v[118:121]
	v_mfma_f32_16x16x32_f16 v[114:117], v[200:203], v[160:163], v[114:117]
	v_mfma_f32_16x16x32_f16 v[102:105], v[192:195], v[168:171], v[102:105]
	v_mfma_f32_16x16x32_f16 v[98:101], v[200:203], v[168:171], v[98:101]
	v_mfma_f32_16x16x32_f16 v[86:89], v[192:195], v[176:179], v[86:89]
	v_mfma_f32_16x16x32_f16 v[82:85], v[200:203], v[176:179], v[82:85]
	v_mfma_f32_16x16x32_f16 v[70:73], v[192:195], v[184:187], v[70:73]
	v_mfma_f32_16x16x32_f16 v[66:69], v[200:203], v[184:187], v[66:69]
	s_setprio 0
	s_mov_b32 m0, s30
	v_lshl_add_u64 v[204:205], v[208:209], 0, s[84:85]
	s_barrier
	ds_read_b128 v[156:159], v139 offset:49152
	ds_read_b128 v[164:167], v139 offset:51200
	ds_read_b128 v[172:175], v139 offset:53248
	ds_read_b128 v[180:183], v139 offset:55296
	ds_read_b128 v[160:163], v139 offset:50176
	ds_read_b128 v[168:171], v139 offset:52224
	ds_read_b128 v[176:179], v139 offset:54272
	ds_read_b128 v[184:187], v139 offset:56320
	global_load_lds_dwordx4 v[204:205], off
	v_lshl_add_u64 v[204:205], v[210:211], 0, s[84:85]
	s_mov_b32 m0, s31
	s_nop 0
	global_load_lds_dwordx4 v[204:205], off
	s_barrier
	s_waitcnt lgkmcnt(4)
	s_setprio 1
	v_mfma_f32_16x16x32_f16 v[62:65], v[140:143], v[156:159], v[62:65]
	v_mfma_f32_16x16x32_f16 v[58:61], v[148:151], v[156:159], v[58:61]
	v_mfma_f32_16x16x32_f16 v[46:49], v[140:143], v[164:167], v[46:49]
	v_mfma_f32_16x16x32_f16 v[42:45], v[148:151], v[164:167], v[42:45]
	v_mfma_f32_16x16x32_f16 v[28:31], v[140:143], v[172:175], v[28:31]
	v_mfma_f32_16x16x32_f16 v[24:27], v[148:151], v[172:175], v[24:27]
	v_mfma_f32_16x16x32_f16 v[12:15], v[140:143], v[180:183], v[12:15]
	v_mfma_f32_16x16x32_f16 v[8:11], v[148:151], v[180:183], v[8:11]
	s_waitcnt lgkmcnt(0)
	v_mfma_f32_16x16x32_f16 v[62:65], v[144:147], v[160:163], v[62:65]
	v_mfma_f32_16x16x32_f16 v[58:61], v[152:155], v[160:163], v[58:61]
	v_mfma_f32_16x16x32_f16 v[46:49], v[144:147], v[168:171], v[46:49]
	v_mfma_f32_16x16x32_f16 v[42:45], v[152:155], v[168:171], v[42:45]
	v_mfma_f32_16x16x32_f16 v[28:31], v[144:147], v[176:179], v[28:31]
	v_mfma_f32_16x16x32_f16 v[24:27], v[152:155], v[176:179], v[24:27]
	v_mfma_f32_16x16x32_f16 v[12:15], v[144:147], v[184:187], v[12:15]
	v_mfma_f32_16x16x32_f16 v[8:11], v[152:155], v[184:187], v[8:11]
	s_setprio 0
	s_barrier
	s_add_u32 s14, s18, 0x40080
	s_addc_u32 s15, s19, 0
	s_add_i32 s18, s20, s26
	v_lshl_add_u64 v[140:141], s[14:15], 0, v[32:33]
	s_mov_b32 m0, s18
	s_nop 0
	global_load_lds_dwordx4 v[140:141], off
	v_lshl_add_u64 v[140:141], s[14:15], 0, v[130:131]
	s_add_i32 m0, s18, 0x2000
	s_nop 0
	global_load_lds_dwordx4 v[140:141], off
	s_waitcnt vmcnt(6)
	s_barrier
	s_setprio 1
	v_mfma_f32_16x16x32_f16 v[54:57], v[188:191], v[156:159], v[54:57]
	v_mfma_f32_16x16x32_f16 v[50:53], v[196:199], v[156:159], v[50:53]
	v_mfma_f32_16x16x32_f16 v[38:41], v[188:191], v[164:167], v[38:41]
	v_mfma_f32_16x16x32_f16 v[34:37], v[196:199], v[164:167], v[34:37]
	v_mfma_f32_16x16x32_f16 v[20:23], v[188:191], v[172:175], v[20:23]
	v_mfma_f32_16x16x32_f16 v[16:19], v[196:199], v[172:175], v[16:19]
	v_mfma_f32_16x16x32_f16 v[4:7], v[188:191], v[180:183], v[4:7]
	v_mfma_f32_16x16x32_f16 v[0:3], v[196:199], v[180:183], v[0:3]
	v_mfma_f32_16x16x32_f16 v[54:57], v[192:195], v[160:163], v[54:57]
	v_mfma_f32_16x16x32_f16 v[50:53], v[200:203], v[160:163], v[50:53]
	v_mfma_f32_16x16x32_f16 v[38:41], v[192:195], v[168:171], v[38:41]
	v_mfma_f32_16x16x32_f16 v[34:37], v[200:203], v[168:171], v[34:37]
	v_mfma_f32_16x16x32_f16 v[20:23], v[192:195], v[176:179], v[20:23]
	v_mfma_f32_16x16x32_f16 v[16:19], v[200:203], v[176:179], v[16:19]
	v_mfma_f32_16x16x32_f16 v[4:7], v[192:195], v[184:187], v[4:7]
	v_mfma_f32_16x16x32_f16 v[0:3], v[200:203], v[184:187], v[0:3]
	s_setprio 0
	s_add_i32 s38, s38, 2
	s_add_u32 s3, s3, 0x100
	s_addc_u32 s37, s37, 0
	s_cmp_gt_u32 s38, 13
	s_mov_b64 s[14:15], s[16:17]
	s_barrier
	s_cbranch_scc0 .LBB0_1276
	v_mul_f32_e32 v144, 0xbfb8aa3b, v127
	v_mul_f32_e32 v141, 0xbfb8aa3b, v126
	v_exp_f32_e32 v145, v144
	v_mul_f32_e32 v144, 0xbfb8aa3b, v128
	v_exp_f32_e32 v141, v141
	v_exp_f32_e32 v146, v144
	v_mul_f32_e32 v144, 0xbfb8aa3b, v129
	v_exp_f32_e32 v147, v144
	v_mul_f32_e32 v144, 0xbfb8aa3b, v122
	v_exp_f32_e32 v148, v144
	v_mul_f32_e32 v144, 0xbfb8aa3b, v123
	v_exp_f32_e32 v149, v144
	v_mul_f32_e32 v144, 0xbfb8aa3b, v124
	v_exp_f32_e32 v150, v144
	v_mul_f32_e32 v144, 0xbfb8aa3b, v125
	v_add_f32_e32 v141, 1.0, v141
	v_exp_f32_e32 v151, v144
	v_rcp_f32_e32 v144, v141
	v_add_f32_e32 v141, 1.0, v145
	v_rcp_f32_e32 v145, v141
	v_add_f32_e32 v141, 1.0, v146
	v_rcp_f32_e32 v146, v141
	v_add_f32_e32 v141, 1.0, v147
	v_rcp_f32_e32 v147, v141
	v_add_f32_e32 v141, 1.0, v148
	v_rcp_f32_e32 v148, v141
	v_add_f32_e32 v141, 1.0, v149
	v_rcp_f32_e32 v149, v141
	v_add_f32_e32 v141, 1.0, v150
	v_rcp_f32_e32 v150, v141
	v_add_f32_e32 v141, 1.0, v151
	v_pk_mul_f32 v[126:127], v[126:127], v[144:145]
	v_rcp_f32_e32 v151, v141
	v_pk_mul_f32 v[118:119], v[126:127], v[118:119]
	v_pk_mul_f32 v[126:127], v[128:129], v[146:147]
	v_cvt_pk_f16_f32 v118, v118, v119
	v_pk_mul_f32 v[120:121], v[126:127], v[120:121]
	v_lshl_or_b32 v142, s36, 7, v138
	v_cvt_pk_f16_f32 v119, v120, v121
	v_pk_mul_f32 v[120:121], v[122:123], v[148:149]
	v_lshl_add_u32 v140, s8, 8, v136
	v_pk_mul_f32 v[114:115], v[120:121], v[114:115]
	v_ashrrev_i32_e32 v143, 31, v142
	v_cvt_pk_f16_f32 v120, v114, v115
	v_pk_mul_f32 v[114:115], v[124:125], v[150:151]
	s_movk_i32 s3, 0x1600
	v_pk_mul_f32 v[114:115], v[114:115], v[116:117]
	v_lshlrev_b64 v[116:117], 1, v[142:143]
	v_cvt_pk_f16_f32 v121, v114, v115
	v_mov_b64_e32 v[114:115], s[92:93]
	v_mad_i64_i32 v[122:123], s[10:11], v140, s3, v[114:115]
	v_lshl_add_u64 v[122:123], v[122:123], 0, v[116:117]
	global_store_dwordx4 v[122:123], v[118:121], off
	v_mul_f32_e32 v122, 0xbfb8aa3b, v106
	v_mul_f32_e32 v123, 0xbfb8aa3b, v107
	v_mul_f32_e32 v118, 0xbfb8aa3b, v110
	v_mul_f32_e32 v119, 0xbfb8aa3b, v111
	v_exp_f32_e32 v118, v118
	v_exp_f32_e32 v119, v119
	v_mul_f32_e32 v120, 0xbfb8aa3b, v112
	v_mul_f32_e32 v121, 0xbfb8aa3b, v113
	v_exp_f32_e32 v120, v120
	v_exp_f32_e32 v121, v121
	v_exp_f32_e32 v122, v122
	v_exp_f32_e32 v123, v123
	v_mul_f32_e32 v124, 0xbfb8aa3b, v108
	v_mul_f32_e32 v125, 0xbfb8aa3b, v109
	v_add_f32_e32 v118, 1.0, v118
	v_add_f32_e32 v119, 1.0, v119
	v_exp_f32_e32 v124, v124
	v_exp_f32_e32 v125, v125
	v_rcp_f32_e32 v118, v118
	v_rcp_f32_e32 v119, v119
	v_add_f32_e32 v120, 1.0, v120
	v_add_f32_e32 v121, 1.0, v121
	v_rcp_f32_e32 v120, v120
	v_rcp_f32_e32 v121, v121
	v_add_f32_e32 v122, 1.0, v122
	v_add_f32_e32 v123, 1.0, v123
	v_rcp_f32_e32 v122, v122
	v_rcp_f32_e32 v123, v123
	v_add_f32_e32 v124, 1.0, v124
	v_add_f32_e32 v125, 1.0, v125
	v_pk_mul_f32 v[110:111], v[110:111], v[118:119]
	v_rcp_f32_e32 v124, v124
	v_rcp_f32_e32 v125, v125
	v_pk_mul_f32 v[102:103], v[110:111], v[102:103]
	v_pk_mul_f32 v[110:111], v[112:113], v[120:121]
	v_cvt_pk_f16_f32 v102, v102, v103
	v_pk_mul_f32 v[104:105], v[110:111], v[104:105]
	s_and_b64 vcc, exec, s[0:1]
	v_cvt_pk_f16_f32 v103, v104, v105
	v_pk_mul_f32 v[104:105], v[106:107], v[122:123]
	s_mov_b32 s36, s35
	v_pk_mul_f32 v[98:99], v[104:105], v[98:99]
	s_mov_b32 s8, s2
	v_cvt_pk_f16_f32 v104, v98, v99
	v_pk_mul_f32 v[98:99], v[108:109], v[124:125]
	s_mov_b64 s[16:17], s[6:7]
	v_pk_mul_f32 v[98:99], v[98:99], v[100:101]
	v_mul_f32_e32 v100, 0xbfb8aa3b, v96
	v_cvt_pk_f16_f32 v105, v98, v99
	v_or_b32_e32 v98, 16, v140
	v_mad_i64_i32 v[98:99], s[10:11], v98, s3, v[114:115]
	v_lshl_add_u64 v[98:99], v[98:99], 0, v[116:117]
	global_store_dwordx4 v[98:99], v[102:105], off
	v_mul_f32_e32 v98, 0xbfb8aa3b, v94
	v_mul_f32_e32 v99, 0xbfb8aa3b, v95
	v_exp_f32_e32 v98, v98
	v_exp_f32_e32 v99, v99
	v_mul_f32_e32 v101, 0xbfb8aa3b, v97
	v_exp_f32_e32 v100, v100
	v_exp_f32_e32 v101, v101
	v_mul_f32_e32 v102, 0xbfb8aa3b, v90
	v_mul_f32_e32 v103, 0xbfb8aa3b, v91
	v_exp_f32_e32 v102, v102
	v_exp_f32_e32 v103, v103
	v_mul_f32_e32 v104, 0xbfb8aa3b, v92
	v_mul_f32_e32 v105, 0xbfb8aa3b, v93
	v_add_f32_e32 v98, 1.0, v98
	v_add_f32_e32 v99, 1.0, v99
	v_exp_f32_e32 v104, v104
	v_exp_f32_e32 v105, v105
	v_rcp_f32_e32 v98, v98
	v_rcp_f32_e32 v99, v99
	v_add_f32_e32 v100, 1.0, v100
	v_add_f32_e32 v101, 1.0, v101
	v_rcp_f32_e32 v100, v100
	v_rcp_f32_e32 v101, v101
	v_add_f32_e32 v102, 1.0, v102
	v_add_f32_e32 v103, 1.0, v103
	v_rcp_f32_e32 v102, v102
	v_rcp_f32_e32 v103, v103
	v_add_f32_e32 v104, 1.0, v104
	v_add_f32_e32 v105, 1.0, v105
	v_pk_mul_f32 v[94:95], v[94:95], v[98:99]
	v_rcp_f32_e32 v104, v104
	v_rcp_f32_e32 v105, v105
	v_pk_mul_f32 v[86:87], v[94:95], v[86:87]
	v_pk_mul_f32 v[94:95], v[96:97], v[100:101]
	v_cvt_pk_f16_f32 v86, v86, v87
	v_pk_mul_f32 v[88:89], v[94:95], v[88:89]
	s_mov_b64 s[14:15], s[4:5]
	v_cvt_pk_f16_f32 v87, v88, v89
	v_pk_mul_f32 v[88:89], v[90:91], v[102:103]
	s_nop 0
	v_pk_mul_f32 v[82:83], v[88:89], v[82:83]
	s_nop 0
	v_cvt_pk_f16_f32 v88, v82, v83
	v_pk_mul_f32 v[82:83], v[92:93], v[104:105]
	s_nop 0
	v_pk_mul_f32 v[82:83], v[82:83], v[84:85]
	v_mul_f32_e32 v84, 0xbfb8aa3b, v80
	v_cvt_pk_f16_f32 v89, v82, v83
	v_or_b32_e32 v82, 32, v140
	v_mad_i64_i32 v[82:83], s[10:11], v82, s3, v[114:115]
	v_lshl_add_u64 v[82:83], v[82:83], 0, v[116:117]
	global_store_dwordx4 v[82:83], v[86:89], off
	v_mul_f32_e32 v82, 0xbfb8aa3b, v78
	v_mul_f32_e32 v83, 0xbfb8aa3b, v79
	v_exp_f32_e32 v82, v82
	v_exp_f32_e32 v83, v83
	v_mul_f32_e32 v85, 0xbfb8aa3b, v81
	v_exp_f32_e32 v84, v84
	v_exp_f32_e32 v85, v85
	v_mul_f32_e32 v86, 0xbfb8aa3b, v74
	v_mul_f32_e32 v87, 0xbfb8aa3b, v75
	v_exp_f32_e32 v86, v86
	v_exp_f32_e32 v87, v87
	v_mul_f32_e32 v88, 0xbfb8aa3b, v76
	v_mul_f32_e32 v89, 0xbfb8aa3b, v77
	v_add_f32_e32 v82, 1.0, v82
	v_add_f32_e32 v83, 1.0, v83
	v_exp_f32_e32 v88, v88
	v_exp_f32_e32 v89, v89
	v_rcp_f32_e32 v82, v82
	v_rcp_f32_e32 v83, v83
	v_add_f32_e32 v84, 1.0, v84
	v_add_f32_e32 v85, 1.0, v85
	v_rcp_f32_e32 v84, v84
	v_rcp_f32_e32 v85, v85
	v_add_f32_e32 v86, 1.0, v86
	v_add_f32_e32 v87, 1.0, v87
	v_rcp_f32_e32 v86, v86
	v_rcp_f32_e32 v87, v87
	v_add_f32_e32 v88, 1.0, v88
	v_add_f32_e32 v89, 1.0, v89
	v_pk_mul_f32 v[78:79], v[78:79], v[82:83]
	v_rcp_f32_e32 v88, v88
	v_rcp_f32_e32 v89, v89
	v_pk_mul_f32 v[70:71], v[78:79], v[70:71]
	v_pk_mul_f32 v[78:79], v[80:81], v[84:85]
	v_cvt_pk_f16_f32 v70, v70, v71
	v_pk_mul_f32 v[72:73], v[78:79], v[72:73]
	s_nop 0
	v_cvt_pk_f16_f32 v71, v72, v73
	v_pk_mul_f32 v[72:73], v[74:75], v[86:87]
	v_add_u32_e32 v74, 0x80, v140
	v_pk_mul_f32 v[66:67], v[72:73], v[66:67]
	s_nop 0
	v_cvt_pk_f16_f32 v72, v66, v67
	v_pk_mul_f32 v[66:67], v[76:77], v[88:89]
	s_nop 0
	v_pk_mul_f32 v[66:67], v[66:67], v[68:69]
	v_mul_f32_e32 v68, 0xbfb8aa3b, v64
	v_cvt_pk_f16_f32 v73, v66, v67
	v_or_b32_e32 v66, 48, v140
	v_mad_i64_i32 v[66:67], s[10:11], v66, s3, v[114:115]
	v_lshl_add_u64 v[66:67], v[66:67], 0, v[116:117]
	global_store_dwordx4 v[66:67], v[70:73], off
	v_mul_f32_e32 v66, 0xbfb8aa3b, v62
	v_mul_f32_e32 v67, 0xbfb8aa3b, v63
	v_exp_f32_e32 v66, v66
	v_exp_f32_e32 v67, v67
	v_mul_f32_e32 v69, 0xbfb8aa3b, v65
	v_exp_f32_e32 v68, v68
	v_exp_f32_e32 v69, v69
	v_mul_f32_e32 v70, 0xbfb8aa3b, v58
	v_mul_f32_e32 v71, 0xbfb8aa3b, v59
	v_exp_f32_e32 v70, v70
	v_exp_f32_e32 v71, v71
	v_mul_f32_e32 v72, 0xbfb8aa3b, v60
	v_mul_f32_e32 v73, 0xbfb8aa3b, v61
	v_add_f32_e32 v66, 1.0, v66
	v_add_f32_e32 v67, 1.0, v67
	v_exp_f32_e32 v72, v72
	v_exp_f32_e32 v73, v73
	v_rcp_f32_e32 v66, v66
	v_rcp_f32_e32 v67, v67
	v_add_f32_e32 v68, 1.0, v68
	v_add_f32_e32 v69, 1.0, v69
	v_rcp_f32_e32 v68, v68
	v_rcp_f32_e32 v69, v69
	v_add_f32_e32 v70, 1.0, v70
	v_add_f32_e32 v71, 1.0, v71
	v_rcp_f32_e32 v70, v70
	v_rcp_f32_e32 v71, v71
	v_add_f32_e32 v72, 1.0, v72
	v_add_f32_e32 v73, 1.0, v73
	v_pk_mul_f32 v[62:63], v[62:63], v[66:67]
	v_rcp_f32_e32 v72, v72
	v_rcp_f32_e32 v73, v73
	v_pk_mul_f32 v[54:55], v[62:63], v[54:55]
	v_pk_mul_f32 v[62:63], v[64:65], v[68:69]
	v_cvt_pk_f16_f32 v54, v54, v55
	v_pk_mul_f32 v[56:57], v[62:63], v[56:57]
	s_nop 0
	v_cvt_pk_f16_f32 v55, v56, v57
	v_pk_mul_f32 v[56:57], v[58:59], v[70:71]
	s_nop 0
	v_pk_mul_f32 v[50:51], v[56:57], v[50:51]
	s_nop 0
	v_cvt_pk_f16_f32 v56, v50, v51
	v_pk_mul_f32 v[50:51], v[60:61], v[72:73]
	s_nop 0
	v_pk_mul_f32 v[50:51], v[50:51], v[52:53]
	v_mul_f32_e32 v52, 0xbfb8aa3b, v48
	v_cvt_pk_f16_f32 v57, v50, v51
	v_mad_i64_i32 v[50:51], s[10:11], v74, s3, v[114:115]
	v_lshl_add_u64 v[50:51], v[50:51], 0, v[116:117]
	global_store_dwordx4 v[50:51], v[54:57], off
	v_mul_f32_e32 v50, 0xbfb8aa3b, v46
	v_mul_f32_e32 v51, 0xbfb8aa3b, v47
	v_exp_f32_e32 v50, v50
	v_exp_f32_e32 v51, v51
	v_mul_f32_e32 v53, 0xbfb8aa3b, v49
	v_exp_f32_e32 v52, v52
	v_exp_f32_e32 v53, v53
	v_mul_f32_e32 v54, 0xbfb8aa3b, v42
	v_mul_f32_e32 v55, 0xbfb8aa3b, v43
	v_exp_f32_e32 v54, v54
	v_exp_f32_e32 v55, v55
	v_mul_f32_e32 v56, 0xbfb8aa3b, v44
	v_mul_f32_e32 v57, 0xbfb8aa3b, v45
	v_add_f32_e32 v50, 1.0, v50
	v_add_f32_e32 v51, 1.0, v51
	v_exp_f32_e32 v56, v56
	v_exp_f32_e32 v57, v57
	v_rcp_f32_e32 v50, v50
	v_rcp_f32_e32 v51, v51
	v_add_f32_e32 v52, 1.0, v52
	v_add_f32_e32 v53, 1.0, v53
	v_rcp_f32_e32 v52, v52
	v_rcp_f32_e32 v53, v53
	v_add_f32_e32 v54, 1.0, v54
	v_add_f32_e32 v55, 1.0, v55
	v_rcp_f32_e32 v54, v54
	v_rcp_f32_e32 v55, v55
	v_add_f32_e32 v56, 1.0, v56
	v_add_f32_e32 v57, 1.0, v57
	v_pk_mul_f32 v[46:47], v[46:47], v[50:51]
	v_rcp_f32_e32 v56, v56
	v_rcp_f32_e32 v57, v57
	v_pk_mul_f32 v[38:39], v[46:47], v[38:39]
	v_pk_mul_f32 v[46:47], v[48:49], v[52:53]
	v_cvt_pk_f16_f32 v38, v38, v39
	v_pk_mul_f32 v[40:41], v[46:47], v[40:41]
	s_nop 0
	v_cvt_pk_f16_f32 v39, v40, v41
	v_pk_mul_f32 v[40:41], v[42:43], v[54:55]
	s_nop 0
	v_pk_mul_f32 v[34:35], v[40:41], v[34:35]
	s_nop 0
	v_cvt_pk_f16_f32 v40, v34, v35
	v_pk_mul_f32 v[34:35], v[44:45], v[56:57]
	s_nop 0
	v_pk_mul_f32 v[34:35], v[34:35], v[36:37]
	v_mul_f32_e32 v36, 0xbfb8aa3b, v30
	v_cvt_pk_f16_f32 v41, v34, v35
	v_add_u32_e32 v34, 0x90, v140
	v_mad_i64_i32 v[34:35], s[10:11], v34, s3, v[114:115]
	v_lshl_add_u64 v[34:35], v[34:35], 0, v[116:117]
	global_store_dwordx4 v[34:35], v[38:41], off
	v_mul_f32_e32 v34, 0xbfb8aa3b, v28
	v_mul_f32_e32 v35, 0xbfb8aa3b, v29
	v_exp_f32_e32 v34, v34
	v_exp_f32_e32 v35, v35
	v_mul_f32_e32 v37, 0xbfb8aa3b, v31
	v_exp_f32_e32 v36, v36
	v_exp_f32_e32 v37, v37
	v_mul_f32_e32 v38, 0xbfb8aa3b, v24
	v_mul_f32_e32 v39, 0xbfb8aa3b, v25
	v_exp_f32_e32 v38, v38
	v_exp_f32_e32 v39, v39
	v_mul_f32_e32 v40, 0xbfb8aa3b, v26
	v_mul_f32_e32 v41, 0xbfb8aa3b, v27
	v_add_f32_e32 v34, 1.0, v34
	v_add_f32_e32 v35, 1.0, v35
	v_exp_f32_e32 v40, v40
	v_exp_f32_e32 v41, v41
	v_rcp_f32_e32 v34, v34
	v_rcp_f32_e32 v35, v35
	v_add_f32_e32 v36, 1.0, v36
	v_add_f32_e32 v37, 1.0, v37
	v_rcp_f32_e32 v36, v36
	v_rcp_f32_e32 v37, v37
	v_add_f32_e32 v38, 1.0, v38
	v_add_f32_e32 v39, 1.0, v39
	v_rcp_f32_e32 v38, v38
	v_rcp_f32_e32 v39, v39
	v_add_f32_e32 v40, 1.0, v40
	v_add_f32_e32 v41, 1.0, v41
	v_pk_mul_f32 v[28:29], v[28:29], v[34:35]
	v_rcp_f32_e32 v40, v40
	v_rcp_f32_e32 v41, v41
	v_pk_mul_f32 v[20:21], v[28:29], v[20:21]
	v_pk_mul_f32 v[28:29], v[30:31], v[36:37]
	v_cvt_pk_f16_f32 v20, v20, v21
	v_pk_mul_f32 v[22:23], v[28:29], v[22:23]
	s_nop 0
	v_cvt_pk_f16_f32 v21, v22, v23
	v_pk_mul_f32 v[22:23], v[24:25], v[38:39]
	s_nop 0
	v_pk_mul_f32 v[16:17], v[22:23], v[16:17]
	s_nop 0
	v_cvt_pk_f16_f32 v22, v16, v17
	v_pk_mul_f32 v[16:17], v[26:27], v[40:41]
	s_nop 0
	v_pk_mul_f32 v[16:17], v[16:17], v[18:19]
	v_mul_f32_e32 v18, 0xbfb8aa3b, v14
	v_cvt_pk_f16_f32 v23, v16, v17
	v_add_u32_e32 v16, 0xa0, v140
	v_mad_i64_i32 v[16:17], s[10:11], v16, s3, v[114:115]
	v_lshl_add_u64 v[16:17], v[16:17], 0, v[116:117]
	global_store_dwordx4 v[16:17], v[20:23], off
	v_mul_f32_e32 v16, 0xbfb8aa3b, v12
	v_mul_f32_e32 v17, 0xbfb8aa3b, v13
	v_exp_f32_e32 v16, v16
	v_exp_f32_e32 v17, v17
	v_mul_f32_e32 v19, 0xbfb8aa3b, v15
	v_exp_f32_e32 v18, v18
	v_exp_f32_e32 v19, v19
	v_mul_f32_e32 v20, 0xbfb8aa3b, v8
	v_mul_f32_e32 v21, 0xbfb8aa3b, v9
	v_exp_f32_e32 v20, v20
	v_exp_f32_e32 v21, v21
	v_mul_f32_e32 v22, 0xbfb8aa3b, v10
	v_mul_f32_e32 v23, 0xbfb8aa3b, v11
	v_add_f32_e32 v16, 1.0, v16
	v_add_f32_e32 v17, 1.0, v17
	v_exp_f32_e32 v22, v22
	v_exp_f32_e32 v23, v23
	v_rcp_f32_e32 v16, v16
	v_rcp_f32_e32 v17, v17
	v_add_f32_e32 v18, 1.0, v18
	v_add_f32_e32 v19, 1.0, v19
	v_rcp_f32_e32 v18, v18
	v_rcp_f32_e32 v19, v19
	v_add_f32_e32 v20, 1.0, v20
	v_add_f32_e32 v21, 1.0, v21
	v_rcp_f32_e32 v20, v20
	v_rcp_f32_e32 v21, v21
	v_add_f32_e32 v22, 1.0, v22
	v_add_f32_e32 v23, 1.0, v23
	v_pk_mul_f32 v[12:13], v[12:13], v[16:17]
	v_rcp_f32_e32 v22, v22
	v_rcp_f32_e32 v23, v23
	v_pk_mul_f32 v[4:5], v[12:13], v[4:5]
	v_pk_mul_f32 v[12:13], v[14:15], v[18:19]
	v_cvt_pk_f16_f32 v4, v4, v5
	v_pk_mul_f32 v[6:7], v[12:13], v[6:7]
	s_nop 0
	v_cvt_pk_f16_f32 v5, v6, v7
	v_pk_mul_f32 v[6:7], v[8:9], v[20:21]
	s_nop 0
	v_pk_mul_f32 v[0:1], v[6:7], v[0:1]
	s_nop 0
	v_cvt_pk_f16_f32 v6, v0, v1
	v_pk_mul_f32 v[0:1], v[10:11], v[22:23]
	s_nop 0
	v_pk_mul_f32 v[0:1], v[0:1], v[2:3]
	s_nop 0
	v_cvt_pk_f16_f32 v7, v0, v1
	v_add_u32_e32 v0, 0xb0, v140
	v_mad_i64_i32 v[0:1], s[10:11], v0, s3, v[114:115]
	v_lshl_add_u64 v[0:1], v[0:1], 0, v[116:117]
	global_store_dwordx4 v[0:1], v[4:7], off
	s_cmp_lg_u32 s34, 1
	s_cbranch_scc1 .Lups_skip
	s_and_b32 s0, s91, 63
	s_cmp_gt_u32 s0, 5
	s_cbranch_scc1 .Lups_skip
	s_cmp_gt_u32 s91, 196
	s_cbranch_scc1 .Lups_skip
	s_waitcnt vmcnt(0)
	s_barrier
	v_readlane_b32 s0, v251, 36
	s_cmp_lg_u32 s0, 0
	s_cbranch_scc1 .Lups_skip
	buffer_wbl2 sc1
	s_waitcnt vmcnt(0)
	v_readlane_b32 s2, v255, 45
	v_readlane_b32 s3, v254, 25
	s_lshl_b32 s2, s2, 1
	s_cmp_eq_u32 s3, 0
	s_cselect_b32 s3, 1, 0
	s_add_i32 s2, s2, s3
	s_lshl_b32 s2, s2, 2
	s_add_i32 s2, s2, 14016
	v_readlane_b32 s0, v251, 32
	v_readlane_b32 s1, v251, 33
	s_add_u32 s0, s0, s2
	s_addc_u32 s1, s1, 0
	s_mov_b64 s[2:3], exec
	s_mov_b64 exec, 1
	global_atomic_add v33, v248, s[0:1]
	s_mov_b64 exec, s[2:3]

.LBB0_1365:
	s_add_i32 s46, s14, 2
	s_add_u32 s12, s10, 0x100
	s_addc_u32 s13, s11, 0
	s_add_i32 s47, 0, 0x10000
	v_add_u32_e32 v134, s47, v230
	ds_read_b128 v[106:109], v134
	ds_read_b128 v[114:117], v134 offset:2048
	ds_read_b128 v[110:113], v134 offset:1024
	ds_read_b128 v[134:137], v134 offset:3072
	s_cmp_eq_u32 s43, s14
	s_cselect_b32 s14, s8, s44
	s_cselect_b32 s17, s7, s13
	s_cselect_b32 s16, s6, s12
	s_cselect_b32 s15, s9, s45
	v_lshl_add_u64 v[178:179], s[10:11], 0, v[184:185]
	s_add_i32 m0, s24, 0xc000
	ds_read_b128 v[138:141], v232
	ds_read_b128 v[154:157], v232 offset:2048
	ds_read_b128 v[162:165], v232 offset:4096
	ds_read_b128 v[170:173], v232 offset:6144
	ds_read_b128 v[150:153], v232 offset:1024
	ds_read_b128 v[158:161], v232 offset:3072
	ds_read_b128 v[166:169], v232 offset:5120
	ds_read_b128 v[174:177], v232 offset:7168
	global_load_lds_dwordx4 v[178:179], off
	v_lshl_add_u64 v[178:179], s[10:11], 0, v[186:187]
	s_add_i32 m0, s24, 0xe000
	s_nop 0
	global_load_lds_dwordx4 v[178:179], off
	s_waitcnt lgkmcnt(8)
	s_barrier
	s_waitcnt lgkmcnt(7)
	s_setprio 1
	v_mfma_f32_16x16x32_f16 v[146:149], v[106:109], v[138:141], v[146:149]
	v_mfma_f32_16x16x32_f16 v[142:145], v[114:117], v[138:141], v[142:145]
	s_waitcnt lgkmcnt(6)
	v_mfma_f32_16x16x32_f16 v[130:133], v[106:109], v[154:157], v[130:133]
	v_mfma_f32_16x16x32_f16 v[122:125], v[114:117], v[154:157], v[122:125]
	s_waitcnt lgkmcnt(5)
	v_mfma_f32_16x16x32_f16 v[94:97], v[106:109], v[162:165], v[94:97]
	v_mfma_f32_16x16x32_f16 v[90:93], v[114:117], v[162:165], v[90:93]
	s_waitcnt lgkmcnt(4)
	v_mfma_f32_16x16x32_f16 v[78:81], v[106:109], v[170:173], v[78:81]
	v_mfma_f32_16x16x32_f16 v[74:77], v[114:117], v[170:173], v[74:77]
	s_waitcnt lgkmcnt(3)
	v_mfma_f32_16x16x32_f16 v[146:149], v[110:113], v[150:153], v[146:149]
	v_mfma_f32_16x16x32_f16 v[142:145], v[134:137], v[150:153], v[142:145]
	s_waitcnt lgkmcnt(2)
	v_mfma_f32_16x16x32_f16 v[130:133], v[110:113], v[158:161], v[130:133]
	v_mfma_f32_16x16x32_f16 v[122:125], v[134:137], v[158:161], v[122:125]
	s_waitcnt lgkmcnt(1)
	v_mfma_f32_16x16x32_f16 v[94:97], v[110:113], v[166:169], v[94:97]
	v_mfma_f32_16x16x32_f16 v[90:93], v[134:137], v[166:169], v[90:93]
	s_waitcnt lgkmcnt(0)
	v_mfma_f32_16x16x32_f16 v[78:81], v[110:113], v[174:177], v[78:81]
	v_mfma_f32_16x16x32_f16 v[74:77], v[134:137], v[174:177], v[74:77]
	s_setprio 0
	s_barrier
	s_add_i32 s48, 0, 0x14000
	s_add_i32 s10, s47, s23
	v_add_u32_e32 v196, s48, v230
	v_lshl_add_u64 v[200:201], s[14:15], 0, v[32:33]
	s_mov_b32 m0, s10
	ds_read_b128 v[178:181], v196
	ds_read_b128 v[192:195], v196 offset:2048
	ds_read_b128 v[188:191], v196 offset:1024
	ds_read_b128 v[196:199], v196 offset:3072
	global_load_lds_dwordx4 v[200:201], off
	v_lshl_add_u64 v[202:203], s[14:15], 0, v[182:183]
	s_add_i32 m0, s10, 0x2000
	s_nop 0
	global_load_lds_dwordx4 v[202:203], off
	s_barrier
	s_waitcnt lgkmcnt(2)
	s_setprio 1
	v_mfma_f32_16x16x32_f16 v[126:129], v[178:181], v[138:141], v[126:129]
	v_mfma_f32_16x16x32_f16 v[118:121], v[192:195], v[138:141], v[118:121]
	v_mfma_f32_16x16x32_f16 v[102:105], v[178:181], v[154:157], v[102:105]
	v_mfma_f32_16x16x32_f16 v[98:101], v[192:195], v[154:157], v[98:101]
	v_mfma_f32_16x16x32_f16 v[86:89], v[178:181], v[162:165], v[86:89]
	v_mfma_f32_16x16x32_f16 v[82:85], v[192:195], v[162:165], v[82:85]
	v_mfma_f32_16x16x32_f16 v[70:73], v[178:181], v[170:173], v[70:73]
	v_mfma_f32_16x16x32_f16 v[66:69], v[192:195], v[170:173], v[66:69]
	s_waitcnt lgkmcnt(0)
	v_mfma_f32_16x16x32_f16 v[126:129], v[188:191], v[150:153], v[126:129]
	v_mfma_f32_16x16x32_f16 v[118:121], v[196:199], v[150:153], v[118:121]
	v_mfma_f32_16x16x32_f16 v[102:105], v[188:191], v[158:161], v[102:105]
	v_mfma_f32_16x16x32_f16 v[98:101], v[196:199], v[158:161], v[98:101]
	v_mfma_f32_16x16x32_f16 v[86:89], v[188:191], v[166:169], v[86:89]
	v_mfma_f32_16x16x32_f16 v[82:85], v[196:199], v[166:169], v[82:85]
	v_mfma_f32_16x16x32_f16 v[70:73], v[188:191], v[174:177], v[70:73]
	v_mfma_f32_16x16x32_f16 v[66:69], v[196:199], v[174:177], v[66:69]
	s_setprio 0
	s_mov_b32 m0, s24
	v_lshl_add_u64 v[204:205], s[16:17], 0, v[32:33]
	s_barrier
	ds_read_b128 v[138:141], v232 offset:16384
	ds_read_b128 v[154:157], v232 offset:18432
	ds_read_b128 v[162:165], v232 offset:20480
	ds_read_b128 v[170:173], v232 offset:22528
	ds_read_b128 v[150:153], v232 offset:17408
	ds_read_b128 v[158:161], v232 offset:19456
	ds_read_b128 v[166:169], v232 offset:21504
	ds_read_b128 v[174:177], v232 offset:23552
	global_load_lds_dwordx4 v[204:205], off
	v_lshl_add_u64 v[206:207], s[16:17], 0, v[182:183]
	s_mov_b32 m0, s25
	s_nop 0
	global_load_lds_dwordx4 v[206:207], off
	s_barrier
	s_waitcnt lgkmcnt(4)
	s_setprio 1
	v_mfma_f32_16x16x32_f16 v[62:65], v[106:109], v[138:141], v[62:65]
	v_mfma_f32_16x16x32_f16 v[58:61], v[114:117], v[138:141], v[58:61]
	v_mfma_f32_16x16x32_f16 v[46:49], v[106:109], v[154:157], v[46:49]
	v_mfma_f32_16x16x32_f16 v[42:45], v[114:117], v[154:157], v[42:45]
	v_mfma_f32_16x16x32_f16 v[28:31], v[106:109], v[162:165], v[28:31]
	v_mfma_f32_16x16x32_f16 v[24:27], v[114:117], v[162:165], v[24:27]
	v_mfma_f32_16x16x32_f16 v[12:15], v[106:109], v[170:173], v[12:15]
	v_mfma_f32_16x16x32_f16 v[8:11], v[114:117], v[170:173], v[8:11]
	s_waitcnt lgkmcnt(0)
	v_mfma_f32_16x16x32_f16 v[62:65], v[110:113], v[150:153], v[62:65]
	v_mfma_f32_16x16x32_f16 v[58:61], v[134:137], v[150:153], v[58:61]
	v_mfma_f32_16x16x32_f16 v[46:49], v[110:113], v[158:161], v[46:49]
	v_mfma_f32_16x16x32_f16 v[42:45], v[134:137], v[158:161], v[42:45]
	v_mfma_f32_16x16x32_f16 v[28:31], v[110:113], v[166:169], v[28:31]
	v_mfma_f32_16x16x32_f16 v[24:27], v[134:137], v[166:169], v[24:27]
	v_mfma_f32_16x16x32_f16 v[12:15], v[110:113], v[174:177], v[12:15]
	v_mfma_f32_16x16x32_f16 v[8:11], v[134:137], v[174:177], v[8:11]
	s_setprio 0
	s_barrier
	s_add_u32 s10, s14, 0xb0000
	s_addc_u32 s11, s15, 0
	s_add_i32 s47, s48, s23
	v_lshl_add_u64 v[106:107], s[10:11], 0, v[32:33]
	s_mov_b32 m0, s47
	s_nop 0
	global_load_lds_dwordx4 v[106:107], off
	v_lshl_add_u64 v[106:107], s[10:11], 0, v[182:183]
	s_add_i32 m0, s47, 0x2000
	s_nop 0
	global_load_lds_dwordx4 v[106:107], off
	s_waitcnt vmcnt(6)
	s_barrier
	s_setprio 1
	v_mfma_f32_16x16x32_f16 v[54:57], v[178:181], v[138:141], v[54:57]
	v_mfma_f32_16x16x32_f16 v[50:53], v[192:195], v[138:141], v[50:53]
	v_mfma_f32_16x16x32_f16 v[38:41], v[178:181], v[154:157], v[38:41]
	v_mfma_f32_16x16x32_f16 v[34:37], v[192:195], v[154:157], v[34:37]
	v_mfma_f32_16x16x32_f16 v[20:23], v[178:181], v[162:165], v[20:23]
	v_mfma_f32_16x16x32_f16 v[16:19], v[192:195], v[162:165], v[16:19]
	v_mfma_f32_16x16x32_f16 v[4:7], v[178:181], v[170:173], v[4:7]
	v_mfma_f32_16x16x32_f16 v[0:3], v[192:195], v[170:173], v[0:3]
	v_mfma_f32_16x16x32_f16 v[54:57], v[188:191], v[150:153], v[54:57]
	v_mfma_f32_16x16x32_f16 v[50:53], v[196:199], v[150:153], v[50:53]
	v_mfma_f32_16x16x32_f16 v[38:41], v[188:191], v[158:161], v[38:41]
	v_mfma_f32_16x16x32_f16 v[34:37], v[196:199], v[158:161], v[34:37]
	v_mfma_f32_16x16x32_f16 v[20:23], v[188:191], v[166:169], v[20:23]
	v_mfma_f32_16x16x32_f16 v[16:19], v[196:199], v[166:169], v[16:19]
	v_mfma_f32_16x16x32_f16 v[4:7], v[188:191], v[174:177], v[4:7]
	v_mfma_f32_16x16x32_f16 v[0:3], v[196:199], v[174:177], v[0:3]
	s_setprio 0
	s_add_i32 s47, 0, 0x18000
	v_add_u32_e32 v134, s47, v230
	s_barrier
	ds_read_b128 v[106:109], v134
	ds_read_b128 v[114:117], v134 offset:2048
	ds_read_b128 v[110:113], v134 offset:1024
	ds_read_b128 v[134:137], v134 offset:3072
	s_add_u32 s10, s16, 0xb0000
	s_addc_u32 s11, s17, 0
	s_mov_b32 m0, s26
	v_lshl_add_u64 v[178:179], s[10:11], 0, v[32:33]
	ds_read_b128 v[138:141], v232 offset:32768
	ds_read_b128 v[154:157], v232 offset:34816
	ds_read_b128 v[162:165], v232 offset:36864
	ds_read_b128 v[170:173], v232 offset:38912
	ds_read_b128 v[150:153], v232 offset:33792
	ds_read_b128 v[158:161], v232 offset:35840
	ds_read_b128 v[166:169], v232 offset:37888
	ds_read_b128 v[174:177], v232 offset:39936
	global_load_lds_dwordx4 v[178:179], off
	v_lshl_add_u64 v[178:179], s[10:11], 0, v[182:183]
	s_mov_b32 m0, s27
	s_nop 0
	global_load_lds_dwordx4 v[178:179], off
	s_waitcnt lgkmcnt(8)
	s_barrier
	s_waitcnt lgkmcnt(7)
	s_setprio 1
	v_mfma_f32_16x16x32_f16 v[146:149], v[106:109], v[138:141], v[146:149]
	v_mfma_f32_16x16x32_f16 v[142:145], v[114:117], v[138:141], v[142:145]
	s_waitcnt lgkmcnt(6)
	v_mfma_f32_16x16x32_f16 v[130:133], v[106:109], v[154:157], v[130:133]
	v_mfma_f32_16x16x32_f16 v[122:125], v[114:117], v[154:157], v[122:125]
	s_waitcnt lgkmcnt(5)
	v_mfma_f32_16x16x32_f16 v[94:97], v[106:109], v[162:165], v[94:97]
	v_mfma_f32_16x16x32_f16 v[90:93], v[114:117], v[162:165], v[90:93]
	s_waitcnt lgkmcnt(4)
	v_mfma_f32_16x16x32_f16 v[78:81], v[106:109], v[170:173], v[78:81]
	v_mfma_f32_16x16x32_f16 v[74:77], v[114:117], v[170:173], v[74:77]
	s_waitcnt lgkmcnt(3)
	v_mfma_f32_16x16x32_f16 v[146:149], v[110:113], v[150:153], v[146:149]
	v_mfma_f32_16x16x32_f16 v[142:145], v[134:137], v[150:153], v[142:145]
	s_waitcnt lgkmcnt(2)
	v_mfma_f32_16x16x32_f16 v[130:133], v[110:113], v[158:161], v[130:133]
	v_mfma_f32_16x16x32_f16 v[122:125], v[134:137], v[158:161], v[122:125]
	s_waitcnt lgkmcnt(1)
	v_mfma_f32_16x16x32_f16 v[94:97], v[110:113], v[166:169], v[94:97]
	v_mfma_f32_16x16x32_f16 v[90:93], v[134:137], v[166:169], v[90:93]
	s_waitcnt lgkmcnt(0)
	v_mfma_f32_16x16x32_f16 v[78:81], v[110:113], v[174:177], v[78:81]
	v_mfma_f32_16x16x32_f16 v[74:77], v[134:137], v[174:177], v[74:77]
	s_setprio 0
	s_barrier
	s_add_i32 s16, 0, 0x1c000
	s_add_i32 s10, s47, s23
	v_add_u32_e32 v196, s16, v230
	v_lshl_add_u64 v[200:201], v[200:201], 0, s[84:85]
	s_mov_b32 m0, s10
	ds_read_b128 v[178:181], v196
	ds_read_b128 v[192:195], v196 offset:2048
	ds_read_b128 v[188:191], v196 offset:1024
	ds_read_b128 v[196:199], v196 offset:3072
	global_load_lds_dwordx4 v[200:201], off
	v_lshl_add_u64 v[200:201], v[202:203], 0, s[84:85]
	s_add_i32 m0, s10, 0x2000
	s_nop 0
	global_load_lds_dwordx4 v[200:201], off
	s_barrier
	s_waitcnt lgkmcnt(2)
	s_setprio 1
	v_mfma_f32_16x16x32_f16 v[126:129], v[178:181], v[138:141], v[126:129]
	v_mfma_f32_16x16x32_f16 v[118:121], v[192:195], v[138:141], v[118:121]
	v_mfma_f32_16x16x32_f16 v[102:105], v[178:181], v[154:157], v[102:105]
	v_mfma_f32_16x16x32_f16 v[98:101], v[192:195], v[154:157], v[98:101]
	v_mfma_f32_16x16x32_f16 v[86:89], v[178:181], v[162:165], v[86:89]
	v_mfma_f32_16x16x32_f16 v[82:85], v[192:195], v[162:165], v[82:85]
	v_mfma_f32_16x16x32_f16 v[70:73], v[178:181], v[170:173], v[70:73]
	v_mfma_f32_16x16x32_f16 v[66:69], v[192:195], v[170:173], v[66:69]
	s_waitcnt lgkmcnt(0)
	v_mfma_f32_16x16x32_f16 v[126:129], v[188:191], v[150:153], v[126:129]
	v_mfma_f32_16x16x32_f16 v[118:121], v[196:199], v[150:153], v[118:121]
	v_mfma_f32_16x16x32_f16 v[102:105], v[188:191], v[158:161], v[102:105]
	v_mfma_f32_16x16x32_f16 v[98:101], v[196:199], v[158:161], v[98:101]
	v_mfma_f32_16x16x32_f16 v[86:89], v[188:191], v[166:169], v[86:89]
	v_mfma_f32_16x16x32_f16 v[82:85], v[196:199], v[166:169], v[82:85]
	v_mfma_f32_16x16x32_f16 v[70:73], v[188:191], v[174:177], v[70:73]
	v_mfma_f32_16x16x32_f16 v[66:69], v[196:199], v[174:177], v[66:69]
	s_setprio 0
	s_mov_b32 m0, s29
	v_lshl_add_u64 v[200:201], v[204:205], 0, s[84:85]
	s_barrier
	ds_read_b128 v[138:141], v232 offset:49152
	ds_read_b128 v[154:157], v232 offset:51200
	ds_read_b128 v[162:165], v232 offset:53248
	ds_read_b128 v[170:173], v232 offset:55296
	ds_read_b128 v[150:153], v232 offset:50176
	ds_read_b128 v[158:161], v232 offset:52224
	ds_read_b128 v[166:169], v232 offset:54272
	ds_read_b128 v[174:177], v232 offset:56320
	global_load_lds_dwordx4 v[200:201], off
	v_lshl_add_u64 v[200:201], v[206:207], 0, s[84:85]
	s_mov_b32 m0, s30
	s_nop 0
	global_load_lds_dwordx4 v[200:201], off
	s_barrier
	s_waitcnt lgkmcnt(4)
	s_setprio 1
	v_mfma_f32_16x16x32_f16 v[62:65], v[106:109], v[138:141], v[62:65]
	v_mfma_f32_16x16x32_f16 v[58:61], v[114:117], v[138:141], v[58:61]
	v_mfma_f32_16x16x32_f16 v[46:49], v[106:109], v[154:157], v[46:49]
	v_mfma_f32_16x16x32_f16 v[42:45], v[114:117], v[154:157], v[42:45]
	v_mfma_f32_16x16x32_f16 v[28:31], v[106:109], v[162:165], v[28:31]
	v_mfma_f32_16x16x32_f16 v[24:27], v[114:117], v[162:165], v[24:27]
	v_mfma_f32_16x16x32_f16 v[12:15], v[106:109], v[170:173], v[12:15]
	v_mfma_f32_16x16x32_f16 v[8:11], v[114:117], v[170:173], v[8:11]
	s_waitcnt lgkmcnt(0)
	v_mfma_f32_16x16x32_f16 v[62:65], v[110:113], v[150:153], v[62:65]
	v_mfma_f32_16x16x32_f16 v[58:61], v[134:137], v[150:153], v[58:61]
	v_mfma_f32_16x16x32_f16 v[46:49], v[110:113], v[158:161], v[46:49]
	v_mfma_f32_16x16x32_f16 v[42:45], v[134:137], v[158:161], v[42:45]
	v_mfma_f32_16x16x32_f16 v[28:31], v[110:113], v[166:169], v[28:31]
	v_mfma_f32_16x16x32_f16 v[24:27], v[134:137], v[166:169], v[24:27]
	v_mfma_f32_16x16x32_f16 v[12:15], v[110:113], v[174:177], v[12:15]
	v_mfma_f32_16x16x32_f16 v[8:11], v[134:137], v[174:177], v[8:11]
	s_setprio 0
	s_barrier
	s_add_u32 s10, s14, 0xb0080
	s_addc_u32 s11, s15, 0
	s_add_i32 s14, s16, s23
	v_lshl_add_u64 v[106:107], s[10:11], 0, v[32:33]
	s_mov_b32 m0, s14
	s_nop 0
	global_load_lds_dwordx4 v[106:107], off
	v_lshl_add_u64 v[106:107], s[10:11], 0, v[182:183]
	s_add_i32 m0, s14, 0x2000
	s_nop 0
	global_load_lds_dwordx4 v[106:107], off
	s_waitcnt vmcnt(6)
	s_barrier
	s_setprio 1
	v_mfma_f32_16x16x32_f16 v[54:57], v[178:181], v[138:141], v[54:57]
	v_mfma_f32_16x16x32_f16 v[50:53], v[192:195], v[138:141], v[50:53]
	v_mfma_f32_16x16x32_f16 v[38:41], v[178:181], v[154:157], v[38:41]
	v_mfma_f32_16x16x32_f16 v[34:37], v[192:195], v[154:157], v[34:37]
	v_mfma_f32_16x16x32_f16 v[20:23], v[178:181], v[162:165], v[20:23]
	v_mfma_f32_16x16x32_f16 v[16:19], v[192:195], v[162:165], v[16:19]
	v_mfma_f32_16x16x32_f16 v[4:7], v[178:181], v[170:173], v[4:7]
	v_mfma_f32_16x16x32_f16 v[0:3], v[192:195], v[170:173], v[0:3]
	v_mfma_f32_16x16x32_f16 v[54:57], v[188:191], v[150:153], v[54:57]
	v_mfma_f32_16x16x32_f16 v[50:53], v[196:199], v[150:153], v[50:53]
	v_mfma_f32_16x16x32_f16 v[38:41], v[188:191], v[158:161], v[38:41]
	v_mfma_f32_16x16x32_f16 v[34:37], v[196:199], v[158:161], v[34:37]
	v_mfma_f32_16x16x32_f16 v[20:23], v[188:191], v[166:169], v[20:23]
	v_mfma_f32_16x16x32_f16 v[16:19], v[196:199], v[166:169], v[16:19]
	v_mfma_f32_16x16x32_f16 v[4:7], v[188:191], v[174:177], v[4:7]
	v_mfma_f32_16x16x32_f16 v[0:3], v[196:199], v[174:177], v[0:3]
	s_setprio 0
	s_add_u32 s44, s44, 0x100
	s_addc_u32 s45, s45, 0
	s_cmp_ge_u32 s46, s42
	s_mov_b64 s[10:11], s[12:13]
	s_mov_b32 s14, s46
	s_barrier
	s_cbranch_scc0 .LBB0_1365
	s_cmp_eq_u32 s40, 0
	s_cselect_b32 s6, 0x9000, 0
	v_lshl_or_b32 v106, s41, 8, v231
	s_add_u32 s6, s31, s6
	s_addc_u32 s7, s34, 0
	v_ashrrev_i32_e32 v107, 31, v106
	v_lshl_add_u64 v[116:117], v[106:107], 2, s[6:7]
	global_load_dwordx4 v[108:111], v[116:117], off offset:16
	global_load_dwordx4 v[112:115], v[116:117], off
	s_cmp_eq_u32 s39, 0
	s_waitcnt vmcnt(0)
	v_pk_mul_f32 v[194:195], v[110:111], 0.5 op_sel_hi:[1,0]
	v_pk_mul_f32 v[198:199], v[114:115], 0.5 op_sel_hi:[1,0]
	v_pk_mul_f32 v[202:203], v[112:113], 0.5 op_sel_hi:[1,0]
	v_pk_mul_f32 v[200:201], v[108:109], 0.5 op_sel_hi:[1,0]
	global_load_dwordx4 v[108:111], v[116:117], off offset:528
	global_load_dwordx4 v[112:115], v[116:117], off offset:512
	s_waitcnt vmcnt(0)
	v_pk_mul_f32 v[188:189], v[110:111], 0.5 op_sel_hi:[1,0]
	v_pk_mul_f32 v[196:197], v[112:113], 0.5 op_sel_hi:[1,0]
	v_lshl_add_u32 v112, s40, 8, v229
	v_pk_mul_f32 v[190:191], v[114:115], 0.5 op_sel_hi:[1,0]
	v_pk_mul_f32 v[192:193], v[108:109], 0.5 op_sel_hi:[1,0]
	v_or_b32_e32 v114, 16, v112
	v_or_b32_e32 v110, 32, v112
	v_or_b32_e32 v108, 48, v112
	v_ashrrev_i32_e32 v113, 31, v112
	v_ashrrev_i32_e32 v115, 31, v114
	v_ashrrev_i32_e32 v111, 31, v110
	v_ashrrev_i32_e32 v109, 31, v108
	s_cbranch_scc1 .LBB0_1368
	s_add_i32 s96, s39, -1
	s_lshl_b64 s[6:7], s[96:97], 20
	v_readlane_b32 s8, v252, 11
	v_readlane_b32 s9, v252, 12
	s_add_u32 s6, s8, s6
	s_addc_u32 s7, s9, s7
	v_lshlrev_b64 v[138:139], 2, v[106:107]
	v_lshrrev_b32_e32 v150, 5, v220
	v_mul_u32_u24_e32 v150, 48, v150
	s_nop 0
	v_sub_co_u32_e32 v138, vcc, v138, v150
	s_nop 1
	v_subbrev_co_u32_e32 v139, vcc, 0, v139, vcc
	v_lshl_add_u64 v[138:139], s[6:7], 0, v[138:139]
	s_mov_b64 s[6:7], 0x80000
	v_lshlrev_b64 v[204:205], 12, v[112:113]
	v_lshl_add_u64 v[204:205], v[204:205], 0, v[138:139]
	v_lshl_add_u64 v[212:213], v[204:205], 0, s[6:7]
	v_lshlrev_b64 v[206:207], 12, v[114:115]
	v_lshl_add_u64 v[206:207], v[206:207], 0, v[138:139]
	v_lshl_add_u64 v[214:215], v[206:207], 0, s[6:7]
	v_lshlrev_b64 v[208:209], 12, v[110:111]
	v_lshl_add_u64 v[208:209], v[208:209], 0, v[138:139]
	v_lshl_add_u64 v[216:217], v[208:209], 0, s[6:7]
	v_lshlrev_b64 v[210:211], 12, v[108:109]
	v_lshl_add_u64 v[210:211], v[210:211], 0, v[138:139]
	v_lshl_add_u64 v[218:219], v[210:211], 0, s[6:7]
	s_waitcnt vmcnt(0)
	v_pk_mul_f32 v[152:153], v[146:147], v[202:203]
	v_pk_mul_f32 v[154:155], v[148:149], v[198:199]
	v_pk_mul_f32 v[156:157], v[142:143], v[200:201]
	v_pk_mul_f32 v[158:159], v[144:145], v[194:195]
	s_nop 1
	v_permlane32_swap_b32_e32 v152, v156
	v_permlane32_swap_b32_e32 v153, v157
	v_permlane32_swap_b32_e32 v154, v158
	v_permlane32_swap_b32_e32 v155, v159
	s_nop 0
	global_store_dwordx4 v[204:205], v[152:155], off
	global_store_dwordx4 v[204:205], v[156:159], off offset:64
	v_pk_mul_f32 v[160:161], v[126:127], v[196:197]
	v_pk_mul_f32 v[162:163], v[128:129], v[190:191]
	v_pk_mul_f32 v[164:165], v[118:119], v[192:193]
	v_pk_mul_f32 v[166:167], v[120:121], v[188:189]
	s_nop 1
	v_permlane32_swap_b32_e32 v160, v164
	v_permlane32_swap_b32_e32 v161, v165
	v_permlane32_swap_b32_e32 v162, v166
	v_permlane32_swap_b32_e32 v163, v167
	s_nop 0
	global_store_dwordx4 v[204:205], v[160:163], off offset:512
	global_store_dwordx4 v[204:205], v[164:167], off offset:576
	v_pk_mul_f32 v[168:169], v[130:131], v[202:203]
	v_pk_mul_f32 v[170:171], v[132:133], v[198:199]
	v_pk_mul_f32 v[172:173], v[122:123], v[200:201]
	v_pk_mul_f32 v[174:175], v[124:125], v[194:195]
	s_nop 1
	v_permlane32_swap_b32_e32 v168, v172
	v_permlane32_swap_b32_e32 v169, v173
	v_permlane32_swap_b32_e32 v170, v174
	v_permlane32_swap_b32_e32 v171, v175
	s_nop 0
	global_store_dwordx4 v[206:207], v[168:171], off
	global_store_dwordx4 v[206:207], v[172:175], off offset:64
	v_pk_mul_f32 v[176:177], v[102:103], v[196:197]
	v_pk_mul_f32 v[178:179], v[104:105], v[190:191]
	v_pk_mul_f32 v[180:181], v[98:99], v[192:193]
	v_pk_mul_f32 v[182:183], v[100:101], v[188:189]
	s_nop 1
	v_permlane32_swap_b32_e32 v176, v180
	v_permlane32_swap_b32_e32 v177, v181
	v_permlane32_swap_b32_e32 v178, v182
	v_permlane32_swap_b32_e32 v179, v183
	s_nop 0
	global_store_dwordx4 v[206:207], v[176:179], off offset:512
	global_store_dwordx4 v[206:207], v[180:183], off offset:576
	v_pk_mul_f32 v[152:153], v[94:95], v[202:203]
	v_pk_mul_f32 v[154:155], v[96:97], v[198:199]
	v_pk_mul_f32 v[156:157], v[90:91], v[200:201]
	v_pk_mul_f32 v[158:159], v[92:93], v[194:195]
	s_nop 1
	v_permlane32_swap_b32_e32 v152, v156
	v_permlane32_swap_b32_e32 v153, v157
	v_permlane32_swap_b32_e32 v154, v158
	v_permlane32_swap_b32_e32 v155, v159
	s_nop 0
	global_store_dwordx4 v[208:209], v[152:155], off
	global_store_dwordx4 v[208:209], v[156:159], off offset:64
	v_pk_mul_f32 v[160:161], v[86:87], v[196:197]
	v_pk_mul_f32 v[162:163], v[88:89], v[190:191]
	v_pk_mul_f32 v[164:165], v[82:83], v[192:193]
	v_pk_mul_f32 v[166:167], v[84:85], v[188:189]
	s_nop 1
	v_permlane32_swap_b32_e32 v160, v164
	v_permlane32_swap_b32_e32 v161, v165
	v_permlane32_swap_b32_e32 v162, v166
	v_permlane32_swap_b32_e32 v163, v167
	s_nop 0
	global_store_dwordx4 v[208:209], v[160:163], off offset:512
	global_store_dwordx4 v[208:209], v[164:167], off offset:576
	v_pk_mul_f32 v[168:169], v[78:79], v[202:203]
	v_pk_mul_f32 v[170:171], v[80:81], v[198:199]
	v_pk_mul_f32 v[172:173], v[74:75], v[200:201]
	v_pk_mul_f32 v[174:175], v[76:77], v[194:195]
	s_nop 1
	v_permlane32_swap_b32_e32 v168, v172
	v_permlane32_swap_b32_e32 v169, v173
	v_permlane32_swap_b32_e32 v170, v174
	v_permlane32_swap_b32_e32 v171, v175
	s_nop 0
	global_store_dwordx4 v[210:211], v[168:171], off
	global_store_dwordx4 v[210:211], v[172:175], off offset:64
	v_pk_mul_f32 v[176:177], v[70:71], v[196:197]
	v_pk_mul_f32 v[178:179], v[72:73], v[190:191]
	v_pk_mul_f32 v[180:181], v[66:67], v[192:193]
	v_pk_mul_f32 v[182:183], v[68:69], v[188:189]
	s_nop 1
	v_permlane32_swap_b32_e32 v176, v180
	v_permlane32_swap_b32_e32 v177, v181
	v_permlane32_swap_b32_e32 v178, v182
	v_permlane32_swap_b32_e32 v179, v183
	s_nop 0
	global_store_dwordx4 v[210:211], v[176:179], off offset:512
	global_store_dwordx4 v[210:211], v[180:183], off offset:576
	v_pk_mul_f32 v[152:153], v[62:63], v[202:203]
	v_pk_mul_f32 v[154:155], v[64:65], v[198:199]
	v_pk_mul_f32 v[156:157], v[58:59], v[200:201]
	v_pk_mul_f32 v[158:159], v[60:61], v[194:195]
	s_nop 1
	v_permlane32_swap_b32_e32 v152, v156
	v_permlane32_swap_b32_e32 v153, v157
	v_permlane32_swap_b32_e32 v154, v158
	v_permlane32_swap_b32_e32 v155, v159
	s_nop 0
	global_store_dwordx4 v[212:213], v[152:155], off
	global_store_dwordx4 v[212:213], v[156:159], off offset:64
	v_pk_mul_f32 v[160:161], v[54:55], v[196:197]
	v_pk_mul_f32 v[162:163], v[56:57], v[190:191]
	v_pk_mul_f32 v[164:165], v[50:51], v[192:193]
	v_pk_mul_f32 v[166:167], v[52:53], v[188:189]
	s_nop 1
	v_permlane32_swap_b32_e32 v160, v164
	v_permlane32_swap_b32_e32 v161, v165
	v_permlane32_swap_b32_e32 v162, v166
	v_permlane32_swap_b32_e32 v163, v167
	s_nop 0
	global_store_dwordx4 v[212:213], v[160:163], off offset:512
	global_store_dwordx4 v[212:213], v[164:167], off offset:576
	v_pk_mul_f32 v[168:169], v[46:47], v[202:203]
	v_pk_mul_f32 v[170:171], v[48:49], v[198:199]
	v_pk_mul_f32 v[172:173], v[42:43], v[200:201]
	v_pk_mul_f32 v[174:175], v[44:45], v[194:195]
	s_nop 1
	v_permlane32_swap_b32_e32 v168, v172
	v_permlane32_swap_b32_e32 v169, v173
	v_permlane32_swap_b32_e32 v170, v174
	v_permlane32_swap_b32_e32 v171, v175
	s_nop 0
	global_store_dwordx4 v[214:215], v[168:171], off
	global_store_dwordx4 v[214:215], v[172:175], off offset:64
	v_pk_mul_f32 v[176:177], v[38:39], v[196:197]
	v_pk_mul_f32 v[178:179], v[40:41], v[190:191]
	v_pk_mul_f32 v[180:181], v[34:35], v[192:193]
	v_pk_mul_f32 v[182:183], v[36:37], v[188:189]
	s_nop 1
	v_permlane32_swap_b32_e32 v176, v180
	v_permlane32_swap_b32_e32 v177, v181
	v_permlane32_swap_b32_e32 v178, v182
	v_permlane32_swap_b32_e32 v179, v183
	s_nop 0
	global_store_dwordx4 v[214:215], v[176:179], off offset:512
	global_store_dwordx4 v[214:215], v[180:183], off offset:576
	v_pk_mul_f32 v[152:153], v[28:29], v[202:203]
	v_pk_mul_f32 v[154:155], v[30:31], v[198:199]
	v_pk_mul_f32 v[156:157], v[24:25], v[200:201]
	v_pk_mul_f32 v[158:159], v[26:27], v[194:195]
	s_nop 1
	v_permlane32_swap_b32_e32 v152, v156
	v_permlane32_swap_b32_e32 v153, v157
	v_permlane32_swap_b32_e32 v154, v158
	v_permlane32_swap_b32_e32 v155, v159
	s_nop 0
	global_store_dwordx4 v[216:217], v[152:155], off
	global_store_dwordx4 v[216:217], v[156:159], off offset:64
	v_pk_mul_f32 v[160:161], v[20:21], v[196:197]
	v_pk_mul_f32 v[162:163], v[22:23], v[190:191]
	v_pk_mul_f32 v[164:165], v[16:17], v[192:193]
	v_pk_mul_f32 v[166:167], v[18:19], v[188:189]
	s_nop 1
	v_permlane32_swap_b32_e32 v160, v164
	v_permlane32_swap_b32_e32 v161, v165
	v_permlane32_swap_b32_e32 v162, v166
	v_permlane32_swap_b32_e32 v163, v167
	s_nop 0
	global_store_dwordx4 v[216:217], v[160:163], off offset:512
	global_store_dwordx4 v[216:217], v[164:167], off offset:576
	v_pk_mul_f32 v[168:169], v[12:13], v[202:203]
	v_pk_mul_f32 v[170:171], v[14:15], v[198:199]
	v_pk_mul_f32 v[172:173], v[8:9], v[200:201]
	v_pk_mul_f32 v[174:175], v[10:11], v[194:195]
	s_nop 1
	v_permlane32_swap_b32_e32 v168, v172
	v_permlane32_swap_b32_e32 v169, v173
	v_permlane32_swap_b32_e32 v170, v174
	v_permlane32_swap_b32_e32 v171, v175
	s_nop 0
	global_store_dwordx4 v[218:219], v[168:171], off
	global_store_dwordx4 v[218:219], v[172:175], off offset:64
	v_pk_mul_f32 v[176:177], v[4:5], v[196:197]
	v_pk_mul_f32 v[178:179], v[6:7], v[190:191]
	v_pk_mul_f32 v[180:181], v[0:1], v[192:193]
	v_pk_mul_f32 v[182:183], v[2:3], v[188:189]
	s_nop 1
	v_permlane32_swap_b32_e32 v176, v180
	v_permlane32_swap_b32_e32 v177, v181
	v_permlane32_swap_b32_e32 v178, v182
	v_permlane32_swap_b32_e32 v179, v183
	s_nop 0
	global_store_dwordx4 v[218:219], v[176:179], off offset:512
	global_store_dwordx4 v[218:219], v[180:183], off offset:576
	s_cbranch_execnz .LBB0_1352
	s_branch .LBB0_1351
